# residual-add GEMM epilogues: row sum-of-squares combined across lane groups with v_permlane16/32_swap instead of two ds_bpermute round trips
# speedup vs baseline: 1.0029x; 1.0029x over previous
.LBB0_598:
	s_waitcnt lgkmcnt(0)
	v_pk_add_f32 v[164:165], v[164:165], 1.0 op_sel_hi:[1,0]
	v_pk_add_f32 v[166:167], v[166:167], 1.0 op_sel_hi:[1,0]
	v_pk_mul_f32 v[160:161], v[160:161], v[164:165]
	v_pk_add_f32 v[158:159], v[158:159], 1.0 op_sel_hi:[1,0]
	v_pk_add_f32 v[164:165], v[156:157], 1.0 op_sel_hi:[1,0]
	v_pk_add_f32 v[150:151], v[150:151], 1.0 op_sel_hi:[1,0]
	v_pk_add_f32 v[148:149], v[148:149], 1.0 op_sel_hi:[1,0]
	v_pk_mul_f32 v[162:163], v[162:163], v[166:167]
	v_pk_mul_f32 v[156:157], v[154:155], v[158:159]
	v_pk_mul_f32 v[158:159], v[152:153], v[164:165]
	v_pk_mul_f32 v[164:165], v[146:147], v[150:151]
	v_pk_mul_f32 v[166:167], v[144:145], v[148:149]
	ds_read_b128 v[144:147], v202 offset:2576
	ds_read_b128 v[148:151], v202 offset:3600
	v_lshl_add_u32 v206, s36, 8, v216
	v_readlane_b32 s72, v243, 5
	s_cmpk_lt_i32 s36, 0x100
	v_readlane_b32 s73, v243, 6
	s_waitcnt lgkmcnt(0)
	v_pk_add_f32 v[148:149], v[148:149], 1.0 op_sel_hi:[1,0]
	v_lshl_or_b32 v202, s2, 8, v219
	v_ashrrev_i32_e32 v207, 31, v206
	v_pk_mul_f32 v[152:153], v[144:145], v[148:149]
	s_cselect_b32 s1, s73, s64
	s_cselect_b32 s0, s72, s63
	v_ashrrev_i32_e32 v203, 31, v202
	v_lshlrev_b64 v[144:145], 12, v[206:207]
	v_lshl_add_u64 v[144:145], s[0:1], 0, v[144:145]
	v_lshlrev_b64 v[204:205], 2, v[202:203]
	v_pk_add_f32 v[150:151], v[150:151], 1.0 op_sel_hi:[1,0]
	v_lshl_add_u64 v[148:149], v[144:145], 0, v[204:205]
	v_pk_mul_f32 v[154:155], v[146:147], v[150:151]
	global_load_dwordx4 v[210:213], v[148:149], off offset:16
	global_load_dwordx4 v[228:231], v[148:149], off
	global_load_dwordx4 v[144:147], v[148:149], off offset:528
	s_nop 0
	global_load_dwordx4 v[148:151], v[148:149], off offset:512
	v_and_b32_e32 v209, 64, v224
	v_xor_b32_e32 v208, 16, v224
	v_add_u32_e32 v209, 64, v209
	v_cmp_lt_i32_e32 vcc, v208, v209
	v_readlane_b32 s74, v243, 7
	v_readlane_b32 s75, v243, 8
	v_cndmask_b32_e32 v208, v224, v208, vcc
	v_lshlrev_b32_e32 v226, 2, v208
	v_xor_b32_e32 v208, 32, v224
	v_cmp_lt_i32_e32 vcc, v208, v209
	v_readlane_b32 s76, v243, 9
	v_readlane_b32 s77, v243, 10
	v_readlane_b32 s78, v243, 11
	v_readlane_b32 s79, v243, 12
	v_readlane_b32 s80, v243, 13
	v_readlane_b32 s81, v243, 14
	v_readlane_b32 s82, v243, 15
	v_readlane_b32 s83, v243, 16
	v_readlane_b32 s84, v243, 17
	v_readlane_b32 s85, v243, 18
	v_readlane_b32 s86, v243, 19
	v_readlane_b32 s87, v243, 20
	v_cndmask_b32_e32 v208, v224, v208, vcc
	v_readlane_b32 s72, v243, 21
	v_lshlrev_b32_e32 v225, 2, v208
	v_lshlrev_b64 v[208:209], 10, v[206:207]
	v_readlane_b32 s87, v243, 36
	v_readlane_b32 s27, v242, 24
	v_lshl_add_u64 v[232:233], v[208:209], 0, v[202:203]
	v_or_b32_e32 v208, 16, v206
	v_readlane_b32 s86, v243, 35
	s_cselect_b32 s37, s87, s27
	v_readlane_b32 s27, v242, 23
	v_ashrrev_i32_e32 v209, 31, v208
	s_cselect_b32 s36, s86, s27
	v_lshl_add_u64 v[204:205], s[0:1], 0, v[204:205]
	v_lshlrev_b64 v[214:215], 12, v[208:209]
	v_lshl_add_u64 v[214:215], v[204:205], 0, v[214:215]
	s_lshl_b32 s0, s2, 2
	s_ashr_i32 s1, s0, 31
	v_readlane_b32 s73, v243, 22
	v_readlane_b32 s74, v243, 23
	v_readlane_b32 s75, v243, 24
	v_readlane_b32 s76, v243, 25
	v_readlane_b32 s77, v243, 26
	v_readlane_b32 s78, v243, 27
	v_readlane_b32 s79, v243, 28
	v_readlane_b32 s80, v243, 29
	v_readlane_b32 s81, v243, 30
	v_readlane_b32 s82, v243, 31
	v_readlane_b32 s83, v243, 32
	v_readlane_b32 s84, v243, 33
	v_readlane_b32 s85, v243, 34
	s_waitcnt vmcnt(0)
	v_pk_fma_f32 v[138:139], v[138:139], v[58:59], v[212:213]
	v_pk_fma_f32 v[142:143], v[142:143], v[50:51], v[230:231]
	v_pk_fma_f32 v[140:141], v[140:141], v[48:49], v[228:229]
	v_pk_fma_f32 v[136:137], v[136:137], v[56:57], v[210:211]
	v_pk_add_f32 v[234:235], v[188:189], v[142:143]
	v_pk_add_f32 v[236:237], v[186:187], v[140:141]
	v_pk_add_f32 v[238:239], v[198:199], v[138:139]
	v_pk_add_f32 v[240:241], v[190:191], v[136:137]
	v_lshlrev_b64 v[210:211], 1, v[232:233]
	v_cvt_pk_bf16_f32 v228, v236, v237
	v_cvt_pk_bf16_f32 v229, v234, v235
	v_cvt_pk_bf16_f32 v230, v240, v241
	v_cvt_pk_bf16_f32 v231, v238, v239
	v_lshl_add_u64 v[212:213], s[36:37], 0, v[210:211]
	global_load_dwordx4 v[136:139], v[214:215], off offset:16
	global_load_dwordx4 v[140:143], v[214:215], off
	v_mul_f32_e32 v227, v237, v237
	global_store_dwordx4 v[212:213], v[228:231], off
	v_fmac_f32_e32 v227, v236, v236
	v_pk_mul_f32 v[232:233], v[156:157], v[238:239]
	v_mul_f32_e32 v228, v235, v235
	v_fmac_f32_e32 v228, v234, v234
	v_add_f32_e32 v227, v227, v228
	v_mul_f32_e32 v228, v241, v241
	v_mul_f32_e32 v229, v239, v239
	v_fmac_f32_e32 v228, v240, v240
	v_fmac_f32_e32 v229, v238, v238
	v_add_f32_e32 v228, v228, v229
	v_add_f32_e32 v227, v227, v228
	v_pk_mul_f32 v[230:231], v[164:165], v[234:235]
	v_pk_mul_f32 v[228:229], v[166:167], v[236:237]
	v_pk_mul_f32 v[234:235], v[158:159], v[240:241]
	v_cvt_pk_bf16_f32 v228, v228, v229
	v_cvt_pk_bf16_f32 v229, v230, v231
	v_cvt_pk_bf16_f32 v230, v234, v235
	v_cvt_pk_bf16_f32 v231, v232, v233
	v_lshl_add_u64 v[232:233], s[8:9], 0, v[210:211]
	global_store_dwordx4 v[232:233], v[228:231], off
	v_pk_fma_f32 v[134:135], v[134:135], v[54:55], v[150:151]
	v_pk_fma_f32 v[132:133], v[132:133], v[52:53], v[148:149]
	v_pk_fma_f32 v[130:131], v[130:131], v[62:63], v[146:147]
	v_pk_fma_f32 v[128:129], v[128:129], v[60:61], v[144:145]
	v_pk_add_f32 v[148:149], v[194:195], v[134:135]
	v_pk_add_f32 v[150:151], v[192:193], v[132:133]
	v_pk_add_f32 v[228:229], v[200:201], v[130:131]
	v_pk_add_f32 v[230:231], v[196:197], v[128:129]
	global_load_dwordx4 v[128:131], v[214:215], off offset:528
	global_load_dwordx4 v[132:135], v[214:215], off offset:512
	v_cvt_pk_bf16_f32 v144, v150, v151
	v_cvt_pk_bf16_f32 v145, v148, v149
	v_cvt_pk_bf16_f32 v146, v230, v231
	v_cvt_pk_bf16_f32 v147, v228, v229
	global_store_dwordx4 v[212:213], v[144:147], off offset:256
	v_or_b32_e32 v210, 0x100, v210
	s_nop 0
	v_mul_f32_e32 v144, v151, v151
	v_mul_f32_e32 v145, v149, v149
	v_fmac_f32_e32 v144, v150, v150
	v_fmac_f32_e32 v145, v148, v148
	v_add_f32_e32 v144, v144, v145
	v_mul_f32_e32 v145, v231, v231
	v_mul_f32_e32 v146, v229, v229
	v_fmac_f32_e32 v145, v230, v230
	v_fmac_f32_e32 v146, v228, v228
	v_add_f32_e32 v144, v227, v144
	v_add_f32_e32 v145, v145, v146
	v_add_f32_e32 v212, v144, v145
	v_pk_mul_f32 v[146:147], v[162:163], v[148:149]
	v_pk_mul_f32 v[144:145], v[160:161], v[150:151]
	v_pk_mul_f32 v[148:149], v[154:155], v[228:229]
	v_pk_mul_f32 v[150:151], v[152:153], v[230:231]
	v_cvt_pk_bf16_f32 v144, v144, v145
	v_cvt_pk_bf16_f32 v145, v146, v147
	v_cvt_pk_bf16_f32 v146, v150, v151
	v_cvt_pk_bf16_f32 v147, v148, v149
	v_lshl_add_u64 v[148:149], s[8:9], 0, v[210:211]
	global_store_dwordx4 v[148:149], v[144:147], off
	v_mov_b32_e32 v244, v212
	v_mov_b32_e32 v245, v212
	s_nop 1
	v_permlane16_swap_b32_e32 v244, v245
	s_waitcnt lgkmcnt(0)
	v_add_f32_e32 v144, v244, v245
	v_mov_b32_e32 v246, v144
	v_mov_b32_e32 v247, v144
	s_nop 1
	v_permlane32_swap_b32_e32 v246, v247
	s_and_saveexec_b64 s[38:39], s[4:5]
	s_cbranch_execz .LBB0_600
	v_lshlrev_b64 v[146:147], 6, v[206:207]
	v_lshl_add_u64 v[146:147], s[12:13], 0, v[146:147]
	v_lshl_add_u64 v[146:147], s[0:1], 2, v[146:147]
	s_lshl_b32 s2, s65, 2
	v_lshl_add_u64 v[146:147], v[146:147], 0, s[2:3]
	s_waitcnt lgkmcnt(0)
	v_add_f32_e32 v144, v246, v247
	global_store_dword v[146:147], v144, off
.LBB0_600:
	s_or_b64 exec, exec, s[38:39]
	s_waitcnt lgkmcnt(0)
	v_lshlrev_b64 v[144:145], 10, v[208:209]
	v_lshl_add_u64 v[146:147], v[144:145], 0, v[202:203]
	v_or_b32_e32 v144, 32, v206
	v_ashrrev_i32_e32 v145, 31, v144
	s_waitcnt vmcnt(6)
	v_pk_fma_f32 v[126:127], v[126:127], v[50:51], v[142:143]
	v_pk_fma_f32 v[124:125], v[124:125], v[48:49], v[140:141]
	v_pk_fma_f32 v[122:123], v[122:123], v[58:59], v[138:139]
	v_pk_fma_f32 v[120:121], v[120:121], v[56:57], v[136:137]
	v_lshlrev_b64 v[148:149], 12, v[144:145]
	v_pk_add_f32 v[140:141], v[188:189], v[126:127]
	v_pk_add_f32 v[142:143], v[186:187], v[124:125]
	v_pk_add_f32 v[150:151], v[198:199], v[122:123]
	v_pk_add_f32 v[210:211], v[190:191], v[120:121]
	v_lshlrev_b64 v[146:147], 1, v[146:147]
	v_lshl_add_u64 v[148:149], v[204:205], 0, v[148:149]
	v_cvt_pk_bf16_f32 v136, v142, v143
	v_cvt_pk_bf16_f32 v137, v140, v141
	v_cvt_pk_bf16_f32 v138, v210, v211
	v_cvt_pk_bf16_f32 v139, v150, v151
	v_lshl_add_u64 v[212:213], s[36:37], 0, v[146:147]
	global_load_dwordx4 v[120:123], v[148:149], off offset:16
	global_load_dwordx4 v[124:127], v[148:149], off
	s_waitcnt vmcnt(4)
	v_pk_fma_f32 v[118:119], v[118:119], v[54:55], v[134:135]
	global_store_dwordx4 v[212:213], v[136:139], off
	v_pk_fma_f32 v[116:117], v[116:117], v[52:53], v[132:133]
	v_pk_fma_f32 v[114:115], v[114:115], v[62:63], v[130:131]
	v_mul_f32_e32 v136, v143, v143
	v_mul_f32_e32 v137, v141, v141
	v_fmac_f32_e32 v136, v142, v142
	v_fmac_f32_e32 v137, v140, v140
	v_add_f32_e32 v136, v136, v137
	v_mul_f32_e32 v137, v211, v211
	v_mul_f32_e32 v138, v151, v151
	v_fmac_f32_e32 v137, v210, v210
	v_fmac_f32_e32 v138, v150, v150
	v_add_f32_e32 v137, v137, v138
	v_add_f32_e32 v207, v136, v137
	v_pk_mul_f32 v[138:139], v[164:165], v[140:141]
	v_pk_mul_f32 v[136:137], v[166:167], v[142:143]
	v_pk_mul_f32 v[140:141], v[156:157], v[150:151]
	v_pk_mul_f32 v[142:143], v[158:159], v[210:211]
	v_cvt_pk_bf16_f32 v136, v136, v137
	v_cvt_pk_bf16_f32 v137, v138, v139
	v_cvt_pk_bf16_f32 v138, v142, v143
	v_cvt_pk_bf16_f32 v139, v140, v141
	v_lshl_add_u64 v[140:141], s[8:9], 0, v[146:147]
	global_store_dwordx4 v[140:141], v[136:139], off
	v_pk_fma_f32 v[112:113], v[112:113], v[60:61], v[128:129]
	v_pk_add_f32 v[132:133], v[194:195], v[118:119]
	v_pk_add_f32 v[134:135], v[192:193], v[116:117]
	v_pk_add_f32 v[136:137], v[200:201], v[114:115]
	v_pk_add_f32 v[138:139], v[196:197], v[112:113]
	global_load_dwordx4 v[112:115], v[148:149], off offset:528
	global_load_dwordx4 v[116:119], v[148:149], off offset:512
	v_cvt_pk_bf16_f32 v128, v134, v135
	v_cvt_pk_bf16_f32 v129, v132, v133
	v_cvt_pk_bf16_f32 v130, v138, v139
	v_cvt_pk_bf16_f32 v131, v136, v137
	global_store_dwordx4 v[212:213], v[128:131], off offset:256
	v_or_b32_e32 v146, 0x100, v146
	s_nop 0
	v_mul_f32_e32 v128, v135, v135
	v_mul_f32_e32 v129, v133, v133
	v_fmac_f32_e32 v128, v134, v134
	v_fmac_f32_e32 v129, v132, v132
	v_add_f32_e32 v128, v128, v129
	v_mul_f32_e32 v129, v139, v139
	v_mul_f32_e32 v130, v137, v137
	v_fmac_f32_e32 v129, v138, v138
	v_fmac_f32_e32 v130, v136, v136
	v_add_f32_e32 v128, v207, v128
	v_add_f32_e32 v129, v129, v130
	v_add_f32_e32 v140, v128, v129
	v_pk_mul_f32 v[130:131], v[162:163], v[132:133]
	v_pk_mul_f32 v[128:129], v[160:161], v[134:135]
	v_pk_mul_f32 v[132:133], v[154:155], v[136:137]
	v_pk_mul_f32 v[134:135], v[152:153], v[138:139]
	v_cvt_pk_bf16_f32 v128, v128, v129
	v_cvt_pk_bf16_f32 v129, v130, v131
	v_cvt_pk_bf16_f32 v130, v134, v135
	v_cvt_pk_bf16_f32 v131, v132, v133
	v_lshl_add_u64 v[132:133], s[8:9], 0, v[146:147]
	global_store_dwordx4 v[132:133], v[128:131], off
	v_mov_b32_e32 v244, v140
	v_mov_b32_e32 v245, v140
	s_nop 1
	v_permlane16_swap_b32_e32 v244, v245
	s_waitcnt lgkmcnt(0)
	v_add_f32_e32 v128, v244, v245
	v_mov_b32_e32 v246, v128
	v_mov_b32_e32 v247, v128
	s_nop 1
	v_permlane32_swap_b32_e32 v246, v247
	s_and_saveexec_b64 s[38:39], s[4:5]
	v_readlane_b32 s84, v243, 43
	s_cbranch_execz .LBB0_602
	v_lshlrev_b64 v[130:131], 6, v[208:209]
	v_lshl_add_u64 v[130:131], s[12:13], 0, v[130:131]
	v_lshl_add_u64 v[130:131], s[0:1], 2, v[130:131]
	s_lshl_b32 s2, s65, 2
	v_lshl_add_u64 v[130:131], v[130:131], 0, s[2:3]
	s_waitcnt lgkmcnt(0)
	v_add_f32_e32 v128, v246, v247
	global_store_dword v[130:131], v128, off
.LBB0_602:
	s_or_b64 exec, exec, s[38:39]
	s_waitcnt lgkmcnt(0)
	v_lshlrev_b64 v[128:129], 10, v[144:145]
	v_lshl_add_u64 v[130:131], v[128:129], 0, v[202:203]
	v_or_b32_e32 v128, 48, v206
	v_ashrrev_i32_e32 v129, 31, v128
	s_waitcnt vmcnt(6)
	v_pk_fma_f32 v[110:111], v[110:111], v[50:51], v[126:127]
	v_pk_fma_f32 v[108:109], v[108:109], v[48:49], v[124:125]
	v_pk_fma_f32 v[106:107], v[106:107], v[58:59], v[122:123]
	v_pk_fma_f32 v[104:105], v[104:105], v[56:57], v[120:121]
	v_lshlrev_b64 v[132:133], 12, v[128:129]
	v_pk_add_f32 v[124:125], v[188:189], v[110:111]
	v_pk_add_f32 v[126:127], v[186:187], v[108:109]
	v_pk_add_f32 v[134:135], v[198:199], v[106:107]
	v_pk_add_f32 v[136:137], v[190:191], v[104:105]
	v_lshlrev_b64 v[130:131], 1, v[130:131]
	v_lshl_add_u64 v[132:133], v[204:205], 0, v[132:133]
	v_cvt_pk_bf16_f32 v120, v126, v127
	v_cvt_pk_bf16_f32 v121, v124, v125
	v_cvt_pk_bf16_f32 v122, v136, v137
	v_cvt_pk_bf16_f32 v123, v134, v135
	v_lshl_add_u64 v[138:139], s[36:37], 0, v[130:131]
	global_load_dwordx4 v[104:107], v[132:133], off offset:16
	global_load_dwordx4 v[108:111], v[132:133], off
	s_waitcnt vmcnt(4)
	v_pk_fma_f32 v[102:103], v[102:103], v[54:55], v[118:119]
	global_store_dwordx4 v[138:139], v[120:123], off
	v_pk_fma_f32 v[100:101], v[100:101], v[52:53], v[116:117]
	v_pk_fma_f32 v[98:99], v[98:99], v[62:63], v[114:115]
	v_mul_f32_e32 v120, v127, v127
	v_mul_f32_e32 v121, v125, v125
	v_fmac_f32_e32 v120, v126, v126
	v_fmac_f32_e32 v121, v124, v124
	v_add_f32_e32 v120, v120, v121
	v_mul_f32_e32 v121, v137, v137
	v_mul_f32_e32 v122, v135, v135
	v_fmac_f32_e32 v121, v136, v136
	v_fmac_f32_e32 v122, v134, v134
	v_add_f32_e32 v121, v121, v122
	v_add_f32_e32 v140, v120, v121
	v_pk_mul_f32 v[122:123], v[164:165], v[124:125]
	v_pk_mul_f32 v[120:121], v[166:167], v[126:127]
	v_pk_mul_f32 v[124:125], v[156:157], v[134:135]
	v_pk_mul_f32 v[126:127], v[158:159], v[136:137]
	v_cvt_pk_bf16_f32 v120, v120, v121
	v_cvt_pk_bf16_f32 v121, v122, v123
	v_cvt_pk_bf16_f32 v122, v126, v127
	v_cvt_pk_bf16_f32 v123, v124, v125
	v_lshl_add_u64 v[124:125], s[8:9], 0, v[130:131]
	global_store_dwordx4 v[124:125], v[120:123], off
	v_pk_fma_f32 v[96:97], v[96:97], v[60:61], v[112:113]
	v_pk_add_f32 v[116:117], v[194:195], v[102:103]
	v_pk_add_f32 v[118:119], v[192:193], v[100:101]
	v_pk_add_f32 v[120:121], v[200:201], v[98:99]
	v_pk_add_f32 v[122:123], v[196:197], v[96:97]
	global_load_dwordx4 v[96:99], v[132:133], off offset:528
	global_load_dwordx4 v[100:103], v[132:133], off offset:512
	v_cvt_pk_bf16_f32 v112, v118, v119
	v_cvt_pk_bf16_f32 v113, v116, v117
	v_cvt_pk_bf16_f32 v114, v122, v123
	v_cvt_pk_bf16_f32 v115, v120, v121
	global_store_dwordx4 v[138:139], v[112:115], off offset:256
	v_or_b32_e32 v130, 0x100, v130
	s_nop 0
	v_mul_f32_e32 v112, v119, v119
	v_mul_f32_e32 v113, v117, v117
	v_fmac_f32_e32 v112, v118, v118
	v_fmac_f32_e32 v113, v116, v116
	v_add_f32_e32 v112, v112, v113
	v_mul_f32_e32 v113, v123, v123
	v_mul_f32_e32 v114, v121, v121
	v_fmac_f32_e32 v113, v122, v122
	v_fmac_f32_e32 v114, v120, v120
	v_add_f32_e32 v112, v140, v112
	v_add_f32_e32 v113, v113, v114
	v_add_f32_e32 v124, v112, v113
	v_pk_mul_f32 v[114:115], v[162:163], v[116:117]
	v_pk_mul_f32 v[112:113], v[160:161], v[118:119]
	v_pk_mul_f32 v[116:117], v[154:155], v[120:121]
	v_pk_mul_f32 v[118:119], v[152:153], v[122:123]
	v_cvt_pk_bf16_f32 v112, v112, v113
	v_cvt_pk_bf16_f32 v113, v114, v115
	v_cvt_pk_bf16_f32 v114, v118, v119
	v_cvt_pk_bf16_f32 v115, v116, v117
	v_lshl_add_u64 v[116:117], s[8:9], 0, v[130:131]
	global_store_dwordx4 v[116:117], v[112:115], off
	v_mov_b32_e32 v244, v124
	v_mov_b32_e32 v245, v124
	s_nop 1
	v_permlane16_swap_b32_e32 v244, v245
	s_waitcnt lgkmcnt(0)
	v_add_f32_e32 v112, v244, v245
	v_mov_b32_e32 v246, v112
	v_mov_b32_e32 v247, v112
	s_nop 1
	v_permlane32_swap_b32_e32 v246, v247
	s_and_saveexec_b64 s[38:39], s[4:5]
	s_cbranch_execz .LBB0_604
	v_lshlrev_b64 v[114:115], 6, v[144:145]
	v_lshl_add_u64 v[114:115], s[12:13], 0, v[114:115]
	v_lshl_add_u64 v[114:115], s[0:1], 2, v[114:115]
	s_lshl_b32 s2, s65, 2
	v_lshl_add_u64 v[114:115], v[114:115], 0, s[2:3]
	s_waitcnt lgkmcnt(0)
	v_add_f32_e32 v112, v246, v247
	global_store_dword v[114:115], v112, off
.LBB0_604:
	s_or_b64 exec, exec, s[38:39]
	s_waitcnt lgkmcnt(0)
	v_lshlrev_b64 v[112:113], 10, v[128:129]
	v_lshl_add_u64 v[114:115], v[112:113], 0, v[202:203]
	v_add_u32_e32 v112, 0x80, v206
	v_ashrrev_i32_e32 v113, 31, v112
	s_waitcnt vmcnt(6)
	v_pk_fma_f32 v[94:95], v[94:95], v[50:51], v[110:111]
	v_pk_fma_f32 v[92:93], v[92:93], v[48:49], v[108:109]
	v_pk_fma_f32 v[90:91], v[90:91], v[58:59], v[106:107]
	v_pk_fma_f32 v[88:89], v[88:89], v[56:57], v[104:105]
	v_lshlrev_b64 v[116:117], 12, v[112:113]
	v_pk_add_f32 v[108:109], v[188:189], v[94:95]
	v_pk_add_f32 v[110:111], v[186:187], v[92:93]
	v_pk_add_f32 v[118:119], v[198:199], v[90:91]
	v_pk_add_f32 v[120:121], v[190:191], v[88:89]
	v_lshlrev_b64 v[114:115], 1, v[114:115]
	v_lshl_add_u64 v[116:117], v[204:205], 0, v[116:117]
	v_cvt_pk_bf16_f32 v104, v110, v111
	v_cvt_pk_bf16_f32 v105, v108, v109
	v_cvt_pk_bf16_f32 v106, v120, v121
	v_cvt_pk_bf16_f32 v107, v118, v119
	v_lshl_add_u64 v[122:123], s[36:37], 0, v[114:115]
	global_load_dwordx4 v[88:91], v[116:117], off offset:16
	global_load_dwordx4 v[92:95], v[116:117], off
	s_waitcnt vmcnt(4)
	v_pk_fma_f32 v[86:87], v[86:87], v[54:55], v[102:103]
	global_store_dwordx4 v[122:123], v[104:107], off
	v_pk_fma_f32 v[84:85], v[84:85], v[52:53], v[100:101]
	v_pk_fma_f32 v[82:83], v[82:83], v[62:63], v[98:99]
	v_mul_f32_e32 v104, v111, v111
	v_mul_f32_e32 v105, v109, v109
	v_fmac_f32_e32 v104, v110, v110
	v_fmac_f32_e32 v105, v108, v108
	v_add_f32_e32 v104, v104, v105
	v_mul_f32_e32 v105, v121, v121
	v_mul_f32_e32 v106, v119, v119
	v_fmac_f32_e32 v105, v120, v120
	v_fmac_f32_e32 v106, v118, v118
	v_add_f32_e32 v105, v105, v106
	v_add_f32_e32 v124, v104, v105
	v_pk_mul_f32 v[106:107], v[164:165], v[108:109]
	v_pk_mul_f32 v[104:105], v[166:167], v[110:111]
	v_pk_mul_f32 v[108:109], v[156:157], v[118:119]
	v_pk_mul_f32 v[110:111], v[158:159], v[120:121]
	v_cvt_pk_bf16_f32 v104, v104, v105
	v_cvt_pk_bf16_f32 v105, v106, v107
	v_cvt_pk_bf16_f32 v106, v110, v111
	v_cvt_pk_bf16_f32 v107, v108, v109
	v_lshl_add_u64 v[108:109], s[8:9], 0, v[114:115]
	global_store_dwordx4 v[108:109], v[104:107], off
	v_pk_fma_f32 v[80:81], v[80:81], v[60:61], v[96:97]
	v_pk_add_f32 v[100:101], v[194:195], v[86:87]
	v_pk_add_f32 v[102:103], v[192:193], v[84:85]
	v_pk_add_f32 v[104:105], v[200:201], v[82:83]
	v_pk_add_f32 v[106:107], v[196:197], v[80:81]
	global_load_dwordx4 v[80:83], v[116:117], off offset:528
	global_load_dwordx4 v[84:87], v[116:117], off offset:512
	v_cvt_pk_bf16_f32 v96, v102, v103
	v_cvt_pk_bf16_f32 v97, v100, v101
	v_cvt_pk_bf16_f32 v98, v106, v107
	v_cvt_pk_bf16_f32 v99, v104, v105
	global_store_dwordx4 v[122:123], v[96:99], off offset:256
	v_or_b32_e32 v114, 0x100, v114
	s_nop 0
	v_mul_f32_e32 v96, v103, v103
	v_mul_f32_e32 v97, v101, v101
	v_fmac_f32_e32 v96, v102, v102
	v_fmac_f32_e32 v97, v100, v100
	v_add_f32_e32 v96, v96, v97
	v_mul_f32_e32 v97, v107, v107
	v_mul_f32_e32 v98, v105, v105
	v_fmac_f32_e32 v97, v106, v106
	v_fmac_f32_e32 v98, v104, v104
	v_add_f32_e32 v96, v124, v96
	v_add_f32_e32 v97, v97, v98
	v_add_f32_e32 v108, v96, v97
	v_pk_mul_f32 v[98:99], v[162:163], v[100:101]
	v_pk_mul_f32 v[96:97], v[160:161], v[102:103]
	v_pk_mul_f32 v[100:101], v[154:155], v[104:105]
	v_pk_mul_f32 v[102:103], v[152:153], v[106:107]
	v_cvt_pk_bf16_f32 v96, v96, v97
	v_cvt_pk_bf16_f32 v97, v98, v99
	v_cvt_pk_bf16_f32 v98, v102, v103
	v_cvt_pk_bf16_f32 v99, v100, v101
	v_lshl_add_u64 v[100:101], s[8:9], 0, v[114:115]
	global_store_dwordx4 v[100:101], v[96:99], off
	v_mov_b32_e32 v244, v108
	v_mov_b32_e32 v245, v108
	s_nop 1
	v_permlane16_swap_b32_e32 v244, v245
	s_waitcnt lgkmcnt(0)
	v_add_f32_e32 v96, v244, v245
	v_mov_b32_e32 v246, v96
	v_mov_b32_e32 v247, v96
	s_nop 1
	v_permlane32_swap_b32_e32 v246, v247
	s_and_saveexec_b64 s[38:39], s[4:5]
	s_cbranch_execz .LBB0_606
	v_lshlrev_b64 v[98:99], 6, v[128:129]
	v_lshl_add_u64 v[98:99], s[12:13], 0, v[98:99]
	v_lshl_add_u64 v[98:99], s[0:1], 2, v[98:99]
	s_lshl_b32 s2, s65, 2
	v_lshl_add_u64 v[98:99], v[98:99], 0, s[2:3]
	s_waitcnt lgkmcnt(0)
	v_add_f32_e32 v96, v246, v247
	global_store_dword v[98:99], v96, off
.LBB0_606:
	s_or_b64 exec, exec, s[38:39]
	s_waitcnt lgkmcnt(0)
	v_lshlrev_b64 v[96:97], 10, v[112:113]
	v_lshl_add_u64 v[98:99], v[96:97], 0, v[202:203]
	v_or_b32_e32 v96, 16, v112
	v_ashrrev_i32_e32 v97, 31, v96
	s_waitcnt vmcnt(6)
	v_pk_fma_f32 v[78:79], v[78:79], v[50:51], v[94:95]
	v_pk_fma_f32 v[76:77], v[76:77], v[48:49], v[92:93]
	v_pk_fma_f32 v[74:75], v[74:75], v[58:59], v[90:91]
	v_pk_fma_f32 v[72:73], v[72:73], v[56:57], v[88:89]
	v_lshlrev_b64 v[100:101], 12, v[96:97]
	v_pk_add_f32 v[92:93], v[188:189], v[78:79]
	v_pk_add_f32 v[94:95], v[186:187], v[76:77]
	v_pk_add_f32 v[102:103], v[198:199], v[74:75]
	v_pk_add_f32 v[104:105], v[190:191], v[72:73]
	v_lshlrev_b64 v[98:99], 1, v[98:99]
	v_lshl_add_u64 v[100:101], v[204:205], 0, v[100:101]
	v_cvt_pk_bf16_f32 v88, v94, v95
	v_cvt_pk_bf16_f32 v89, v92, v93
	v_cvt_pk_bf16_f32 v90, v104, v105
	v_cvt_pk_bf16_f32 v91, v102, v103
	v_lshl_add_u64 v[106:107], s[36:37], 0, v[98:99]
	global_load_dwordx4 v[72:75], v[100:101], off offset:16
	global_load_dwordx4 v[76:79], v[100:101], off
	s_waitcnt vmcnt(4)
	v_pk_fma_f32 v[70:71], v[70:71], v[54:55], v[86:87]
	global_store_dwordx4 v[106:107], v[88:91], off
	v_pk_fma_f32 v[68:69], v[68:69], v[52:53], v[84:85]
	v_pk_fma_f32 v[66:67], v[66:67], v[62:63], v[82:83]
	v_mul_f32_e32 v88, v95, v95
	v_mul_f32_e32 v89, v93, v93
	v_fmac_f32_e32 v88, v94, v94
	v_fmac_f32_e32 v89, v92, v92
	v_add_f32_e32 v88, v88, v89
	v_mul_f32_e32 v89, v105, v105
	v_mul_f32_e32 v90, v103, v103
	v_fmac_f32_e32 v89, v104, v104
	v_fmac_f32_e32 v90, v102, v102
	v_add_f32_e32 v89, v89, v90
	v_add_f32_e32 v108, v88, v89
	v_pk_mul_f32 v[90:91], v[164:165], v[92:93]
	v_pk_mul_f32 v[88:89], v[166:167], v[94:95]
	v_pk_mul_f32 v[92:93], v[156:157], v[102:103]
	v_pk_mul_f32 v[94:95], v[158:159], v[104:105]
	v_cvt_pk_bf16_f32 v88, v88, v89
	v_cvt_pk_bf16_f32 v89, v90, v91
	v_cvt_pk_bf16_f32 v90, v94, v95
	v_cvt_pk_bf16_f32 v91, v92, v93
	v_lshl_add_u64 v[92:93], s[8:9], 0, v[98:99]
	global_store_dwordx4 v[92:93], v[88:91], off
	v_pk_fma_f32 v[64:65], v[64:65], v[60:61], v[80:81]
	v_pk_add_f32 v[84:85], v[194:195], v[70:71]
	v_pk_add_f32 v[86:87], v[192:193], v[68:69]
	v_pk_add_f32 v[88:89], v[200:201], v[66:67]
	v_pk_add_f32 v[90:91], v[196:197], v[64:65]
	global_load_dwordx4 v[64:67], v[100:101], off offset:528
	global_load_dwordx4 v[68:71], v[100:101], off offset:512
	v_cvt_pk_bf16_f32 v80, v86, v87
	v_cvt_pk_bf16_f32 v81, v84, v85
	v_cvt_pk_bf16_f32 v82, v90, v91
	v_cvt_pk_bf16_f32 v83, v88, v89
	global_store_dwordx4 v[106:107], v[80:83], off offset:256
	v_or_b32_e32 v98, 0x100, v98
	s_nop 0
	v_mul_f32_e32 v80, v87, v87
	v_mul_f32_e32 v81, v85, v85
	v_fmac_f32_e32 v80, v86, v86
	v_fmac_f32_e32 v81, v84, v84
	v_add_f32_e32 v80, v80, v81
	v_mul_f32_e32 v81, v91, v91
	v_mul_f32_e32 v82, v89, v89
	v_fmac_f32_e32 v81, v90, v90
	v_fmac_f32_e32 v82, v88, v88
	v_add_f32_e32 v80, v108, v80
	v_add_f32_e32 v81, v81, v82
	v_add_f32_e32 v92, v80, v81
	v_pk_mul_f32 v[82:83], v[162:163], v[84:85]
	v_pk_mul_f32 v[80:81], v[160:161], v[86:87]
	v_pk_mul_f32 v[84:85], v[154:155], v[88:89]
	v_pk_mul_f32 v[86:87], v[152:153], v[90:91]
	v_cvt_pk_bf16_f32 v80, v80, v81
	v_cvt_pk_bf16_f32 v81, v82, v83
	v_cvt_pk_bf16_f32 v82, v86, v87
	v_cvt_pk_bf16_f32 v83, v84, v85
	v_lshl_add_u64 v[84:85], s[8:9], 0, v[98:99]
	global_store_dwordx4 v[84:85], v[80:83], off
	v_mov_b32_e32 v244, v92
	v_mov_b32_e32 v245, v92
	s_nop 1
	v_permlane16_swap_b32_e32 v244, v245
	s_waitcnt lgkmcnt(0)
	v_add_f32_e32 v80, v244, v245
	v_mov_b32_e32 v246, v80
	v_mov_b32_e32 v247, v80
	s_nop 1
	v_permlane32_swap_b32_e32 v246, v247
	s_and_saveexec_b64 s[38:39], s[4:5]
	s_cbranch_execz .LBB0_608
	v_lshlrev_b64 v[82:83], 6, v[112:113]
	v_lshl_add_u64 v[82:83], s[12:13], 0, v[82:83]
	v_lshl_add_u64 v[82:83], s[0:1], 2, v[82:83]
	s_lshl_b32 s2, s65, 2
	v_lshl_add_u64 v[82:83], v[82:83], 0, s[2:3]
	s_waitcnt lgkmcnt(0)
	v_add_f32_e32 v80, v246, v247
	global_store_dword v[82:83], v80, off
.LBB0_608:
	s_or_b64 exec, exec, s[38:39]
	s_waitcnt lgkmcnt(0)
	v_lshlrev_b64 v[80:81], 10, v[96:97]
	v_lshl_add_u64 v[82:83], v[80:81], 0, v[202:203]
	v_or_b32_e32 v80, 32, v112
	v_ashrrev_i32_e32 v81, 31, v80
	s_waitcnt vmcnt(6)
	v_pk_fma_f32 v[46:47], v[46:47], v[50:51], v[78:79]
	v_pk_fma_f32 v[44:45], v[44:45], v[48:49], v[76:77]
	v_pk_fma_f32 v[42:43], v[42:43], v[58:59], v[74:75]
	v_pk_fma_f32 v[40:41], v[40:41], v[56:57], v[72:73]
	v_lshlrev_b64 v[84:85], 12, v[80:81]
	v_pk_add_f32 v[76:77], v[188:189], v[46:47]
	v_pk_add_f32 v[78:79], v[186:187], v[44:45]
	v_pk_add_f32 v[86:87], v[198:199], v[42:43]
	v_pk_add_f32 v[88:89], v[190:191], v[40:41]
	v_lshlrev_b64 v[82:83], 1, v[82:83]
	v_lshl_add_u64 v[84:85], v[204:205], 0, v[84:85]
	v_cvt_pk_bf16_f32 v72, v78, v79
	v_cvt_pk_bf16_f32 v73, v76, v77
	v_cvt_pk_bf16_f32 v74, v88, v89
	v_cvt_pk_bf16_f32 v75, v86, v87
	v_lshl_add_u64 v[90:91], s[36:37], 0, v[82:83]
	global_load_dwordx4 v[40:43], v[84:85], off offset:16
	global_load_dwordx4 v[44:47], v[84:85], off
	s_waitcnt vmcnt(4)
	v_pk_fma_f32 v[38:39], v[38:39], v[54:55], v[70:71]
	global_store_dwordx4 v[90:91], v[72:75], off
	v_pk_fma_f32 v[36:37], v[36:37], v[52:53], v[68:69]
	v_pk_fma_f32 v[34:35], v[34:35], v[62:63], v[66:67]
	v_mul_f32_e32 v72, v79, v79
	v_mul_f32_e32 v73, v77, v77
	v_fmac_f32_e32 v72, v78, v78
	v_fmac_f32_e32 v73, v76, v76
	v_add_f32_e32 v72, v72, v73
	v_mul_f32_e32 v73, v89, v89
	v_mul_f32_e32 v74, v87, v87
	v_fmac_f32_e32 v73, v88, v88
	v_fmac_f32_e32 v74, v86, v86
	v_add_f32_e32 v73, v73, v74
	v_add_f32_e32 v92, v72, v73
	v_pk_mul_f32 v[74:75], v[164:165], v[76:77]
	v_pk_mul_f32 v[72:73], v[166:167], v[78:79]
	v_pk_mul_f32 v[76:77], v[156:157], v[86:87]
	v_pk_mul_f32 v[78:79], v[158:159], v[88:89]
	v_cvt_pk_bf16_f32 v72, v72, v73
	v_cvt_pk_bf16_f32 v73, v74, v75
	v_cvt_pk_bf16_f32 v74, v78, v79
	v_cvt_pk_bf16_f32 v75, v76, v77
	v_lshl_add_u64 v[76:77], s[8:9], 0, v[82:83]
	global_store_dwordx4 v[76:77], v[72:75], off
	v_pk_fma_f32 v[32:33], v[32:33], v[60:61], v[64:65]
	v_pk_add_f32 v[68:69], v[194:195], v[38:39]
	v_pk_add_f32 v[70:71], v[192:193], v[36:37]
	v_pk_add_f32 v[72:73], v[200:201], v[34:35]
	v_pk_add_f32 v[74:75], v[196:197], v[32:33]
	global_load_dwordx4 v[32:35], v[84:85], off offset:528
	global_load_dwordx4 v[36:39], v[84:85], off offset:512
	v_cvt_pk_bf16_f32 v64, v70, v71
	v_cvt_pk_bf16_f32 v65, v68, v69
	v_cvt_pk_bf16_f32 v66, v74, v75
	v_cvt_pk_bf16_f32 v67, v72, v73
	global_store_dwordx4 v[90:91], v[64:67], off offset:256
	v_or_b32_e32 v82, 0x100, v82
	s_nop 0
	v_mul_f32_e32 v64, v71, v71
	v_mul_f32_e32 v65, v69, v69
	v_fmac_f32_e32 v64, v70, v70
	v_fmac_f32_e32 v65, v68, v68
	v_add_f32_e32 v64, v64, v65
	v_mul_f32_e32 v65, v75, v75
	v_mul_f32_e32 v66, v73, v73
	v_fmac_f32_e32 v65, v74, v74
	v_fmac_f32_e32 v66, v72, v72
	v_add_f32_e32 v64, v92, v64
	v_add_f32_e32 v65, v65, v66
	v_add_f32_e32 v76, v64, v65
	v_pk_mul_f32 v[66:67], v[162:163], v[68:69]
	v_pk_mul_f32 v[64:65], v[160:161], v[70:71]
	v_pk_mul_f32 v[68:69], v[154:155], v[72:73]
	v_pk_mul_f32 v[70:71], v[152:153], v[74:75]
	v_cvt_pk_bf16_f32 v64, v64, v65
	v_cvt_pk_bf16_f32 v65, v66, v67
	v_cvt_pk_bf16_f32 v66, v70, v71
	v_cvt_pk_bf16_f32 v67, v68, v69
	v_lshl_add_u64 v[68:69], s[8:9], 0, v[82:83]
	global_store_dwordx4 v[68:69], v[64:67], off
	v_mov_b32_e32 v244, v76
	v_mov_b32_e32 v245, v76
	s_nop 1
	v_permlane16_swap_b32_e32 v244, v245
	s_waitcnt lgkmcnt(0)
	v_add_f32_e32 v64, v244, v245
	v_mov_b32_e32 v246, v64
	v_mov_b32_e32 v247, v64
	s_nop 1
	v_permlane32_swap_b32_e32 v246, v247
	s_and_saveexec_b64 s[38:39], s[4:5]
	s_cbranch_execz .LBB0_610
	v_lshlrev_b64 v[66:67], 6, v[96:97]
	v_lshl_add_u64 v[66:67], s[12:13], 0, v[66:67]
	v_lshl_add_u64 v[66:67], s[0:1], 2, v[66:67]
	s_lshl_b32 s2, s65, 2
	v_lshl_add_u64 v[66:67], v[66:67], 0, s[2:3]
	s_waitcnt lgkmcnt(0)
	v_add_f32_e32 v64, v246, v247
	global_store_dword v[66:67], v64, off
.LBB0_610:
	s_or_b64 exec, exec, s[38:39]
	s_waitcnt lgkmcnt(0)
	v_lshlrev_b64 v[64:65], 10, v[80:81]
	v_lshl_add_u64 v[66:67], v[64:65], 0, v[202:203]
	v_or_b32_e32 v64, 48, v112
	v_ashrrev_i32_e32 v65, 31, v64
	s_waitcnt vmcnt(6)
	v_pk_fma_f32 v[30:31], v[30:31], v[50:51], v[46:47]
	v_pk_fma_f32 v[28:29], v[28:29], v[48:49], v[44:45]
	v_pk_fma_f32 v[26:27], v[26:27], v[58:59], v[42:43]
	v_pk_fma_f32 v[24:25], v[24:25], v[56:57], v[40:41]
	v_lshlrev_b64 v[68:69], 12, v[64:65]
	v_pk_add_f32 v[44:45], v[188:189], v[30:31]
	v_pk_add_f32 v[46:47], v[186:187], v[28:29]
	v_pk_add_f32 v[70:71], v[198:199], v[26:27]
	v_pk_add_f32 v[72:73], v[190:191], v[24:25]
	v_lshlrev_b64 v[66:67], 1, v[66:67]
	v_lshl_add_u64 v[68:69], v[204:205], 0, v[68:69]
	v_cvt_pk_bf16_f32 v40, v46, v47
	v_cvt_pk_bf16_f32 v41, v44, v45
	v_cvt_pk_bf16_f32 v42, v72, v73
	v_cvt_pk_bf16_f32 v43, v70, v71
	v_lshl_add_u64 v[74:75], s[36:37], 0, v[66:67]
	global_load_dwordx4 v[28:31], v[68:69], off offset:16
	global_load_dwordx4 v[24:27], v[68:69], off
	s_waitcnt vmcnt(4)
	v_pk_fma_f32 v[22:23], v[22:23], v[54:55], v[38:39]
	global_store_dwordx4 v[74:75], v[40:43], off
	v_pk_fma_f32 v[20:21], v[20:21], v[52:53], v[36:37]
	v_pk_fma_f32 v[18:19], v[18:19], v[62:63], v[34:35]
	v_mul_f32_e32 v40, v47, v47
	v_mul_f32_e32 v41, v45, v45
	v_fmac_f32_e32 v40, v46, v46
	v_fmac_f32_e32 v41, v44, v44
	v_add_f32_e32 v40, v40, v41
	v_mul_f32_e32 v41, v73, v73
	v_mul_f32_e32 v42, v71, v71
	v_fmac_f32_e32 v41, v72, v72
	v_fmac_f32_e32 v42, v70, v70
	v_add_f32_e32 v41, v41, v42
	v_add_f32_e32 v76, v40, v41
	v_pk_mul_f32 v[42:43], v[164:165], v[44:45]
	v_pk_mul_f32 v[40:41], v[166:167], v[46:47]
	v_pk_mul_f32 v[44:45], v[156:157], v[70:71]
	v_pk_mul_f32 v[46:47], v[158:159], v[72:73]
	v_cvt_pk_bf16_f32 v40, v40, v41
	v_cvt_pk_bf16_f32 v41, v42, v43
	v_cvt_pk_bf16_f32 v42, v46, v47
	v_cvt_pk_bf16_f32 v43, v44, v45
	v_lshl_add_u64 v[44:45], s[8:9], 0, v[66:67]
	global_store_dwordx4 v[44:45], v[40:43], off
	v_pk_fma_f32 v[16:17], v[16:17], v[60:61], v[32:33]
	v_pk_add_f32 v[36:37], v[194:195], v[22:23]
	v_pk_add_f32 v[38:39], v[192:193], v[20:21]
	v_pk_add_f32 v[40:41], v[200:201], v[18:19]
	v_pk_add_f32 v[42:43], v[196:197], v[16:17]
	global_load_dwordx4 v[20:23], v[68:69], off offset:528
	global_load_dwordx4 v[16:19], v[68:69], off offset:512
	v_cvt_pk_bf16_f32 v32, v38, v39
	v_cvt_pk_bf16_f32 v33, v36, v37
	v_cvt_pk_bf16_f32 v34, v42, v43
	v_cvt_pk_bf16_f32 v35, v40, v41
	global_store_dwordx4 v[74:75], v[32:35], off offset:256
	v_or_b32_e32 v66, 0x100, v66
	s_nop 0
	v_mul_f32_e32 v32, v39, v39
	v_mul_f32_e32 v33, v37, v37
	v_fmac_f32_e32 v32, v38, v38
	v_fmac_f32_e32 v33, v36, v36
	v_add_f32_e32 v32, v32, v33
	v_mul_f32_e32 v33, v43, v43
	v_mul_f32_e32 v34, v41, v41
	v_fmac_f32_e32 v33, v42, v42
	v_fmac_f32_e32 v34, v40, v40
	v_add_f32_e32 v32, v76, v32
	v_add_f32_e32 v33, v33, v34
	v_add_f32_e32 v44, v32, v33
	v_pk_mul_f32 v[34:35], v[162:163], v[36:37]
	v_pk_mul_f32 v[32:33], v[160:161], v[38:39]
	v_pk_mul_f32 v[36:37], v[154:155], v[40:41]
	v_pk_mul_f32 v[38:39], v[152:153], v[42:43]
	v_cvt_pk_bf16_f32 v32, v32, v33
	v_cvt_pk_bf16_f32 v33, v34, v35
	v_cvt_pk_bf16_f32 v34, v38, v39
	v_cvt_pk_bf16_f32 v35, v36, v37
	v_lshl_add_u64 v[36:37], s[8:9], 0, v[66:67]
	global_store_dwordx4 v[36:37], v[32:35], off
	v_mov_b32_e32 v244, v44
	v_mov_b32_e32 v245, v44
	s_nop 1
	v_permlane16_swap_b32_e32 v244, v245
	s_waitcnt lgkmcnt(0)
	v_add_f32_e32 v32, v244, v245
	v_mov_b32_e32 v246, v32
	v_mov_b32_e32 v247, v32
	s_nop 1
	v_permlane32_swap_b32_e32 v246, v247
	s_and_saveexec_b64 s[38:39], s[4:5]
	s_cbranch_execz .LBB0_612
	v_lshlrev_b64 v[34:35], 6, v[80:81]
	v_lshl_add_u64 v[34:35], s[12:13], 0, v[34:35]
	v_lshl_add_u64 v[34:35], s[0:1], 2, v[34:35]
	s_lshl_b32 s2, s65, 2
	v_lshl_add_u64 v[34:35], v[34:35], 0, s[2:3]
	s_waitcnt lgkmcnt(0)
	v_add_f32_e32 v32, v246, v247
	global_store_dword v[34:35], v32, off
.LBB0_612:
	s_or_b64 exec, exec, s[38:39]
	s_waitcnt lgkmcnt(0)
	v_lshlrev_b64 v[32:33], 10, v[64:65]
	v_lshl_add_u64 v[32:33], v[32:33], 0, v[202:203]
	s_waitcnt vmcnt(7)
	v_pk_fma_f32 v[14:15], v[14:15], v[58:59], v[30:31]
	v_pk_fma_f32 v[12:13], v[12:13], v[56:57], v[28:29]
	s_waitcnt vmcnt(6)
	v_pk_fma_f32 v[10:11], v[10:11], v[50:51], v[26:27]
	v_pk_fma_f32 v[8:9], v[8:9], v[48:49], v[24:25]
	v_pk_add_f32 v[14:15], v[198:199], v[14:15]
	v_pk_add_f32 v[12:13], v[190:191], v[12:13]
	v_pk_add_f32 v[24:25], v[188:189], v[10:11]
	v_pk_add_f32 v[26:27], v[186:187], v[8:9]
	v_lshlrev_b64 v[28:29], 1, v[32:33]
	v_cvt_pk_bf16_f32 v8, v26, v27
	v_cvt_pk_bf16_f32 v9, v24, v25
	v_cvt_pk_bf16_f32 v10, v12, v13
	v_cvt_pk_bf16_f32 v11, v14, v15
	v_lshl_add_u64 v[30:31], s[36:37], 0, v[28:29]
	global_store_dwordx4 v[30:31], v[8:11], off
	v_pk_mul_f32 v[32:33], v[156:157], v[14:15]
	v_pk_mul_f32 v[34:35], v[158:159], v[12:13]
	v_pk_mul_f32 v[10:11], v[164:165], v[24:25]
	v_pk_mul_f32 v[8:9], v[166:167], v[26:27]
	s_waitcnt vmcnt(4)
	v_pk_fma_f32 v[0:1], v[0:1], v[60:61], v[20:21]
	v_cvt_pk_bf16_f32 v8, v8, v9
	v_cvt_pk_bf16_f32 v9, v10, v11
	v_cvt_pk_bf16_f32 v10, v34, v35
	v_cvt_pk_bf16_f32 v11, v32, v33
	v_lshl_add_u64 v[32:33], s[8:9], 0, v[28:29]
	global_store_dwordx4 v[32:33], v[8:11], off
	v_pk_fma_f32 v[2:3], v[2:3], v[62:63], v[22:23]
	v_or_b32_e32 v28, 0x100, v28
	v_pk_add_f32 v[10:11], v[196:197], v[0:1]
	s_waitcnt vmcnt(4)
	v_pk_fma_f32 v[0:1], v[6:7], v[54:55], v[18:19]
	v_pk_add_f32 v[8:9], v[200:201], v[2:3]
	v_pk_fma_f32 v[2:3], v[4:5], v[52:53], v[16:17]
	v_pk_add_f32 v[4:5], v[194:195], v[0:1]
	v_mul_f32_e32 v0, v27, v27
	v_mul_f32_e32 v1, v25, v25
	v_fmac_f32_e32 v0, v26, v26
	v_fmac_f32_e32 v1, v24, v24
	v_pk_add_f32 v[6:7], v[192:193], v[2:3]
	v_add_f32_e32 v0, v0, v1
	v_mul_f32_e32 v1, v13, v13
	v_mul_f32_e32 v2, v15, v15
	v_fmac_f32_e32 v1, v12, v12
	v_fmac_f32_e32 v2, v14, v14
	v_add_f32_e32 v1, v1, v2
	v_add_f32_e32 v12, v0, v1
	v_cvt_pk_bf16_f32 v0, v6, v7
	v_cvt_pk_bf16_f32 v1, v4, v5
	v_cvt_pk_bf16_f32 v2, v10, v11
	v_cvt_pk_bf16_f32 v3, v8, v9
	global_store_dwordx4 v[30:31], v[0:3], off offset:256
	s_nop 1
	v_mul_f32_e32 v0, v7, v7
	v_mul_f32_e32 v1, v5, v5
	v_fmac_f32_e32 v0, v6, v6
	v_fmac_f32_e32 v1, v4, v4
	v_add_f32_e32 v0, v0, v1
	v_mul_f32_e32 v1, v11, v11
	v_mul_f32_e32 v2, v9, v9
	v_fmac_f32_e32 v1, v10, v10
	v_fmac_f32_e32 v2, v8, v8
	v_add_f32_e32 v0, v12, v0
	v_add_f32_e32 v1, v1, v2
	v_add_f32_e32 v12, v1, v0
	v_pk_mul_f32 v[2:3], v[160:161], v[6:7]
	v_pk_mul_f32 v[6:7], v[154:155], v[8:9]
	v_mov_b32_e32 v244, v12
	v_mov_b32_e32 v245, v12
	s_nop 1
	v_permlane16_swap_b32_e32 v244, v245
	v_pk_mul_f32 v[0:1], v[162:163], v[4:5]
	v_cvt_pk_bf16_f32 v2, v2, v3
	v_cvt_pk_bf16_f32 v3, v0, v1
	v_pk_mul_f32 v[4:5], v[152:153], v[10:11]
	s_waitcnt lgkmcnt(0)
	v_add_f32_e32 v0, v244, v245
	v_mov_b32_e32 v246, v0
	v_mov_b32_e32 v247, v0
	s_nop 1
	v_permlane32_swap_b32_e32 v246, v247
	v_cvt_pk_bf16_f32 v4, v4, v5
	v_cvt_pk_bf16_f32 v5, v6, v7
	v_lshl_add_u64 v[6:7], s[8:9], 0, v[28:29]
	global_store_dwordx4 v[6:7], v[2:5], off
	s_and_saveexec_b64 s[36:37], s[4:5]
	s_cbranch_execz .LBB0_561
	v_lshlrev_b64 v[2:3], 6, v[64:65]
	v_lshl_add_u64 v[2:3], s[12:13], 0, v[2:3]
	v_lshl_add_u64 v[2:3], s[0:1], 2, v[2:3]
	s_lshl_b32 s2, s65, 2
	v_lshl_add_u64 v[2:3], v[2:3], 0, s[2:3]
	s_waitcnt lgkmcnt(0)
	v_add_f32_e32 v0, v246, v247
	global_store_dword v[2:3], v0, off
	s_branch .LBB0_561

.LBB0_876:
	ds_read_b128 v[68:71], v194
	ds_read_b128 v[76:79], v194 offset:1024
	ds_read_b128 v[136:139], v194 offset:2048
	ds_read_b128 v[140:143], v194 offset:3072
	s_add_u32 s40, s0, 0xfff00080
	s_addc_u32 s41, s1, -1
	s_cmp_eq_u32 s67, 60
	s_cselect_b32 s45, s29, s41
	s_cselect_b32 s44, s43, s40
	s_cselect_b32 s41, s27, s47
	s_cselect_b32 s40, s48, s46
	v_lshl_add_u64 v[206:207], s[0:1], 0, v[152:153]
	s_add_i32 m0, s49, 0xc000
	ds_read_b128 v[160:163], v195
	ds_read_b128 v[164:167], v195 offset:1024
	ds_read_b128 v[170:173], v195 offset:2048
	ds_read_b128 v[174:177], v195 offset:3072
	ds_read_b128 v[178:181], v195 offset:4096
	ds_read_b128 v[182:185], v195 offset:5120
	ds_read_b128 v[198:201], v195 offset:6144
	ds_read_b128 v[202:205], v195 offset:7168
	global_load_lds_dwordx4 v[206:207], off
	v_lshl_add_u64 v[206:207], s[0:1], 0, v[154:155]
	s_add_i32 m0, s49, 0xe000
	s_nop 0
	global_load_lds_dwordx4 v[206:207], off
	s_waitcnt lgkmcnt(8)
	s_barrier
	s_waitcnt lgkmcnt(0)
	s_setprio 1
	s_waitcnt lgkmcnt(0)
	v_mfma_f32_16x16x32_bf16 v[92:95], v[68:71], v[160:163], v[92:95]
	v_mfma_f32_16x16x32_bf16 v[88:91], v[136:139], v[160:163], v[88:91]
	v_mfma_f32_16x16x32_bf16 v[124:127], v[68:71], v[170:173], v[124:127]
	v_mfma_f32_16x16x32_bf16 v[120:123], v[136:139], v[170:173], v[120:123]
	v_mfma_f32_16x16x32_bf16 v[108:111], v[68:71], v[178:181], v[108:111]
	v_mfma_f32_16x16x32_bf16 v[104:107], v[136:139], v[178:181], v[104:107]
	v_mfma_f32_16x16x32_bf16 v[84:87], v[68:71], v[198:201], v[84:87]
	v_mfma_f32_16x16x32_bf16 v[80:83], v[136:139], v[198:201], v[80:83]
	v_mfma_f32_16x16x32_bf16 v[92:95], v[76:79], v[164:167], v[92:95]
	v_mfma_f32_16x16x32_bf16 v[88:91], v[140:143], v[164:167], v[88:91]
	v_mfma_f32_16x16x32_bf16 v[124:127], v[76:79], v[174:177], v[124:127]
	v_mfma_f32_16x16x32_bf16 v[120:123], v[140:143], v[174:177], v[120:123]
	v_mfma_f32_16x16x32_bf16 v[108:111], v[76:79], v[182:185], v[108:111]
	v_mfma_f32_16x16x32_bf16 v[104:107], v[140:143], v[182:185], v[104:107]
	v_mfma_f32_16x16x32_bf16 v[84:87], v[76:79], v[202:205], v[84:87]
	v_mfma_f32_16x16x32_bf16 v[80:83], v[140:143], v[202:205], v[80:83]
	s_setprio 0
	s_barrier
	s_add_i32 s68, s64, s52
	v_lshl_add_u64 v[222:223], s[40:41], 0, v[146:147]
	s_mov_b32 m0, s68
	ds_read_b128 v[206:209], v196
	ds_read_b128 v[210:213], v196 offset:1024
	ds_read_b128 v[214:217], v196 offset:2048
	ds_read_b128 v[218:221], v196 offset:3072
	global_load_lds_dwordx4 v[222:223], off
	v_lshl_add_u64 v[224:225], s[40:41], 0, v[150:151]
	s_add_i32 m0, s68, 0x2000
	s_nop 0
	global_load_lds_dwordx4 v[224:225], off
	s_barrier
	s_waitcnt lgkmcnt(0)
	s_setprio 1
	s_waitcnt lgkmcnt(0)
	v_mfma_f32_16x16x32_bf16 v[132:135], v[206:209], v[160:163], v[132:135]
	v_mfma_f32_16x16x32_bf16 v[128:131], v[214:217], v[160:163], v[128:131]
	v_mfma_f32_16x16x32_bf16 v[116:119], v[206:209], v[170:173], v[116:119]
	v_mfma_f32_16x16x32_bf16 v[112:115], v[214:217], v[170:173], v[112:115]
	v_mfma_f32_16x16x32_bf16 v[100:103], v[206:209], v[178:181], v[100:103]
	v_mfma_f32_16x16x32_bf16 v[96:99], v[214:217], v[178:181], v[96:99]
	v_mfma_f32_16x16x32_bf16 v[72:75], v[206:209], v[198:201], v[72:75]
	v_mfma_f32_16x16x32_bf16 v[64:67], v[214:217], v[198:201], v[64:67]
	v_mfma_f32_16x16x32_bf16 v[132:135], v[210:213], v[164:167], v[132:135]
	v_mfma_f32_16x16x32_bf16 v[128:131], v[218:221], v[164:167], v[128:131]
	v_mfma_f32_16x16x32_bf16 v[116:119], v[210:213], v[174:177], v[116:119]
	v_mfma_f32_16x16x32_bf16 v[112:115], v[218:221], v[174:177], v[112:115]
	v_mfma_f32_16x16x32_bf16 v[100:103], v[210:213], v[182:185], v[100:103]
	v_mfma_f32_16x16x32_bf16 v[96:99], v[218:221], v[182:185], v[96:99]
	v_mfma_f32_16x16x32_bf16 v[72:75], v[210:213], v[202:205], v[72:75]
	v_mfma_f32_16x16x32_bf16 v[64:67], v[218:221], v[202:205], v[64:67]
	s_setprio 0
	s_mov_b32 m0, s49
	v_lshl_add_u64 v[226:227], s[44:45], 0, v[144:145]
	s_barrier
	ds_read_b128 v[160:163], v195 offset:16384
	ds_read_b128 v[164:167], v195 offset:17408
	ds_read_b128 v[170:173], v195 offset:18432
	ds_read_b128 v[174:177], v195 offset:19456
	ds_read_b128 v[178:181], v195 offset:20480
	ds_read_b128 v[182:185], v195 offset:21504
	ds_read_b128 v[198:201], v195 offset:22528
	ds_read_b128 v[202:205], v195 offset:23552
	global_load_lds_dwordx4 v[226:227], off
	v_lshl_add_u64 v[228:229], s[44:45], 0, v[148:149]
	s_mov_b32 m0, s53
	s_nop 0
	global_load_lds_dwordx4 v[228:229], off
	s_barrier
	s_waitcnt lgkmcnt(0)
	s_setprio 1
	s_waitcnt lgkmcnt(0)
	v_mfma_f32_16x16x32_bf16 v[60:63], v[68:71], v[160:163], v[60:63]
	v_mfma_f32_16x16x32_bf16 v[56:59], v[136:139], v[160:163], v[56:59]
	v_mfma_f32_16x16x32_bf16 v[44:47], v[68:71], v[170:173], v[44:47]
	v_mfma_f32_16x16x32_bf16 v[40:43], v[136:139], v[170:173], v[40:43]
	v_mfma_f32_16x16x32_bf16 v[28:31], v[68:71], v[178:181], v[28:31]
	v_mfma_f32_16x16x32_bf16 v[24:27], v[136:139], v[178:181], v[24:27]
	v_mfma_f32_16x16x32_bf16 v[8:11], v[68:71], v[198:201], v[8:11]
	v_mfma_f32_16x16x32_bf16 v[12:15], v[136:139], v[198:201], v[12:15]
	v_mfma_f32_16x16x32_bf16 v[60:63], v[76:79], v[164:167], v[60:63]
	v_mfma_f32_16x16x32_bf16 v[56:59], v[140:143], v[164:167], v[56:59]
	v_mfma_f32_16x16x32_bf16 v[44:47], v[76:79], v[174:177], v[44:47]
	v_mfma_f32_16x16x32_bf16 v[40:43], v[140:143], v[174:177], v[40:43]
	v_mfma_f32_16x16x32_bf16 v[28:31], v[76:79], v[182:185], v[28:31]
	v_mfma_f32_16x16x32_bf16 v[24:27], v[140:143], v[182:185], v[24:27]
	v_mfma_f32_16x16x32_bf16 v[8:11], v[76:79], v[202:205], v[8:11]
	v_mfma_f32_16x16x32_bf16 v[12:15], v[140:143], v[202:205], v[12:15]
	s_setprio 0
	s_barrier
	s_add_u32 s68, s40, 0x100000
	s_addc_u32 s69, s41, 0
	s_add_i32 s70, s65, s52
	v_lshl_add_u64 v[68:69], s[68:69], 0, v[146:147]
	s_mov_b32 m0, s70
	s_nop 0
	global_load_lds_dwordx4 v[68:69], off
	v_lshl_add_u64 v[68:69], s[68:69], 0, v[150:151]
	s_add_i32 m0, s70, 0x2000
	s_nop 0
	global_load_lds_dwordx4 v[68:69], off
	s_waitcnt vmcnt(6)
	s_barrier
	s_setprio 1
	v_mfma_f32_16x16x32_bf16 v[52:55], v[206:209], v[160:163], v[52:55]
	v_mfma_f32_16x16x32_bf16 v[48:51], v[214:217], v[160:163], v[48:51]
	v_mfma_f32_16x16x32_bf16 v[36:39], v[206:209], v[170:173], v[36:39]
	v_mfma_f32_16x16x32_bf16 v[32:35], v[214:217], v[170:173], v[32:35]
	v_mfma_f32_16x16x32_bf16 v[20:23], v[206:209], v[178:181], v[20:23]
	v_mfma_f32_16x16x32_bf16 v[16:19], v[214:217], v[178:181], v[16:19]
	v_mfma_f32_16x16x32_bf16 v[0:3], v[206:209], v[198:201], v[0:3]
	v_mfma_f32_16x16x32_bf16 v[4:7], v[214:217], v[198:201], v[4:7]
	v_mfma_f32_16x16x32_bf16 v[52:55], v[210:213], v[164:167], v[52:55]
	v_mfma_f32_16x16x32_bf16 v[48:51], v[218:221], v[164:167], v[48:51]
	v_mfma_f32_16x16x32_bf16 v[36:39], v[210:213], v[174:177], v[36:39]
	v_mfma_f32_16x16x32_bf16 v[32:35], v[218:221], v[174:177], v[32:35]
	v_mfma_f32_16x16x32_bf16 v[20:23], v[210:213], v[182:185], v[20:23]
	v_mfma_f32_16x16x32_bf16 v[16:19], v[218:221], v[182:185], v[16:19]
	v_mfma_f32_16x16x32_bf16 v[0:3], v[210:213], v[202:205], v[0:3]
	v_mfma_f32_16x16x32_bf16 v[4:7], v[218:221], v[202:205], v[4:7]
	s_setprio 0
	s_add_i32 s68, 0, 0x18000
	v_add_u32_e32 v140, s68, v189
	s_barrier
	ds_read_b128 v[68:71], v140
	ds_read_b128 v[76:79], v140 offset:1024
	ds_read_b128 v[136:139], v140 offset:2048
	ds_read_b128 v[140:143], v140 offset:3072
	s_add_u32 s44, s44, 0x100000
	s_addc_u32 s45, s45, 0
	s_mov_b32 m0, s54
	v_lshl_add_u64 v[206:207], s[44:45], 0, v[144:145]
	ds_read_b128 v[160:163], v195 offset:32768
	ds_read_b128 v[164:167], v195 offset:33792
	ds_read_b128 v[170:173], v195 offset:34816
	ds_read_b128 v[174:177], v195 offset:35840
	ds_read_b128 v[178:181], v195 offset:36864
	ds_read_b128 v[182:185], v195 offset:37888
	ds_read_b128 v[198:201], v195 offset:38912
	ds_read_b128 v[202:205], v195 offset:39936
	global_load_lds_dwordx4 v[206:207], off
	v_lshl_add_u64 v[206:207], s[44:45], 0, v[148:149]
	s_mov_b32 m0, s55
	s_nop 0
	global_load_lds_dwordx4 v[206:207], off
	s_waitcnt lgkmcnt(8)
	s_barrier
	s_waitcnt lgkmcnt(0)
	s_setprio 1
	s_waitcnt lgkmcnt(0)
	v_mfma_f32_16x16x32_bf16 v[92:95], v[68:71], v[160:163], v[92:95]
	v_mfma_f32_16x16x32_bf16 v[88:91], v[136:139], v[160:163], v[88:91]
	v_mfma_f32_16x16x32_bf16 v[124:127], v[68:71], v[170:173], v[124:127]
	v_mfma_f32_16x16x32_bf16 v[120:123], v[136:139], v[170:173], v[120:123]
	v_mfma_f32_16x16x32_bf16 v[108:111], v[68:71], v[178:181], v[108:111]
	v_mfma_f32_16x16x32_bf16 v[104:107], v[136:139], v[178:181], v[104:107]
	v_mfma_f32_16x16x32_bf16 v[84:87], v[68:71], v[198:201], v[84:87]
	v_mfma_f32_16x16x32_bf16 v[80:83], v[136:139], v[198:201], v[80:83]
	v_mfma_f32_16x16x32_bf16 v[92:95], v[76:79], v[164:167], v[92:95]
	v_mfma_f32_16x16x32_bf16 v[88:91], v[140:143], v[164:167], v[88:91]
	v_mfma_f32_16x16x32_bf16 v[124:127], v[76:79], v[174:177], v[124:127]
	v_mfma_f32_16x16x32_bf16 v[120:123], v[140:143], v[174:177], v[120:123]
	v_mfma_f32_16x16x32_bf16 v[108:111], v[76:79], v[182:185], v[108:111]
	v_mfma_f32_16x16x32_bf16 v[104:107], v[140:143], v[182:185], v[104:107]
	v_mfma_f32_16x16x32_bf16 v[84:87], v[76:79], v[202:205], v[84:87]
	v_mfma_f32_16x16x32_bf16 v[80:83], v[140:143], v[202:205], v[80:83]
	s_setprio 0
	s_barrier
	s_add_i32 s44, 0, 0x1c000
	s_add_i32 s45, s68, s52
	v_add_u32_e32 v218, s44, v189
	v_lshl_add_u64 v[222:223], v[222:223], 0, s[20:21]
	s_mov_b32 m0, s45
	ds_read_b128 v[206:209], v218
	ds_read_b128 v[210:213], v218 offset:1024
	ds_read_b128 v[214:217], v218 offset:2048
	ds_read_b128 v[218:221], v218 offset:3072
	global_load_lds_dwordx4 v[222:223], off
	v_lshl_add_u64 v[222:223], v[224:225], 0, s[20:21]
	s_add_i32 m0, s45, 0x2000
	s_nop 0
	global_load_lds_dwordx4 v[222:223], off
	s_barrier
	s_waitcnt lgkmcnt(0)
	s_setprio 1
	s_waitcnt lgkmcnt(0)
	v_mfma_f32_16x16x32_bf16 v[132:135], v[206:209], v[160:163], v[132:135]
	v_mfma_f32_16x16x32_bf16 v[128:131], v[214:217], v[160:163], v[128:131]
	v_mfma_f32_16x16x32_bf16 v[116:119], v[206:209], v[170:173], v[116:119]
	v_mfma_f32_16x16x32_bf16 v[112:115], v[214:217], v[170:173], v[112:115]
	v_mfma_f32_16x16x32_bf16 v[100:103], v[206:209], v[178:181], v[100:103]
	v_mfma_f32_16x16x32_bf16 v[96:99], v[214:217], v[178:181], v[96:99]
	v_mfma_f32_16x16x32_bf16 v[72:75], v[206:209], v[198:201], v[72:75]
	v_mfma_f32_16x16x32_bf16 v[64:67], v[214:217], v[198:201], v[64:67]
	v_mfma_f32_16x16x32_bf16 v[132:135], v[210:213], v[164:167], v[132:135]
	v_mfma_f32_16x16x32_bf16 v[128:131], v[218:221], v[164:167], v[128:131]
	v_mfma_f32_16x16x32_bf16 v[116:119], v[210:213], v[174:177], v[116:119]
	v_mfma_f32_16x16x32_bf16 v[112:115], v[218:221], v[174:177], v[112:115]
	v_mfma_f32_16x16x32_bf16 v[100:103], v[210:213], v[182:185], v[100:103]
	v_mfma_f32_16x16x32_bf16 v[96:99], v[218:221], v[182:185], v[96:99]
	v_mfma_f32_16x16x32_bf16 v[72:75], v[210:213], v[202:205], v[72:75]
	v_mfma_f32_16x16x32_bf16 v[64:67], v[218:221], v[202:205], v[64:67]
	s_setprio 0
	s_mov_b32 m0, s59
	v_lshl_add_u64 v[222:223], v[226:227], 0, s[20:21]
	s_barrier
	ds_read_b128 v[160:163], v195 offset:49152
	ds_read_b128 v[164:167], v195 offset:50176
	ds_read_b128 v[170:173], v195 offset:51200
	ds_read_b128 v[174:177], v195 offset:52224
	ds_read_b128 v[178:181], v195 offset:53248
	ds_read_b128 v[182:185], v195 offset:54272
	ds_read_b128 v[198:201], v195 offset:55296
	ds_read_b128 v[202:205], v195 offset:56320
	global_load_lds_dwordx4 v[222:223], off
	v_lshl_add_u64 v[222:223], v[228:229], 0, s[20:21]
	s_mov_b32 m0, s60
	s_nop 0
	global_load_lds_dwordx4 v[222:223], off
	s_barrier
	s_waitcnt lgkmcnt(0)
	s_setprio 1
	s_waitcnt lgkmcnt(0)
	v_mfma_f32_16x16x32_bf16 v[60:63], v[68:71], v[160:163], v[60:63]
	v_mfma_f32_16x16x32_bf16 v[56:59], v[136:139], v[160:163], v[56:59]
	v_mfma_f32_16x16x32_bf16 v[44:47], v[68:71], v[170:173], v[44:47]
	v_mfma_f32_16x16x32_bf16 v[40:43], v[136:139], v[170:173], v[40:43]
	v_mfma_f32_16x16x32_bf16 v[28:31], v[68:71], v[178:181], v[28:31]
	v_mfma_f32_16x16x32_bf16 v[24:27], v[136:139], v[178:181], v[24:27]
	v_mfma_f32_16x16x32_bf16 v[8:11], v[68:71], v[198:201], v[8:11]
	v_mfma_f32_16x16x32_bf16 v[12:15], v[136:139], v[198:201], v[12:15]
	v_mfma_f32_16x16x32_bf16 v[60:63], v[76:79], v[164:167], v[60:63]
	v_mfma_f32_16x16x32_bf16 v[56:59], v[140:143], v[164:167], v[56:59]
	v_mfma_f32_16x16x32_bf16 v[44:47], v[76:79], v[174:177], v[44:47]
	v_mfma_f32_16x16x32_bf16 v[40:43], v[140:143], v[174:177], v[40:43]
	v_mfma_f32_16x16x32_bf16 v[28:31], v[76:79], v[182:185], v[28:31]
	v_mfma_f32_16x16x32_bf16 v[24:27], v[140:143], v[182:185], v[24:27]
	v_mfma_f32_16x16x32_bf16 v[8:11], v[76:79], v[202:205], v[8:11]
	v_mfma_f32_16x16x32_bf16 v[12:15], v[140:143], v[202:205], v[12:15]
	s_setprio 0
	s_barrier
	s_add_u32 s40, s40, 0x100080
	s_addc_u32 s41, s41, 0
	s_add_i32 s44, s44, s52
	v_lshl_add_u64 v[68:69], s[40:41], 0, v[146:147]
	s_mov_b32 m0, s44
	s_nop 0
	global_load_lds_dwordx4 v[68:69], off
	v_lshl_add_u64 v[68:69], s[40:41], 0, v[150:151]
	s_add_i32 m0, s44, 0x2000
	s_nop 0
	global_load_lds_dwordx4 v[68:69], off
	s_waitcnt vmcnt(6)
	s_barrier
	s_setprio 1
	v_mfma_f32_16x16x32_bf16 v[52:55], v[206:209], v[160:163], v[52:55]
	v_mfma_f32_16x16x32_bf16 v[48:51], v[214:217], v[160:163], v[48:51]
	v_mfma_f32_16x16x32_bf16 v[36:39], v[206:209], v[170:173], v[36:39]
	v_mfma_f32_16x16x32_bf16 v[32:35], v[214:217], v[170:173], v[32:35]
	v_mfma_f32_16x16x32_bf16 v[20:23], v[206:209], v[178:181], v[20:23]
	v_mfma_f32_16x16x32_bf16 v[16:19], v[214:217], v[178:181], v[16:19]
	v_mfma_f32_16x16x32_bf16 v[0:3], v[206:209], v[198:201], v[0:3]
	v_mfma_f32_16x16x32_bf16 v[4:7], v[214:217], v[198:201], v[4:7]
	v_mfma_f32_16x16x32_bf16 v[52:55], v[210:213], v[164:167], v[52:55]
	v_mfma_f32_16x16x32_bf16 v[48:51], v[218:221], v[164:167], v[48:51]
	v_mfma_f32_16x16x32_bf16 v[36:39], v[210:213], v[174:177], v[36:39]
	v_mfma_f32_16x16x32_bf16 v[32:35], v[218:221], v[174:177], v[32:35]
	v_mfma_f32_16x16x32_bf16 v[20:23], v[210:213], v[182:185], v[20:23]
	v_mfma_f32_16x16x32_bf16 v[16:19], v[218:221], v[182:185], v[16:19]
	v_mfma_f32_16x16x32_bf16 v[0:3], v[210:213], v[202:205], v[0:3]
	v_mfma_f32_16x16x32_bf16 v[4:7], v[218:221], v[202:205], v[4:7]
	s_setprio 0
	s_add_i32 s67, s67, 2
	s_add_u32 s0, s0, 0x100
	s_addc_u32 s1, s1, 0
	s_add_u32 s46, s46, 0x100
	s_addc_u32 s47, s47, 0
	s_cmp_gt_u32 s67, 61
	s_barrier
	s_cbranch_scc0 .LBB0_876
	v_add_u32_e32 v224, s39, v192
	ds_read_b128 v[136:139], v224 offset:3072
	ds_read_b128 v[68:71], v224
	ds_read_b128 v[76:79], v224 offset:16
	ds_read_b128 v[140:143], v224 offset:2048
	ds_read_b128 v[164:167], v224 offset:3088
	s_waitcnt lgkmcnt(0)
	v_pk_add_f32 v[160:161], v[138:139], 1.0 op_sel_hi:[1,0]
	v_pk_add_f32 v[162:163], v[136:137], 1.0 op_sel_hi:[1,0]
	ds_read_b128 v[136:139], v224 offset:2064
	v_pk_mul_f32 v[160:161], v[142:143], v[160:161]
	v_pk_mul_f32 v[162:163], v[140:141], v[162:163]
	v_pk_add_f32 v[140:141], v[166:167], 1.0 op_sel_hi:[1,0]
	v_pk_add_f32 v[142:143], v[164:165], 1.0 op_sel_hi:[1,0]
	v_add_u32_e32 v172, s61, v190
	s_waitcnt lgkmcnt(0)
	v_pk_mul_f32 v[164:165], v[138:139], v[140:141]
	v_pk_mul_f32 v[166:167], v[136:137], v[142:143]
	ds_read_b128 v[136:139], v224 offset:3584
	ds_read_b128 v[176:179], v224 offset:2560
	ds_read_b128 v[140:143], v172
	ds_read_b128 v[198:201], v224 offset:3600
	v_add_u32_e32 v182, s33, v188
	ds_read_b128 v[202:205], v172 offset:1024
	v_or_b32_e32 v172, s42, v191
	v_ashrrev_i32_e32 v183, 31, v182
	s_waitcnt lgkmcnt(0)
	v_pk_add_f32 v[170:171], v[138:139], 1.0 op_sel_hi:[1,0]
	v_pk_add_f32 v[210:211], v[136:137], 1.0 op_sel_hi:[1,0]
	v_lshlrev_b32_e32 v136, 16, v140
	v_and_b32_e32 v137, 0xffff0000, v140
	v_lshlrev_b32_e32 v138, 16, v141
	v_and_b32_e32 v139, 0xffff0000, v141
	v_lshlrev_b32_e32 v140, 16, v142
	v_and_b32_e32 v141, 0xffff0000, v142
	v_lshlrev_b32_e32 v142, 16, v143
	v_and_b32_e32 v143, 0xffff0000, v143
	v_ashrrev_i32_e32 v173, 31, v172
	v_lshlrev_b64 v[174:175], 10, v[182:183]
	v_or_b32_e32 v184, 16, v182
	v_lshl_add_u64 v[174:175], v[174:175], 0, v[172:173]
	v_ashrrev_i32_e32 v185, 31, v184
	v_pk_fma_f32 v[94:95], v[94:95], v[70:71], v[138:139]
	v_pk_fma_f32 v[92:93], v[92:93], v[68:69], v[136:137]
	v_pk_fma_f32 v[90:91], v[90:91], v[78:79], v[142:143]
	v_pk_fma_f32 v[88:89], v[88:89], v[76:77], v[140:141]
	v_lshl_add_u64 v[180:181], v[172:173], 1, s[30:31]
	v_lshlrev_b64 v[206:207], 11, v[184:185]
	v_pk_add_f32 v[212:213], v[94:95], 0 op_sel_hi:[1,0]
	v_pk_add_f32 v[214:215], v[92:93], 0 op_sel_hi:[1,0]
	v_pk_add_f32 v[216:217], v[90:91], 0 op_sel_hi:[1,0]
	v_pk_add_f32 v[218:219], v[88:89], 0 op_sel_hi:[1,0]
	v_lshlrev_b64 v[220:221], 1, v[174:175]
	v_lshl_add_u64 v[206:207], v[180:181], 0, v[206:207]
	v_cvt_pk_bf16_f32 v88, v214, v215
	v_cvt_pk_bf16_f32 v89, v212, v213
	v_cvt_pk_bf16_f32 v90, v218, v219
	v_cvt_pk_bf16_f32 v91, v216, v217
	v_lshl_add_u64 v[222:223], s[30:31], 0, v[220:221]
	v_readlane_b32 s40, v243, 54
	global_load_dwordx4 v[140:143], v[206:207], off
	v_pk_mul_f32 v[92:93], v[164:165], v[216:217]
	global_store_dwordx4 v[222:223], v[88:91], off
	v_pk_mul_f32 v[94:95], v[166:167], v[218:219]
	v_readlane_b32 s41, v243, 55
	v_pk_mul_f32 v[90:91], v[160:161], v[212:213]
	v_pk_mul_f32 v[88:89], v[162:163], v[214:215]
	v_pk_mul_f32 v[174:175], v[178:179], v[170:171]
	v_cvt_pk_bf16_f32 v88, v88, v89
	v_cvt_pk_bf16_f32 v89, v90, v91
	v_cvt_pk_bf16_f32 v90, v94, v95
	v_cvt_pk_bf16_f32 v91, v92, v93
	v_lshl_add_u64 v[92:93], s[40:41], 0, v[220:221]
	global_store_dwordx4 v[92:93], v[88:91], off
	global_load_dwordx4 v[136:139], v[206:207], off offset:256
	ds_read_b128 v[206:209], v224 offset:2576
	ds_read_b128 v[88:91], v224 offset:512
	ds_read_b128 v[92:95], v224 offset:528
	v_pk_add_f32 v[170:171], v[200:201], 1.0 op_sel_hi:[1,0]
	v_pk_add_f32 v[198:199], v[198:199], 1.0 op_sel_hi:[1,0]
	v_lshlrev_b32_e32 v200, 16, v202
	s_waitcnt lgkmcnt(0)
	v_pk_mul_f32 v[178:179], v[208:209], v[170:171]
	v_pk_mul_f32 v[170:171], v[206:207], v[198:199]
	v_and_b32_e32 v199, 64, v197
	v_xor_b32_e32 v198, 16, v197
	v_add_u32_e32 v208, 64, v199
	v_cmp_lt_i32_e32 vcc, v198, v208
	v_and_b32_e32 v201, 0xffff0000, v202
	v_lshlrev_b32_e32 v202, 16, v203
	v_and_b32_e32 v203, 0xffff0000, v203
	v_lshlrev_b32_e32 v206, 16, v204
	v_and_b32_e32 v207, 0xffff0000, v204
	v_lshlrev_b32_e32 v204, 16, v205
	v_and_b32_e32 v205, 0xffff0000, v205
	v_cndmask_b32_e32 v198, v197, v198, vcc
	v_lshlrev_b32_e32 v199, 2, v198
	v_xor_b32_e32 v198, 32, v197
	v_pk_fma_f32 v[134:135], v[134:135], v[90:91], v[202:203]
	v_pk_fma_f32 v[132:133], v[132:133], v[88:89], v[200:201]
	v_pk_fma_f32 v[130:131], v[130:131], v[94:95], v[204:205]
	v_pk_fma_f32 v[128:129], v[128:129], v[92:93], v[206:207]
	v_cmp_lt_i32_e32 vcc, v198, v208
	v_mul_f32_e32 v208, v215, v215
	v_mul_f32_e32 v209, v213, v213
	v_pk_add_f32 v[134:135], v[134:135], 0 op_sel_hi:[1,0]
	v_pk_add_f32 v[132:133], v[132:133], 0 op_sel_hi:[1,0]
	v_pk_add_f32 v[200:201], v[130:131], 0 op_sel_hi:[1,0]
	v_pk_add_f32 v[202:203], v[128:129], 0 op_sel_hi:[1,0]
	v_fmac_f32_e32 v208, v214, v214
	v_fmac_f32_e32 v209, v212, v212
	v_cvt_pk_bf16_f32 v128, v132, v133
	v_cvt_pk_bf16_f32 v129, v134, v135
	v_cvt_pk_bf16_f32 v130, v202, v203
	v_cvt_pk_bf16_f32 v131, v200, v201
	v_pk_mul_f32 v[176:177], v[176:177], v[210:211]
	v_add_f32_e32 v208, v208, v209
	v_mul_f32_e32 v209, v219, v219
	v_mul_f32_e32 v210, v217, v217
	global_store_dwordx4 v[222:223], v[128:131], off offset:256
	v_fmac_f32_e32 v209, v218, v218
	v_fmac_f32_e32 v210, v216, v216
	v_mul_f32_e32 v128, v133, v133
	v_mul_f32_e32 v129, v135, v135
	v_fmac_f32_e32 v128, v132, v132
	v_fmac_f32_e32 v129, v134, v134
	v_add_f32_e32 v209, v209, v210
	v_add_f32_e32 v128, v128, v129
	v_mul_f32_e32 v129, v203, v203
	v_mul_f32_e32 v130, v201, v201
	v_add_f32_e32 v208, v208, v209
	v_fmac_f32_e32 v129, v202, v202
	v_fmac_f32_e32 v130, v200, v200
	v_add_f32_e32 v128, v208, v128
	v_add_f32_e32 v129, v129, v130
	v_add_f32_e32 v204, v129, v128
	v_pk_mul_f32 v[128:129], v[174:175], v[134:135]
	v_pk_mul_f32 v[134:135], v[178:179], v[200:201]
	v_mov_b32_e32 v244, v204
	v_mov_b32_e32 v245, v204
	s_nop 1
	v_permlane16_swap_b32_e32 v244, v245
	v_cndmask_b32_e32 v198, v197, v198, vcc
	v_pk_mul_f32 v[130:131], v[176:177], v[132:133]
	v_lshlrev_b32_e32 v198, 2, v198
	v_cvt_pk_bf16_f32 v130, v130, v131
	v_cvt_pk_bf16_f32 v131, v128, v129
	s_waitcnt lgkmcnt(0)
	v_add_f32_e32 v128, v244, v245
	v_mov_b32_e32 v246, v128
	v_mov_b32_e32 v247, v128
	s_nop 1
	v_permlane32_swap_b32_e32 v246, v247
	s_lshl_b32 s0, s38, 2
	v_pk_mul_f32 v[132:133], v[170:171], v[202:203]
	v_or_b32_e32 v220, 0x100, v220
	s_ashr_i32 s1, s0, 31
	v_cvt_pk_bf16_f32 v132, v132, v133
	v_cvt_pk_bf16_f32 v133, v134, v135
	v_lshl_add_u64 v[134:135], s[40:41], 0, v[220:221]
	global_store_dwordx4 v[134:135], v[130:133], off
	s_and_saveexec_b64 s[38:39], s[4:5]
	s_cbranch_execz .LBB0_879
	v_lshlrev_b64 v[130:131], 6, v[182:183]
	v_lshl_add_u64 v[130:131], s[16:17], 0, v[130:131]
	v_lshl_add_u64 v[130:131], s[0:1], 2, v[130:131]
	s_lshl_b32 s40, s58, 2
	s_mov_b32 s41, s3
	v_lshl_add_u64 v[130:131], v[130:131], 0, s[40:41]
	s_waitcnt lgkmcnt(0)
	v_add_f32_e32 v128, v246, v247
	global_store_dword v[130:131], v128, off
.LBB0_879:
	s_or_b64 exec, exec, s[38:39]
	s_waitcnt lgkmcnt(0)
	v_lshlrev_b64 v[128:129], 10, v[184:185]
	s_waitcnt vmcnt(0)
	v_lshlrev_b32_e32 v130, 16, v140
	v_and_b32_e32 v131, 0xffff0000, v140
	v_lshlrev_b32_e32 v132, 16, v141
	v_and_b32_e32 v133, 0xffff0000, v141
	v_lshlrev_b32_e32 v134, 16, v142
	v_and_b32_e32 v135, 0xffff0000, v142
	v_lshlrev_b32_e32 v140, 16, v143
	v_and_b32_e32 v141, 0xffff0000, v143
	v_lshl_add_u64 v[142:143], v[128:129], 0, v[172:173]
	v_or_b32_e32 v128, 32, v182
	v_ashrrev_i32_e32 v129, 31, v128
	v_pk_fma_f32 v[124:125], v[124:125], v[68:69], v[130:131]
	v_pk_fma_f32 v[126:127], v[126:127], v[70:71], v[132:133]
	v_pk_fma_f32 v[120:121], v[120:121], v[76:77], v[134:135]
	v_pk_fma_f32 v[122:123], v[122:123], v[78:79], v[140:141]
	v_lshlrev_b64 v[200:201], 11, v[128:129]
	v_pk_add_f32 v[130:131], v[126:127], 0 op_sel_hi:[1,0]
	v_pk_add_f32 v[132:133], v[124:125], 0 op_sel_hi:[1,0]
	v_pk_add_f32 v[134:135], v[122:123], 0 op_sel_hi:[1,0]
	v_pk_add_f32 v[140:141], v[120:121], 0 op_sel_hi:[1,0]
	v_lshlrev_b64 v[142:143], 1, v[142:143]
	v_lshl_add_u64 v[200:201], v[180:181], 0, v[200:201]
	v_cvt_pk_bf16_f32 v120, v132, v133
	v_cvt_pk_bf16_f32 v121, v130, v131
	v_cvt_pk_bf16_f32 v122, v140, v141
	v_cvt_pk_bf16_f32 v123, v134, v135
	v_lshl_add_u64 v[202:203], s[30:31], 0, v[142:143]
	v_readlane_b32 s38, v243, 54
	global_load_dwordx4 v[124:127], v[200:201], off
	v_pk_mul_f32 v[204:205], v[164:165], v[134:135]
	global_store_dwordx4 v[202:203], v[120:123], off
	v_pk_mul_f32 v[206:207], v[166:167], v[140:141]
	v_readlane_b32 s39, v243, 55
	v_pk_mul_f32 v[122:123], v[160:161], v[130:131]
	v_pk_mul_f32 v[120:121], v[162:163], v[132:133]
	v_mul_f32_e32 v133, v133, v133
	v_cvt_pk_bf16_f32 v120, v120, v121
	v_cvt_pk_bf16_f32 v121, v122, v123
	v_cvt_pk_bf16_f32 v122, v206, v207
	v_cvt_pk_bf16_f32 v123, v204, v205
	v_lshl_add_u64 v[204:205], s[38:39], 0, v[142:143]
	global_store_dwordx4 v[204:205], v[120:123], off
	global_load_dwordx4 v[120:123], v[200:201], off offset:256
	v_mul_f32_e32 v131, v131, v131
	v_fmac_f32_e32 v133, v132, v132
	v_fmac_f32_e32 v131, v130, v130
	v_add_f32_e32 v130, v133, v131
	v_mul_f32_e32 v131, v141, v141
	v_mul_f32_e32 v132, v135, v135
	v_lshlrev_b32_e32 v200, 16, v136
	v_and_b32_e32 v201, 0xffff0000, v136
	v_lshlrev_b32_e32 v136, 16, v137
	v_and_b32_e32 v137, 0xffff0000, v137
	v_lshlrev_b32_e32 v204, 16, v138
	v_and_b32_e32 v205, 0xffff0000, v138
	v_lshlrev_b32_e32 v138, 16, v139
	v_and_b32_e32 v139, 0xffff0000, v139
	v_fmac_f32_e32 v131, v140, v140
	v_fmac_f32_e32 v132, v134, v134
	v_add_f32_e32 v131, v131, v132
	v_pk_fma_f32 v[116:117], v[116:117], v[88:89], v[200:201]
	v_pk_fma_f32 v[118:119], v[118:119], v[90:91], v[136:137]
	v_pk_fma_f32 v[112:113], v[112:113], v[92:93], v[204:205]
	v_pk_fma_f32 v[114:115], v[114:115], v[94:95], v[138:139]
	v_add_f32_e32 v134, v130, v131
	v_pk_add_f32 v[118:119], v[118:119], 0 op_sel_hi:[1,0]
	v_pk_add_f32 v[116:117], v[116:117], 0 op_sel_hi:[1,0]
	v_pk_add_f32 v[130:131], v[114:115], 0 op_sel_hi:[1,0]
	v_pk_add_f32 v[132:133], v[112:113], 0 op_sel_hi:[1,0]
	v_cvt_pk_bf16_f32 v112, v116, v117
	v_cvt_pk_bf16_f32 v113, v118, v119
	v_cvt_pk_bf16_f32 v114, v132, v133
	v_cvt_pk_bf16_f32 v115, v130, v131
	global_store_dwordx4 v[202:203], v[112:115], off offset:256
	v_or_b32_e32 v142, 0x100, v142
	s_nop 0
	v_mul_f32_e32 v112, v117, v117
	v_mul_f32_e32 v113, v119, v119
	v_fmac_f32_e32 v112, v116, v116
	v_fmac_f32_e32 v113, v118, v118
	v_add_f32_e32 v112, v112, v113
	v_mul_f32_e32 v113, v133, v133
	v_mul_f32_e32 v114, v131, v131
	v_fmac_f32_e32 v113, v132, v132
	v_fmac_f32_e32 v114, v130, v130
	v_add_f32_e32 v112, v134, v112
	v_add_f32_e32 v113, v113, v114
	v_add_f32_e32 v134, v113, v112
	v_pk_mul_f32 v[112:113], v[174:175], v[118:119]
	v_pk_mul_f32 v[118:119], v[178:179], v[130:131]
	v_mov_b32_e32 v244, v134
	v_mov_b32_e32 v245, v134
	s_nop 1
	v_permlane16_swap_b32_e32 v244, v245
	v_pk_mul_f32 v[114:115], v[176:177], v[116:117]
	v_pk_mul_f32 v[116:117], v[170:171], v[132:133]
	v_cvt_pk_bf16_f32 v114, v114, v115
	v_cvt_pk_bf16_f32 v115, v112, v113
	s_waitcnt lgkmcnt(0)
	v_add_f32_e32 v112, v244, v245
	v_mov_b32_e32 v246, v112
	v_mov_b32_e32 v247, v112
	s_nop 1
	v_permlane32_swap_b32_e32 v246, v247
	v_cvt_pk_bf16_f32 v116, v116, v117
	v_cvt_pk_bf16_f32 v117, v118, v119
	v_lshl_add_u64 v[118:119], s[38:39], 0, v[142:143]
	global_store_dwordx4 v[118:119], v[114:117], off
	s_and_saveexec_b64 s[38:39], s[4:5]
	s_cbranch_execz .LBB0_881
	v_lshlrev_b64 v[114:115], 6, v[184:185]
	v_lshl_add_u64 v[114:115], s[16:17], 0, v[114:115]
	v_lshl_add_u64 v[114:115], s[0:1], 2, v[114:115]
	s_lshl_b32 s40, s58, 2
	s_mov_b32 s41, s3
	v_lshl_add_u64 v[114:115], v[114:115], 0, s[40:41]
	s_waitcnt lgkmcnt(0)
	v_add_f32_e32 v112, v246, v247
	global_store_dword v[114:115], v112, off
.LBB0_881:
	s_or_b64 exec, exec, s[38:39]
	s_waitcnt lgkmcnt(0)
	v_lshlrev_b64 v[112:113], 10, v[128:129]
	s_waitcnt vmcnt(5)
	v_lshlrev_b32_e32 v114, 16, v124
	v_and_b32_e32 v115, 0xffff0000, v124
	v_lshlrev_b32_e32 v116, 16, v125
	v_and_b32_e32 v117, 0xffff0000, v125
	v_lshlrev_b32_e32 v118, 16, v126
	v_and_b32_e32 v119, 0xffff0000, v126
	v_lshlrev_b32_e32 v124, 16, v127
	v_and_b32_e32 v125, 0xffff0000, v127
	v_lshl_add_u64 v[126:127], v[112:113], 0, v[172:173]
	v_or_b32_e32 v112, 48, v182
	v_ashrrev_i32_e32 v113, 31, v112
	v_pk_fma_f32 v[108:109], v[108:109], v[68:69], v[114:115]
	v_pk_fma_f32 v[110:111], v[110:111], v[70:71], v[116:117]
	v_pk_fma_f32 v[104:105], v[104:105], v[76:77], v[118:119]
	v_pk_fma_f32 v[106:107], v[106:107], v[78:79], v[124:125]
	v_lshlrev_b64 v[130:131], 11, v[112:113]
	v_pk_add_f32 v[114:115], v[110:111], 0 op_sel_hi:[1,0]
	v_pk_add_f32 v[116:117], v[108:109], 0 op_sel_hi:[1,0]
	v_pk_add_f32 v[118:119], v[106:107], 0 op_sel_hi:[1,0]
	v_pk_add_f32 v[124:125], v[104:105], 0 op_sel_hi:[1,0]
	v_lshlrev_b64 v[126:127], 1, v[126:127]
	v_lshl_add_u64 v[130:131], v[180:181], 0, v[130:131]
	v_cvt_pk_bf16_f32 v104, v116, v117
	v_cvt_pk_bf16_f32 v105, v114, v115
	v_cvt_pk_bf16_f32 v106, v124, v125
	v_cvt_pk_bf16_f32 v107, v118, v119
	v_lshl_add_u64 v[132:133], s[30:31], 0, v[126:127]
	v_readlane_b32 s38, v243, 54
	global_load_dwordx4 v[108:111], v[130:131], off
	v_pk_mul_f32 v[134:135], v[164:165], v[118:119]
	global_store_dwordx4 v[132:133], v[104:107], off
	v_pk_mul_f32 v[136:137], v[166:167], v[124:125]
	v_readlane_b32 s39, v243, 55
	v_pk_mul_f32 v[106:107], v[160:161], v[114:115]
	v_pk_mul_f32 v[104:105], v[162:163], v[116:117]
	v_mul_f32_e32 v117, v117, v117
	v_cvt_pk_bf16_f32 v104, v104, v105
	v_cvt_pk_bf16_f32 v105, v106, v107
	v_cvt_pk_bf16_f32 v106, v136, v137
	v_cvt_pk_bf16_f32 v107, v134, v135
	v_lshl_add_u64 v[134:135], s[38:39], 0, v[126:127]
	global_store_dwordx4 v[134:135], v[104:107], off
	global_load_dwordx4 v[104:107], v[130:131], off offset:256
	v_mul_f32_e32 v115, v115, v115
	v_fmac_f32_e32 v117, v116, v116
	v_fmac_f32_e32 v115, v114, v114
	v_add_f32_e32 v114, v117, v115
	v_mul_f32_e32 v115, v125, v125
	v_mul_f32_e32 v116, v119, v119
	s_waitcnt vmcnt(6)
	v_lshlrev_b32_e32 v130, 16, v120
	v_and_b32_e32 v131, 0xffff0000, v120
	v_lshlrev_b32_e32 v120, 16, v121
	v_and_b32_e32 v121, 0xffff0000, v121
	v_lshlrev_b32_e32 v134, 16, v122
	v_and_b32_e32 v135, 0xffff0000, v122
	v_lshlrev_b32_e32 v122, 16, v123
	v_and_b32_e32 v123, 0xffff0000, v123
	v_fmac_f32_e32 v115, v124, v124
	v_fmac_f32_e32 v116, v118, v118
	v_add_f32_e32 v115, v115, v116
	v_pk_fma_f32 v[100:101], v[100:101], v[88:89], v[130:131]
	v_pk_fma_f32 v[102:103], v[102:103], v[90:91], v[120:121]
	v_pk_fma_f32 v[96:97], v[96:97], v[92:93], v[134:135]
	v_pk_fma_f32 v[98:99], v[98:99], v[94:95], v[122:123]
	v_add_f32_e32 v118, v114, v115
	v_pk_add_f32 v[102:103], v[102:103], 0 op_sel_hi:[1,0]
	v_pk_add_f32 v[100:101], v[100:101], 0 op_sel_hi:[1,0]
	v_pk_add_f32 v[114:115], v[98:99], 0 op_sel_hi:[1,0]
	v_pk_add_f32 v[116:117], v[96:97], 0 op_sel_hi:[1,0]
	v_cvt_pk_bf16_f32 v96, v100, v101
	v_cvt_pk_bf16_f32 v97, v102, v103
	v_cvt_pk_bf16_f32 v98, v116, v117
	v_cvt_pk_bf16_f32 v99, v114, v115
	global_store_dwordx4 v[132:133], v[96:99], off offset:256
	v_or_b32_e32 v126, 0x100, v126
	s_nop 0
	v_mul_f32_e32 v96, v101, v101
	v_mul_f32_e32 v97, v103, v103
	v_fmac_f32_e32 v96, v100, v100
	v_fmac_f32_e32 v97, v102, v102
	v_add_f32_e32 v96, v96, v97
	v_mul_f32_e32 v97, v117, v117
	v_mul_f32_e32 v98, v115, v115
	v_fmac_f32_e32 v97, v116, v116
	v_fmac_f32_e32 v98, v114, v114
	v_add_f32_e32 v96, v118, v96
	v_add_f32_e32 v97, v97, v98
	v_add_f32_e32 v118, v97, v96
	v_pk_mul_f32 v[96:97], v[174:175], v[102:103]
	v_pk_mul_f32 v[102:103], v[178:179], v[114:115]
	v_mov_b32_e32 v244, v118
	v_mov_b32_e32 v245, v118
	s_nop 1
	v_permlane16_swap_b32_e32 v244, v245
	v_pk_mul_f32 v[98:99], v[176:177], v[100:101]
	v_pk_mul_f32 v[100:101], v[170:171], v[116:117]
	v_cvt_pk_bf16_f32 v98, v98, v99
	v_cvt_pk_bf16_f32 v99, v96, v97
	s_waitcnt lgkmcnt(0)
	v_add_f32_e32 v96, v244, v245
	v_mov_b32_e32 v246, v96
	v_mov_b32_e32 v247, v96
	s_nop 1
	v_permlane32_swap_b32_e32 v246, v247
	v_cvt_pk_bf16_f32 v100, v100, v101
	v_cvt_pk_bf16_f32 v101, v102, v103
	v_lshl_add_u64 v[102:103], s[38:39], 0, v[126:127]
	global_store_dwordx4 v[102:103], v[98:101], off
	s_and_saveexec_b64 s[38:39], s[4:5]
	s_cbranch_execz .LBB0_883
	v_lshlrev_b64 v[98:99], 6, v[128:129]
	v_lshl_add_u64 v[98:99], s[16:17], 0, v[98:99]
	v_lshl_add_u64 v[98:99], s[0:1], 2, v[98:99]
	s_lshl_b32 s40, s58, 2
	s_mov_b32 s41, s3
	v_lshl_add_u64 v[98:99], v[98:99], 0, s[40:41]
	s_waitcnt lgkmcnt(0)
	v_add_f32_e32 v96, v246, v247
	global_store_dword v[98:99], v96, off
.LBB0_883:
	s_or_b64 exec, exec, s[38:39]
	s_waitcnt lgkmcnt(0)
	v_lshlrev_b64 v[96:97], 10, v[112:113]
	s_waitcnt vmcnt(5)
	v_lshlrev_b32_e32 v98, 16, v108
	v_and_b32_e32 v99, 0xffff0000, v108
	v_lshlrev_b32_e32 v100, 16, v109
	v_and_b32_e32 v101, 0xffff0000, v109
	v_lshlrev_b32_e32 v102, 16, v110
	v_and_b32_e32 v103, 0xffff0000, v110
	v_lshlrev_b32_e32 v108, 16, v111
	v_and_b32_e32 v109, 0xffff0000, v111
	v_lshl_add_u64 v[110:111], v[96:97], 0, v[172:173]
	v_add_u32_e32 v96, 0x80, v182
	v_ashrrev_i32_e32 v97, 31, v96
	v_pk_fma_f32 v[84:85], v[84:85], v[68:69], v[98:99]
	v_pk_fma_f32 v[86:87], v[86:87], v[70:71], v[100:101]
	v_pk_fma_f32 v[80:81], v[80:81], v[76:77], v[102:103]
	v_pk_fma_f32 v[82:83], v[82:83], v[78:79], v[108:109]
	v_lshlrev_b64 v[114:115], 11, v[96:97]
	v_pk_add_f32 v[98:99], v[86:87], 0 op_sel_hi:[1,0]
	v_pk_add_f32 v[100:101], v[84:85], 0 op_sel_hi:[1,0]
	v_pk_add_f32 v[102:103], v[82:83], 0 op_sel_hi:[1,0]
	v_pk_add_f32 v[108:109], v[80:81], 0 op_sel_hi:[1,0]
	v_lshlrev_b64 v[110:111], 1, v[110:111]
	v_lshl_add_u64 v[114:115], v[180:181], 0, v[114:115]
	v_cvt_pk_bf16_f32 v80, v100, v101
	v_cvt_pk_bf16_f32 v81, v98, v99
	v_cvt_pk_bf16_f32 v82, v108, v109
	v_cvt_pk_bf16_f32 v83, v102, v103
	v_lshl_add_u64 v[116:117], s[30:31], 0, v[110:111]
	v_readlane_b32 s38, v243, 54
	global_load_dwordx4 v[84:87], v[114:115], off
	v_pk_mul_f32 v[118:119], v[164:165], v[102:103]
	global_store_dwordx4 v[116:117], v[80:83], off
	v_pk_mul_f32 v[120:121], v[166:167], v[108:109]
	v_readlane_b32 s39, v243, 55
	v_pk_mul_f32 v[82:83], v[160:161], v[98:99]
	v_pk_mul_f32 v[80:81], v[162:163], v[100:101]
	v_mul_f32_e32 v101, v101, v101
	v_cvt_pk_bf16_f32 v80, v80, v81
	v_cvt_pk_bf16_f32 v81, v82, v83
	v_cvt_pk_bf16_f32 v82, v120, v121
	v_cvt_pk_bf16_f32 v83, v118, v119
	v_lshl_add_u64 v[118:119], s[38:39], 0, v[110:111]
	global_store_dwordx4 v[118:119], v[80:83], off
	global_load_dwordx4 v[80:83], v[114:115], off offset:256
	v_mul_f32_e32 v99, v99, v99
	v_fmac_f32_e32 v101, v100, v100
	v_fmac_f32_e32 v99, v98, v98
	v_add_f32_e32 v98, v101, v99
	v_mul_f32_e32 v99, v109, v109
	v_mul_f32_e32 v100, v103, v103
	s_waitcnt vmcnt(6)
	v_lshlrev_b32_e32 v114, 16, v104
	v_and_b32_e32 v115, 0xffff0000, v104
	v_lshlrev_b32_e32 v104, 16, v105
	v_and_b32_e32 v105, 0xffff0000, v105
	v_lshlrev_b32_e32 v118, 16, v106
	v_and_b32_e32 v119, 0xffff0000, v106
	v_lshlrev_b32_e32 v106, 16, v107
	v_and_b32_e32 v107, 0xffff0000, v107
	v_fmac_f32_e32 v99, v108, v108
	v_fmac_f32_e32 v100, v102, v102
	v_add_f32_e32 v99, v99, v100
	v_pk_fma_f32 v[72:73], v[72:73], v[88:89], v[114:115]
	v_pk_fma_f32 v[74:75], v[74:75], v[90:91], v[104:105]
	v_pk_fma_f32 v[64:65], v[64:65], v[92:93], v[118:119]
	v_pk_fma_f32 v[66:67], v[66:67], v[94:95], v[106:107]
	v_add_f32_e32 v102, v98, v99
	v_pk_add_f32 v[74:75], v[74:75], 0 op_sel_hi:[1,0]
	v_pk_add_f32 v[72:73], v[72:73], 0 op_sel_hi:[1,0]
	v_pk_add_f32 v[98:99], v[66:67], 0 op_sel_hi:[1,0]
	v_pk_add_f32 v[100:101], v[64:65], 0 op_sel_hi:[1,0]
	v_cvt_pk_bf16_f32 v64, v72, v73
	v_cvt_pk_bf16_f32 v65, v74, v75
	v_cvt_pk_bf16_f32 v66, v100, v101
	v_cvt_pk_bf16_f32 v67, v98, v99
	global_store_dwordx4 v[116:117], v[64:67], off offset:256
	v_or_b32_e32 v110, 0x100, v110
	s_nop 0
	v_mul_f32_e32 v64, v73, v73
	v_mul_f32_e32 v65, v75, v75
	v_fmac_f32_e32 v64, v72, v72
	v_fmac_f32_e32 v65, v74, v74
	v_add_f32_e32 v64, v64, v65
	v_mul_f32_e32 v65, v101, v101
	v_mul_f32_e32 v66, v99, v99
	v_fmac_f32_e32 v65, v100, v100
	v_fmac_f32_e32 v66, v98, v98
	v_add_f32_e32 v64, v102, v64
	v_add_f32_e32 v65, v65, v66
	v_add_f32_e32 v102, v65, v64
	v_mov_b32_e32 v244, v102
	v_mov_b32_e32 v245, v102
	s_nop 1
	v_permlane16_swap_b32_e32 v244, v245
	v_pk_mul_f32 v[64:65], v[174:175], v[74:75]
	v_pk_mul_f32 v[66:67], v[176:177], v[72:73]
	v_cvt_pk_bf16_f32 v73, v64, v65
	v_pk_mul_f32 v[98:99], v[178:179], v[98:99]
	s_waitcnt lgkmcnt(0)
	v_add_f32_e32 v64, v244, v245
	v_mov_b32_e32 v246, v64
	v_mov_b32_e32 v247, v64
	s_nop 1
	v_permlane32_swap_b32_e32 v246, v247
	v_pk_mul_f32 v[74:75], v[170:171], v[100:101]
	v_cvt_pk_bf16_f32 v72, v66, v67
	v_cvt_pk_bf16_f32 v74, v74, v75
	v_cvt_pk_bf16_f32 v75, v98, v99
	v_lshl_add_u64 v[66:67], s[38:39], 0, v[110:111]
	global_store_dwordx4 v[66:67], v[72:75], off
	s_and_saveexec_b64 s[38:39], s[4:5]
	v_readlane_b32 s69, v242, 0
	s_cbranch_execz .LBB0_885
	v_lshlrev_b64 v[66:67], 6, v[112:113]
	v_lshl_add_u64 v[66:67], s[16:17], 0, v[66:67]
	v_lshl_add_u64 v[66:67], s[0:1], 2, v[66:67]
	s_lshl_b32 s40, s58, 2
	s_mov_b32 s41, s3
	v_lshl_add_u64 v[66:67], v[66:67], 0, s[40:41]
	s_waitcnt lgkmcnt(0)
	v_add_f32_e32 v64, v246, v247
	global_store_dword v[66:67], v64, off
.LBB0_885:
	s_or_b64 exec, exec, s[38:39]
	s_waitcnt lgkmcnt(0)
	v_lshlrev_b64 v[64:65], 10, v[96:97]
	s_waitcnt vmcnt(5)
	v_lshlrev_b32_e32 v66, 16, v84
	v_and_b32_e32 v67, 0xffff0000, v84
	v_lshlrev_b32_e32 v72, 16, v85
	v_and_b32_e32 v73, 0xffff0000, v85
	v_lshlrev_b32_e32 v74, 16, v86
	v_and_b32_e32 v75, 0xffff0000, v86
	v_lshlrev_b32_e32 v84, 16, v87
	v_and_b32_e32 v85, 0xffff0000, v87
	v_lshl_add_u64 v[86:87], v[64:65], 0, v[172:173]
	v_or_b32_e32 v64, 16, v96
	v_ashrrev_i32_e32 v65, 31, v64
	v_pk_fma_f32 v[60:61], v[60:61], v[68:69], v[66:67]
	v_pk_fma_f32 v[62:63], v[62:63], v[70:71], v[72:73]
	v_pk_fma_f32 v[56:57], v[56:57], v[76:77], v[74:75]
	v_pk_fma_f32 v[58:59], v[58:59], v[78:79], v[84:85]
	v_lshlrev_b64 v[98:99], 11, v[64:65]
	v_pk_add_f32 v[66:67], v[62:63], 0 op_sel_hi:[1,0]
	v_pk_add_f32 v[72:73], v[60:61], 0 op_sel_hi:[1,0]
	v_pk_add_f32 v[74:75], v[58:59], 0 op_sel_hi:[1,0]
	v_pk_add_f32 v[84:85], v[56:57], 0 op_sel_hi:[1,0]
	v_lshlrev_b64 v[86:87], 1, v[86:87]
	v_lshl_add_u64 v[98:99], v[180:181], 0, v[98:99]
	v_cvt_pk_bf16_f32 v56, v72, v73
	v_cvt_pk_bf16_f32 v57, v66, v67
	v_cvt_pk_bf16_f32 v58, v84, v85
	v_cvt_pk_bf16_f32 v59, v74, v75
	v_lshl_add_u64 v[100:101], s[30:31], 0, v[86:87]
	v_readlane_b32 s38, v243, 54
	global_load_dwordx4 v[60:63], v[98:99], off
	v_pk_mul_f32 v[102:103], v[164:165], v[74:75]
	global_store_dwordx4 v[100:101], v[56:59], off
	v_pk_mul_f32 v[104:105], v[166:167], v[84:85]
	v_readlane_b32 s39, v243, 55
	v_pk_mul_f32 v[58:59], v[160:161], v[66:67]
	v_pk_mul_f32 v[56:57], v[162:163], v[72:73]
	v_mul_f32_e32 v73, v73, v73
	v_cvt_pk_bf16_f32 v56, v56, v57
	v_cvt_pk_bf16_f32 v57, v58, v59
	v_cvt_pk_bf16_f32 v58, v104, v105
	v_cvt_pk_bf16_f32 v59, v102, v103
	v_lshl_add_u64 v[102:103], s[38:39], 0, v[86:87]
	global_store_dwordx4 v[102:103], v[56:59], off
	global_load_dwordx4 v[56:59], v[98:99], off offset:256
	v_mul_f32_e32 v67, v67, v67
	v_fmac_f32_e32 v73, v72, v72
	v_fmac_f32_e32 v67, v66, v66
	v_add_f32_e32 v66, v73, v67
	v_mul_f32_e32 v67, v85, v85
	v_mul_f32_e32 v72, v75, v75
	s_waitcnt vmcnt(6)
	v_lshlrev_b32_e32 v98, 16, v80
	v_and_b32_e32 v99, 0xffff0000, v80
	v_lshlrev_b32_e32 v80, 16, v81
	v_and_b32_e32 v81, 0xffff0000, v81
	v_lshlrev_b32_e32 v102, 16, v82
	v_and_b32_e32 v103, 0xffff0000, v82
	v_lshlrev_b32_e32 v82, 16, v83
	v_and_b32_e32 v83, 0xffff0000, v83
	v_fmac_f32_e32 v67, v84, v84
	v_fmac_f32_e32 v72, v74, v74
	v_add_f32_e32 v67, v67, v72
	v_pk_fma_f32 v[52:53], v[52:53], v[88:89], v[98:99]
	v_pk_fma_f32 v[54:55], v[54:55], v[90:91], v[80:81]
	v_pk_fma_f32 v[48:49], v[48:49], v[92:93], v[102:103]
	v_pk_fma_f32 v[50:51], v[50:51], v[94:95], v[82:83]
	v_add_f32_e32 v74, v66, v67
	v_pk_add_f32 v[54:55], v[54:55], 0 op_sel_hi:[1,0]
	v_pk_add_f32 v[52:53], v[52:53], 0 op_sel_hi:[1,0]
	v_pk_add_f32 v[66:67], v[50:51], 0 op_sel_hi:[1,0]
	v_pk_add_f32 v[72:73], v[48:49], 0 op_sel_hi:[1,0]
	v_cvt_pk_bf16_f32 v48, v52, v53
	v_cvt_pk_bf16_f32 v49, v54, v55
	v_cvt_pk_bf16_f32 v50, v72, v73
	v_cvt_pk_bf16_f32 v51, v66, v67
	global_store_dwordx4 v[100:101], v[48:51], off offset:256
	v_or_b32_e32 v86, 0x100, v86
	s_nop 0
	v_mul_f32_e32 v48, v53, v53
	v_mul_f32_e32 v49, v55, v55
	v_fmac_f32_e32 v48, v52, v52
	v_fmac_f32_e32 v49, v54, v54
	v_add_f32_e32 v48, v48, v49
	v_mul_f32_e32 v49, v73, v73
	v_mul_f32_e32 v50, v67, v67
	v_fmac_f32_e32 v49, v72, v72
	v_fmac_f32_e32 v50, v66, v66
	v_add_f32_e32 v48, v74, v48
	v_add_f32_e32 v49, v49, v50
	v_add_f32_e32 v74, v49, v48
	v_pk_mul_f32 v[48:49], v[174:175], v[54:55]
	v_pk_mul_f32 v[54:55], v[178:179], v[66:67]
	v_mov_b32_e32 v244, v74
	v_mov_b32_e32 v245, v74
	s_nop 1
	v_permlane16_swap_b32_e32 v244, v245
	v_pk_mul_f32 v[50:51], v[176:177], v[52:53]
	v_pk_mul_f32 v[52:53], v[170:171], v[72:73]
	v_cvt_pk_bf16_f32 v50, v50, v51
	v_cvt_pk_bf16_f32 v51, v48, v49
	s_waitcnt lgkmcnt(0)
	v_add_f32_e32 v48, v244, v245
	v_mov_b32_e32 v246, v48
	v_mov_b32_e32 v247, v48
	s_nop 1
	v_permlane32_swap_b32_e32 v246, v247
	v_cvt_pk_bf16_f32 v52, v52, v53
	v_cvt_pk_bf16_f32 v53, v54, v55
	v_lshl_add_u64 v[54:55], s[38:39], 0, v[86:87]
	global_store_dwordx4 v[54:55], v[50:53], off
	s_and_saveexec_b64 s[38:39], s[4:5]
	s_cbranch_execz .LBB0_887
	v_lshlrev_b64 v[50:51], 6, v[96:97]
	v_lshl_add_u64 v[50:51], s[16:17], 0, v[50:51]
	v_lshl_add_u64 v[50:51], s[0:1], 2, v[50:51]
	s_lshl_b32 s40, s58, 2
	s_mov_b32 s41, s3
	v_lshl_add_u64 v[50:51], v[50:51], 0, s[40:41]
	s_waitcnt lgkmcnt(0)
	v_add_f32_e32 v48, v246, v247
	global_store_dword v[50:51], v48, off
.LBB0_887:
	s_or_b64 exec, exec, s[38:39]
	s_waitcnt lgkmcnt(0)
	v_lshlrev_b64 v[48:49], 10, v[64:65]
	s_waitcnt vmcnt(5)
	v_lshlrev_b32_e32 v50, 16, v60
	v_and_b32_e32 v51, 0xffff0000, v60
	v_lshlrev_b32_e32 v52, 16, v61
	v_and_b32_e32 v53, 0xffff0000, v61
	v_lshlrev_b32_e32 v54, 16, v62
	v_and_b32_e32 v55, 0xffff0000, v62
	v_lshlrev_b32_e32 v60, 16, v63
	v_and_b32_e32 v61, 0xffff0000, v63
	v_lshl_add_u64 v[62:63], v[48:49], 0, v[172:173]
	v_or_b32_e32 v48, 32, v96
	v_ashrrev_i32_e32 v49, 31, v48
	v_pk_fma_f32 v[44:45], v[44:45], v[68:69], v[50:51]
	v_pk_fma_f32 v[46:47], v[46:47], v[70:71], v[52:53]
	v_pk_fma_f32 v[40:41], v[40:41], v[76:77], v[54:55]
	v_pk_fma_f32 v[42:43], v[42:43], v[78:79], v[60:61]
	v_lshlrev_b64 v[66:67], 11, v[48:49]
	v_pk_add_f32 v[50:51], v[46:47], 0 op_sel_hi:[1,0]
	v_pk_add_f32 v[52:53], v[44:45], 0 op_sel_hi:[1,0]
	v_pk_add_f32 v[54:55], v[42:43], 0 op_sel_hi:[1,0]
	v_pk_add_f32 v[60:61], v[40:41], 0 op_sel_hi:[1,0]
	v_lshlrev_b64 v[62:63], 1, v[62:63]
	v_lshl_add_u64 v[66:67], v[180:181], 0, v[66:67]
	v_cvt_pk_bf16_f32 v40, v52, v53
	v_cvt_pk_bf16_f32 v41, v50, v51
	v_cvt_pk_bf16_f32 v42, v60, v61
	v_cvt_pk_bf16_f32 v43, v54, v55
	v_lshl_add_u64 v[72:73], s[30:31], 0, v[62:63]
	v_readlane_b32 s38, v243, 54
	global_load_dwordx4 v[44:47], v[66:67], off
	v_pk_mul_f32 v[74:75], v[164:165], v[54:55]
	global_store_dwordx4 v[72:73], v[40:43], off
	v_pk_mul_f32 v[80:81], v[166:167], v[60:61]
	v_readlane_b32 s39, v243, 55
	v_pk_mul_f32 v[42:43], v[160:161], v[50:51]
	v_pk_mul_f32 v[40:41], v[162:163], v[52:53]
	v_mul_f32_e32 v53, v53, v53
	v_cvt_pk_bf16_f32 v40, v40, v41
	v_cvt_pk_bf16_f32 v41, v42, v43
	v_cvt_pk_bf16_f32 v42, v80, v81
	v_cvt_pk_bf16_f32 v43, v74, v75
	v_lshl_add_u64 v[74:75], s[38:39], 0, v[62:63]
	global_store_dwordx4 v[74:75], v[40:43], off
	global_load_dwordx4 v[40:43], v[66:67], off offset:256
	v_mul_f32_e32 v51, v51, v51
	v_fmac_f32_e32 v53, v52, v52
	v_fmac_f32_e32 v51, v50, v50
	v_add_f32_e32 v50, v53, v51
	v_mul_f32_e32 v51, v61, v61
	v_mul_f32_e32 v52, v55, v55
	s_waitcnt vmcnt(6)
	v_lshlrev_b32_e32 v66, 16, v56
	v_and_b32_e32 v67, 0xffff0000, v56
	v_lshlrev_b32_e32 v56, 16, v57
	v_and_b32_e32 v57, 0xffff0000, v57
	v_lshlrev_b32_e32 v74, 16, v58
	v_and_b32_e32 v75, 0xffff0000, v58
	v_lshlrev_b32_e32 v58, 16, v59
	v_and_b32_e32 v59, 0xffff0000, v59
	v_fmac_f32_e32 v51, v60, v60
	v_fmac_f32_e32 v52, v54, v54
	v_add_f32_e32 v51, v51, v52
	v_pk_fma_f32 v[36:37], v[36:37], v[88:89], v[66:67]
	v_pk_fma_f32 v[38:39], v[38:39], v[90:91], v[56:57]
	v_pk_fma_f32 v[32:33], v[32:33], v[92:93], v[74:75]
	v_pk_fma_f32 v[34:35], v[34:35], v[94:95], v[58:59]
	v_add_f32_e32 v54, v50, v51
	v_pk_add_f32 v[38:39], v[38:39], 0 op_sel_hi:[1,0]
	v_pk_add_f32 v[36:37], v[36:37], 0 op_sel_hi:[1,0]
	v_pk_add_f32 v[50:51], v[34:35], 0 op_sel_hi:[1,0]
	v_pk_add_f32 v[52:53], v[32:33], 0 op_sel_hi:[1,0]
	v_cvt_pk_bf16_f32 v32, v36, v37
	v_cvt_pk_bf16_f32 v33, v38, v39
	v_cvt_pk_bf16_f32 v34, v52, v53
	v_cvt_pk_bf16_f32 v35, v50, v51
	global_store_dwordx4 v[72:73], v[32:35], off offset:256
	v_or_b32_e32 v62, 0x100, v62
	s_nop 0
	v_mul_f32_e32 v32, v37, v37
	v_mul_f32_e32 v33, v39, v39
	v_fmac_f32_e32 v32, v36, v36
	v_fmac_f32_e32 v33, v38, v38
	v_add_f32_e32 v32, v32, v33
	v_mul_f32_e32 v33, v53, v53
	v_mul_f32_e32 v34, v51, v51
	v_fmac_f32_e32 v33, v52, v52
	v_fmac_f32_e32 v34, v50, v50
	v_add_f32_e32 v32, v54, v32
	v_add_f32_e32 v33, v33, v34
	v_add_f32_e32 v54, v33, v32
	v_pk_mul_f32 v[32:33], v[174:175], v[38:39]
	v_pk_mul_f32 v[38:39], v[178:179], v[50:51]
	v_mov_b32_e32 v244, v54
	v_mov_b32_e32 v245, v54
	s_nop 1
	v_permlane16_swap_b32_e32 v244, v245
	v_pk_mul_f32 v[34:35], v[176:177], v[36:37]
	v_pk_mul_f32 v[36:37], v[170:171], v[52:53]
	v_cvt_pk_bf16_f32 v34, v34, v35
	v_cvt_pk_bf16_f32 v35, v32, v33
	s_waitcnt lgkmcnt(0)
	v_add_f32_e32 v32, v244, v245
	v_mov_b32_e32 v246, v32
	v_mov_b32_e32 v247, v32
	s_nop 1
	v_permlane32_swap_b32_e32 v246, v247
	v_cvt_pk_bf16_f32 v36, v36, v37
	v_cvt_pk_bf16_f32 v37, v38, v39
	v_lshl_add_u64 v[38:39], s[38:39], 0, v[62:63]
	global_store_dwordx4 v[38:39], v[34:37], off
	s_and_saveexec_b64 s[38:39], s[4:5]
	s_cbranch_execz .LBB0_889
	v_lshlrev_b64 v[34:35], 6, v[64:65]
	v_lshl_add_u64 v[34:35], s[16:17], 0, v[34:35]
	v_lshl_add_u64 v[34:35], s[0:1], 2, v[34:35]
	s_lshl_b32 s40, s58, 2
	s_mov_b32 s41, s3
	v_lshl_add_u64 v[34:35], v[34:35], 0, s[40:41]
	s_waitcnt lgkmcnt(0)
	v_add_f32_e32 v32, v246, v247
	global_store_dword v[34:35], v32, off
.LBB0_889:
	s_or_b64 exec, exec, s[38:39]
	s_waitcnt lgkmcnt(0)
	v_lshlrev_b64 v[32:33], 10, v[48:49]
	s_waitcnt vmcnt(5)
	v_lshlrev_b32_e32 v34, 16, v44
	v_and_b32_e32 v35, 0xffff0000, v44
	v_lshlrev_b32_e32 v36, 16, v45
	v_and_b32_e32 v37, 0xffff0000, v45
	v_lshlrev_b32_e32 v38, 16, v46
	v_and_b32_e32 v39, 0xffff0000, v46
	v_lshlrev_b32_e32 v44, 16, v47
	v_and_b32_e32 v45, 0xffff0000, v47
	v_lshl_add_u64 v[46:47], v[32:33], 0, v[172:173]
	v_or_b32_e32 v32, 48, v96
	v_ashrrev_i32_e32 v33, 31, v32
	v_pk_fma_f32 v[28:29], v[28:29], v[68:69], v[34:35]
	v_pk_fma_f32 v[30:31], v[30:31], v[70:71], v[36:37]
	v_pk_fma_f32 v[24:25], v[24:25], v[76:77], v[38:39]
	v_pk_fma_f32 v[26:27], v[26:27], v[78:79], v[44:45]
	v_lshlrev_b64 v[50:51], 11, v[32:33]
	v_pk_add_f32 v[34:35], v[30:31], 0 op_sel_hi:[1,0]
	v_pk_add_f32 v[36:37], v[28:29], 0 op_sel_hi:[1,0]
	v_pk_add_f32 v[38:39], v[26:27], 0 op_sel_hi:[1,0]
	v_pk_add_f32 v[44:45], v[24:25], 0 op_sel_hi:[1,0]
	v_lshlrev_b64 v[46:47], 1, v[46:47]
	v_lshl_add_u64 v[50:51], v[180:181], 0, v[50:51]
	v_cvt_pk_bf16_f32 v28, v36, v37
	v_cvt_pk_bf16_f32 v29, v34, v35
	v_cvt_pk_bf16_f32 v30, v44, v45
	v_cvt_pk_bf16_f32 v31, v38, v39
	v_lshl_add_u64 v[52:53], s[30:31], 0, v[46:47]
	v_readlane_b32 s38, v243, 54
	global_load_dwordx4 v[24:27], v[50:51], off
	v_pk_mul_f32 v[54:55], v[164:165], v[38:39]
	global_store_dwordx4 v[52:53], v[28:31], off
	v_pk_mul_f32 v[56:57], v[166:167], v[44:45]
	v_readlane_b32 s39, v243, 55
	v_pk_mul_f32 v[30:31], v[160:161], v[34:35]
	v_pk_mul_f32 v[28:29], v[162:163], v[36:37]
	v_mul_f32_e32 v37, v37, v37
	v_cvt_pk_bf16_f32 v28, v28, v29
	v_cvt_pk_bf16_f32 v29, v30, v31
	v_cvt_pk_bf16_f32 v30, v56, v57
	v_cvt_pk_bf16_f32 v31, v54, v55
	v_lshl_add_u64 v[54:55], s[38:39], 0, v[46:47]
	global_store_dwordx4 v[54:55], v[28:31], off
	global_load_dwordx4 v[28:31], v[50:51], off offset:256
	v_mul_f32_e32 v35, v35, v35
	v_fmac_f32_e32 v37, v36, v36
	v_fmac_f32_e32 v35, v34, v34
	v_add_f32_e32 v34, v37, v35
	v_mul_f32_e32 v35, v45, v45
	v_mul_f32_e32 v36, v39, v39
	s_waitcnt vmcnt(6)
	v_lshlrev_b32_e32 v50, 16, v40
	v_and_b32_e32 v51, 0xffff0000, v40
	v_lshlrev_b32_e32 v40, 16, v41
	v_and_b32_e32 v41, 0xffff0000, v41
	v_lshlrev_b32_e32 v54, 16, v42
	v_and_b32_e32 v55, 0xffff0000, v42
	v_lshlrev_b32_e32 v42, 16, v43
	v_and_b32_e32 v43, 0xffff0000, v43
	v_fmac_f32_e32 v35, v44, v44
	v_fmac_f32_e32 v36, v38, v38
	v_add_f32_e32 v35, v35, v36
	v_pk_fma_f32 v[20:21], v[20:21], v[88:89], v[50:51]
	v_pk_fma_f32 v[22:23], v[22:23], v[90:91], v[40:41]
	v_pk_fma_f32 v[16:17], v[16:17], v[92:93], v[54:55]
	v_pk_fma_f32 v[18:19], v[18:19], v[94:95], v[42:43]
	v_add_f32_e32 v38, v34, v35
	v_pk_add_f32 v[22:23], v[22:23], 0 op_sel_hi:[1,0]
	v_pk_add_f32 v[20:21], v[20:21], 0 op_sel_hi:[1,0]
	v_pk_add_f32 v[34:35], v[18:19], 0 op_sel_hi:[1,0]
	v_pk_add_f32 v[36:37], v[16:17], 0 op_sel_hi:[1,0]
	v_cvt_pk_bf16_f32 v16, v20, v21
	v_cvt_pk_bf16_f32 v17, v22, v23
	v_cvt_pk_bf16_f32 v18, v36, v37
	v_cvt_pk_bf16_f32 v19, v34, v35
	global_store_dwordx4 v[52:53], v[16:19], off offset:256
	v_or_b32_e32 v46, 0x100, v46
	s_nop 0
	v_mul_f32_e32 v16, v21, v21
	v_mul_f32_e32 v17, v23, v23
	v_fmac_f32_e32 v16, v20, v20
	v_fmac_f32_e32 v17, v22, v22
	v_add_f32_e32 v16, v16, v17
	v_mul_f32_e32 v17, v37, v37
	v_mul_f32_e32 v18, v35, v35
	v_fmac_f32_e32 v17, v36, v36
	v_fmac_f32_e32 v18, v34, v34
	v_add_f32_e32 v16, v38, v16
	v_add_f32_e32 v17, v17, v18
	v_add_f32_e32 v38, v17, v16
	v_pk_mul_f32 v[16:17], v[174:175], v[22:23]
	v_pk_mul_f32 v[22:23], v[178:179], v[34:35]
	v_mov_b32_e32 v244, v38
	v_mov_b32_e32 v245, v38
	s_nop 1
	v_permlane16_swap_b32_e32 v244, v245
	v_pk_mul_f32 v[18:19], v[176:177], v[20:21]
	v_pk_mul_f32 v[20:21], v[170:171], v[36:37]
	v_cvt_pk_bf16_f32 v18, v18, v19
	v_cvt_pk_bf16_f32 v19, v16, v17
	s_waitcnt lgkmcnt(0)
	v_add_f32_e32 v16, v244, v245
	v_mov_b32_e32 v246, v16
	v_mov_b32_e32 v247, v16
	s_nop 1
	v_permlane32_swap_b32_e32 v246, v247
	v_cvt_pk_bf16_f32 v20, v20, v21
	v_cvt_pk_bf16_f32 v21, v22, v23
	v_lshl_add_u64 v[22:23], s[38:39], 0, v[46:47]
	global_store_dwordx4 v[22:23], v[18:21], off
	s_and_saveexec_b64 s[38:39], s[4:5]
	s_cbranch_execz .LBB0_891
	v_lshlrev_b64 v[18:19], 6, v[48:49]
	v_lshl_add_u64 v[18:19], s[16:17], 0, v[18:19]
	v_lshl_add_u64 v[18:19], s[0:1], 2, v[18:19]
	s_lshl_b32 s40, s58, 2
	s_mov_b32 s41, s3
	v_lshl_add_u64 v[18:19], v[18:19], 0, s[40:41]
	s_waitcnt lgkmcnt(0)
	v_add_f32_e32 v16, v246, v247
	global_store_dword v[18:19], v16, off
.LBB0_891:
	s_or_b64 exec, exec, s[38:39]
	s_waitcnt vmcnt(5)
	v_lshlrev_b32_e32 v16, 16, v24
	s_waitcnt lgkmcnt(0)
	v_and_b32_e32 v17, 0xffff0000, v24
	v_lshlrev_b32_e32 v18, 16, v25
	v_and_b32_e32 v19, 0xffff0000, v25
	v_lshlrev_b32_e32 v20, 16, v26
	v_and_b32_e32 v21, 0xffff0000, v26
	v_lshlrev_b32_e32 v22, 16, v27
	v_and_b32_e32 v23, 0xffff0000, v27
	v_lshlrev_b64 v[34:35], 10, v[32:33]
	v_lshl_add_u64 v[34:35], v[34:35], 0, v[172:173]
	v_pk_fma_f32 v[12:13], v[12:13], v[76:77], v[20:21]
	v_pk_fma_f32 v[14:15], v[14:15], v[78:79], v[22:23]
	v_pk_fma_f32 v[8:9], v[8:9], v[68:69], v[16:17]
	v_pk_fma_f32 v[10:11], v[10:11], v[70:71], v[18:19]
	v_pk_add_f32 v[14:15], v[14:15], 0 op_sel_hi:[1,0]
	v_pk_add_f32 v[12:13], v[12:13], 0 op_sel_hi:[1,0]
	v_pk_add_f32 v[16:17], v[10:11], 0 op_sel_hi:[1,0]
	v_pk_add_f32 v[18:19], v[8:9], 0 op_sel_hi:[1,0]
	v_lshlrev_b64 v[20:21], 1, v[34:35]
	v_cvt_pk_bf16_f32 v8, v18, v19
	v_cvt_pk_bf16_f32 v9, v16, v17
	v_cvt_pk_bf16_f32 v10, v12, v13
	v_cvt_pk_bf16_f32 v11, v14, v15
	v_lshl_add_u64 v[22:23], s[30:31], 0, v[20:21]
	v_readlane_b32 s30, v243, 54
	s_waitcnt vmcnt(2)
	v_lshlrev_b32_e32 v24, 16, v28
	v_and_b32_e32 v25, 0xffff0000, v28
	global_store_dwordx4 v[22:23], v[8:11], off
	v_pk_mul_f32 v[34:35], v[164:165], v[14:15]
	v_pk_mul_f32 v[36:37], v[166:167], v[12:13]
	v_pk_mul_f32 v[10:11], v[160:161], v[16:17]
	v_pk_mul_f32 v[8:9], v[162:163], v[18:19]
	v_readlane_b32 s31, v243, 55
	v_cvt_pk_bf16_f32 v8, v8, v9
	v_cvt_pk_bf16_f32 v9, v10, v11
	v_cvt_pk_bf16_f32 v10, v36, v37
	v_cvt_pk_bf16_f32 v11, v34, v35
	v_lshl_add_u64 v[34:35], s[30:31], 0, v[20:21]
	v_pk_fma_f32 v[0:1], v[0:1], v[88:89], v[24:25]
	v_lshlrev_b32_e32 v26, 16, v29
	v_and_b32_e32 v27, 0xffff0000, v29
	global_store_dwordx4 v[34:35], v[8:11], off
	v_pk_fma_f32 v[2:3], v[2:3], v[90:91], v[26:27]
	v_lshlrev_b32_e32 v28, 16, v30
	v_pk_add_f32 v[8:9], v[0:1], 0 op_sel_hi:[1,0]
	v_mul_f32_e32 v0, v19, v19
	v_mul_f32_e32 v1, v17, v17
	v_fmac_f32_e32 v0, v18, v18
	v_fmac_f32_e32 v1, v16, v16
	v_and_b32_e32 v29, 0xffff0000, v30
	v_lshlrev_b32_e32 v30, 16, v31
	v_and_b32_e32 v31, 0xffff0000, v31
	v_pk_add_f32 v[10:11], v[2:3], 0 op_sel_hi:[1,0]
	v_add_f32_e32 v0, v0, v1
	v_mul_f32_e32 v1, v13, v13
	v_mul_f32_e32 v2, v15, v15
	v_pk_fma_f32 v[6:7], v[6:7], v[94:95], v[30:31]
	v_pk_fma_f32 v[4:5], v[4:5], v[92:93], v[28:29]
	v_fmac_f32_e32 v1, v12, v12
	v_fmac_f32_e32 v2, v14, v14
	v_pk_add_f32 v[4:5], v[4:5], 0 op_sel_hi:[1,0]
	v_pk_add_f32 v[6:7], v[6:7], 0 op_sel_hi:[1,0]
	v_add_f32_e32 v1, v1, v2
	v_add_f32_e32 v12, v1, v0
	v_cvt_pk_bf16_f32 v0, v8, v9
	v_cvt_pk_bf16_f32 v1, v10, v11
	v_cvt_pk_bf16_f32 v2, v4, v5
	v_cvt_pk_bf16_f32 v3, v6, v7
	global_store_dwordx4 v[22:23], v[0:3], off offset:256
	v_or_b32_e32 v20, 0x100, v20
	s_nop 0
	v_mul_f32_e32 v0, v9, v9
	v_mul_f32_e32 v1, v11, v11
	v_fmac_f32_e32 v0, v8, v8
	v_fmac_f32_e32 v1, v10, v10
	v_add_f32_e32 v0, v0, v1
	v_mul_f32_e32 v1, v5, v5
	v_mul_f32_e32 v2, v7, v7
	v_fmac_f32_e32 v1, v4, v4
	v_fmac_f32_e32 v2, v6, v6
	v_add_f32_e32 v0, v12, v0
	v_add_f32_e32 v1, v1, v2
	v_add_f32_e32 v12, v1, v0
	v_pk_mul_f32 v[2:3], v[176:177], v[8:9]
	v_mov_b32_e32 v244, v12
	v_mov_b32_e32 v245, v12
	s_nop 1
	v_permlane16_swap_b32_e32 v244, v245
	v_pk_mul_f32 v[0:1], v[174:175], v[10:11]
	v_cvt_pk_bf16_f32 v2, v2, v3
	v_cvt_pk_bf16_f32 v3, v0, v1
	v_pk_mul_f32 v[6:7], v[178:179], v[6:7]
	s_waitcnt lgkmcnt(0)
	v_add_f32_e32 v0, v244, v245
	v_mov_b32_e32 v246, v0
	v_mov_b32_e32 v247, v0
	s_nop 1
	v_permlane32_swap_b32_e32 v246, v247
	v_pk_mul_f32 v[4:5], v[170:171], v[4:5]
	s_nop 0
	v_cvt_pk_bf16_f32 v4, v4, v5
	v_cvt_pk_bf16_f32 v5, v6, v7
	v_lshl_add_u64 v[6:7], s[30:31], 0, v[20:21]
	global_store_dwordx4 v[6:7], v[2:5], off
	s_and_saveexec_b64 s[30:31], s[4:5]
	s_cbranch_execz .LBB0_854
	v_lshlrev_b64 v[2:3], 6, v[32:33]
	v_lshl_add_u64 v[2:3], s[16:17], 0, v[2:3]
	v_lshl_add_u64 v[2:3], s[0:1], 2, v[2:3]
	s_lshl_b32 s0, s58, 2
	s_mov_b32 s1, s3
	v_lshl_add_u64 v[2:3], v[2:3], 0, s[0:1]
	s_waitcnt lgkmcnt(0)
	v_add_f32_e32 v0, v246, v247
	global_store_dword v[2:3], v0, off
	s_branch .LBB0_854

.LBB0_1299:
	s_waitcnt lgkmcnt(0)
	v_pk_add_f32 v[166:167], v[166:167], 1.0 op_sel_hi:[1,0]
	v_pk_add_f32 v[164:165], v[164:165], 1.0 op_sel_hi:[1,0]
	v_add_u32_e32 v214, s72, v207
	v_pk_mul_f32 v[162:163], v[162:163], v[166:167]
	v_pk_mul_f32 v[160:161], v[160:161], v[164:165]
	v_pk_add_f32 v[164:165], v[158:159], 1.0 op_sel_hi:[1,0]
	v_pk_add_f32 v[166:167], v[156:157], 1.0 op_sel_hi:[1,0]
	ds_read_b128 v[156:159], v214
	v_pk_mul_f32 v[154:155], v[154:155], v[164:165]
	v_add_u32_e32 v164, s33, v205
	v_ashrrev_i32_e32 v165, 31, v164
	v_pk_mul_f32 v[152:153], v[152:153], v[166:167]
	s_waitcnt lgkmcnt(0)
	v_lshlrev_b32_e32 v218, 16, v156
	v_and_b32_e32 v219, 0xffff0000, v156
	v_or_b32_e32 v156, s46, v208
	v_lshlrev_b32_e32 v220, 16, v157
	v_and_b32_e32 v221, 0xffff0000, v157
	s_and_b64 s[0:1], s[44:45], exec
	v_ashrrev_i32_e32 v157, 31, v156
	v_lshlrev_b64 v[166:167], 10, v[164:165]
	v_lshlrev_b32_e32 v222, 16, v158
	v_and_b32_e32 v223, 0xffff0000, v158
	v_lshlrev_b32_e32 v224, 16, v159
	v_and_b32_e32 v225, 0xffff0000, v159
	v_readlane_b32 s0, v242, 24
	v_lshl_add_u64 v[226:227], v[166:167], 0, v[156:157]
	v_or_b32_e32 v166, 16, v164
	s_cselect_b32 s1, s9, s0
	v_readlane_b32 s0, v242, 23
	v_ashrrev_i32_e32 v167, 31, v166
	v_pk_fma_f32 v[140:141], v[140:141], v[64:65], v[218:219]
	v_pk_fma_f32 v[142:143], v[142:143], v[66:67], v[220:221]
	v_pk_fma_f32 v[136:137], v[136:137], v[80:81], v[222:223]
	v_pk_fma_f32 v[138:139], v[138:139], v[82:83], v[224:225]
	s_cselect_b32 s0, s8, s0
	v_lshl_add_u64 v[158:159], v[156:157], 1, s[42:43]
	v_lshlrev_b64 v[228:229], 11, v[166:167]
	v_pk_add_f32 v[230:231], v[188:189], v[142:143]
	v_pk_add_f32 v[232:233], v[186:187], v[140:141]
	v_pk_add_f32 v[234:235], v[198:199], v[138:139]
	v_pk_add_f32 v[236:237], v[190:191], v[136:137]
	v_lshlrev_b64 v[226:227], 1, v[226:227]
	v_lshl_add_u64 v[228:229], v[158:159], 0, v[228:229]
	v_cvt_pk_bf16_f32 v136, v232, v233
	v_cvt_pk_bf16_f32 v137, v230, v231
	v_cvt_pk_bf16_f32 v138, v236, v237
	v_cvt_pk_bf16_f32 v139, v234, v235
	v_lshl_add_u64 v[238:239], s[0:1], 0, v[226:227]
	global_load_dwordx4 v[140:143], v[228:229], off
	v_pk_mul_f32 v[218:219], v[162:163], v[234:235]
	global_store_dwordx4 v[238:239], v[136:139], off
	v_pk_mul_f32 v[220:221], v[160:161], v[236:237]
	ds_read_b128 v[214:217], v214 offset:1024
	v_pk_mul_f32 v[138:139], v[154:155], v[230:231]
	v_pk_mul_f32 v[136:137], v[152:153], v[232:233]
	v_pk_add_f32 v[150:151], v[150:151], 1.0 op_sel_hi:[1,0]
	v_cvt_pk_bf16_f32 v136, v136, v137
	v_cvt_pk_bf16_f32 v137, v138, v139
	v_cvt_pk_bf16_f32 v138, v220, v221
	v_cvt_pk_bf16_f32 v139, v218, v219
	v_lshl_add_u64 v[218:219], s[6:7], 0, v[226:227]
	global_store_dwordx4 v[218:219], v[136:139], off
	global_load_dwordx4 v[136:139], v[228:229], off offset:256
	ds_read_b128 v[218:221], v213 offset:2576
	ds_read_b128 v[222:225], v213 offset:3600
	v_pk_add_f32 v[228:229], v[148:149], 1.0 op_sel_hi:[1,0]
	v_pk_mul_f32 v[148:149], v[146:147], v[150:151]
	v_pk_mul_f32 v[150:151], v[144:145], v[228:229]
	v_mul_f32_e32 v213, v233, v233
	s_waitcnt lgkmcnt(0)
	v_pk_add_f32 v[144:145], v[224:225], 1.0 op_sel_hi:[1,0]
	v_pk_add_f32 v[222:223], v[222:223], 1.0 op_sel_hi:[1,0]
	v_pk_mul_f32 v[146:147], v[220:221], v[144:145]
	v_pk_mul_f32 v[144:145], v[218:219], v[222:223]
	v_lshlrev_b32_e32 v218, 16, v214
	v_and_b32_e32 v219, 0xffff0000, v214
	v_lshlrev_b32_e32 v214, 16, v215
	v_and_b32_e32 v215, 0xffff0000, v215
	v_lshlrev_b32_e32 v220, 16, v216
	v_and_b32_e32 v221, 0xffff0000, v216
	v_lshlrev_b32_e32 v216, 16, v217
	v_and_b32_e32 v217, 0xffff0000, v217
	v_pk_fma_f32 v[132:133], v[132:133], v[76:77], v[218:219]
	v_pk_fma_f32 v[134:135], v[134:135], v[78:79], v[214:215]
	v_pk_fma_f32 v[128:129], v[128:129], v[84:85], v[220:221]
	v_pk_fma_f32 v[130:131], v[130:131], v[86:87], v[216:217]
	v_mul_f32_e32 v222, v231, v231
	v_pk_add_f32 v[134:135], v[192:193], v[134:135]
	v_pk_add_f32 v[132:133], v[194:195], v[132:133]
	v_pk_add_f32 v[214:215], v[200:201], v[130:131]
	v_pk_add_f32 v[216:217], v[196:197], v[128:129]
	v_fmac_f32_e32 v213, v232, v232
	v_fmac_f32_e32 v222, v230, v230
	v_cvt_pk_bf16_f32 v128, v132, v133
	v_cvt_pk_bf16_f32 v129, v134, v135
	v_cvt_pk_bf16_f32 v130, v216, v217
	v_cvt_pk_bf16_f32 v131, v214, v215
	v_add_f32_e32 v213, v213, v222
	v_mul_f32_e32 v222, v237, v237
	v_mul_f32_e32 v223, v235, v235
	global_store_dwordx4 v[238:239], v[128:131], off offset:256
	v_fmac_f32_e32 v222, v236, v236
	v_fmac_f32_e32 v223, v234, v234
	v_mul_f32_e32 v128, v133, v133
	v_mul_f32_e32 v129, v135, v135
	v_fmac_f32_e32 v128, v132, v132
	v_fmac_f32_e32 v129, v134, v134
	v_add_f32_e32 v222, v222, v223
	v_add_f32_e32 v128, v128, v129
	v_mul_f32_e32 v129, v217, v217
	v_mul_f32_e32 v130, v215, v215
	v_add_f32_e32 v213, v213, v222
	v_fmac_f32_e32 v129, v216, v216
	v_fmac_f32_e32 v130, v214, v214
	v_add_f32_e32 v128, v213, v128
	v_add_f32_e32 v129, v129, v130
	v_add_f32_e32 v213, v129, v128
	v_pk_mul_f32 v[128:129], v[148:149], v[134:135]
	v_pk_mul_f32 v[134:135], v[146:147], v[214:215]
	v_mov_b32_e32 v244, v213
	v_mov_b32_e32 v245, v213
	s_nop 1
	v_permlane16_swap_b32_e32 v244, v245
	v_pk_mul_f32 v[130:131], v[150:151], v[132:133]
	s_lshl_b32 s40, s40, 2
	v_cvt_pk_bf16_f32 v130, v130, v131
	v_cvt_pk_bf16_f32 v131, v128, v129
	s_waitcnt lgkmcnt(0)
	v_add_f32_e32 v128, v244, v245
	v_mov_b32_e32 v246, v128
	v_mov_b32_e32 v247, v128
	s_nop 1
	v_permlane32_swap_b32_e32 v246, v247
	v_pk_mul_f32 v[132:133], v[144:145], v[216:217]
	v_or_b32_e32 v226, 0x100, v226
	s_ashr_i32 s41, s40, 31
	v_cvt_pk_bf16_f32 v132, v132, v133
	v_cvt_pk_bf16_f32 v133, v134, v135
	v_lshl_add_u64 v[134:135], s[6:7], 0, v[226:227]
	global_store_dwordx4 v[134:135], v[130:133], off
	s_and_saveexec_b64 s[42:43], s[2:3]
	s_cbranch_execz .LBB0_1301
	v_lshlrev_b64 v[130:131], 6, v[164:165]
	v_lshl_add_u64 v[130:131], s[10:11], 0, v[130:131]
	v_lshl_add_u64 v[130:131], s[40:41], 2, v[130:131]
	s_lshl_b32 s44, s69, 2
	s_mov_b32 s45, s13
	v_lshl_add_u64 v[130:131], v[130:131], 0, s[44:45]
	s_waitcnt lgkmcnt(0)
	v_add_f32_e32 v128, v246, v247
	global_store_dword v[130:131], v128, off
.LBB0_1301:
	s_or_b64 exec, exec, s[42:43]
	s_waitcnt lgkmcnt(0)
	v_lshlrev_b64 v[128:129], 10, v[166:167]
	s_waitcnt vmcnt(0)
	v_lshlrev_b32_e32 v130, 16, v140
	v_and_b32_e32 v131, 0xffff0000, v140
	v_lshlrev_b32_e32 v132, 16, v141
	v_and_b32_e32 v133, 0xffff0000, v141
	v_lshlrev_b32_e32 v134, 16, v142
	v_and_b32_e32 v135, 0xffff0000, v142
	v_lshlrev_b32_e32 v140, 16, v143
	v_and_b32_e32 v141, 0xffff0000, v143
	v_lshl_add_u64 v[142:143], v[128:129], 0, v[156:157]
	v_or_b32_e32 v128, 32, v164
	v_ashrrev_i32_e32 v129, 31, v128
	v_pk_fma_f32 v[124:125], v[124:125], v[64:65], v[130:131]
	v_pk_fma_f32 v[126:127], v[126:127], v[66:67], v[132:133]
	v_pk_fma_f32 v[120:121], v[120:121], v[80:81], v[134:135]
	v_pk_fma_f32 v[122:123], v[122:123], v[82:83], v[140:141]
	v_lshlrev_b64 v[214:215], 11, v[128:129]
	v_pk_add_f32 v[130:131], v[188:189], v[126:127]
	v_pk_add_f32 v[132:133], v[186:187], v[124:125]
	v_pk_add_f32 v[134:135], v[198:199], v[122:123]
	v_pk_add_f32 v[140:141], v[190:191], v[120:121]
	v_lshlrev_b64 v[142:143], 1, v[142:143]
	v_lshl_add_u64 v[214:215], v[158:159], 0, v[214:215]
	v_cvt_pk_bf16_f32 v120, v132, v133
	v_cvt_pk_bf16_f32 v121, v130, v131
	v_cvt_pk_bf16_f32 v122, v140, v141
	v_cvt_pk_bf16_f32 v123, v134, v135
	v_lshl_add_u64 v[216:217], s[0:1], 0, v[142:143]
	global_load_dwordx4 v[124:127], v[214:215], off
	v_pk_mul_f32 v[218:219], v[162:163], v[134:135]
	global_store_dwordx4 v[216:217], v[120:123], off
	v_pk_mul_f32 v[220:221], v[160:161], v[140:141]
	s_nop 0
	v_pk_mul_f32 v[122:123], v[154:155], v[130:131]
	v_pk_mul_f32 v[120:121], v[152:153], v[132:133]
	v_mul_f32_e32 v133, v133, v133
	v_cvt_pk_bf16_f32 v120, v120, v121
	v_cvt_pk_bf16_f32 v121, v122, v123
	v_cvt_pk_bf16_f32 v122, v220, v221
	v_cvt_pk_bf16_f32 v123, v218, v219
	v_lshl_add_u64 v[218:219], s[6:7], 0, v[142:143]
	global_store_dwordx4 v[218:219], v[120:123], off
	global_load_dwordx4 v[120:123], v[214:215], off offset:256
	v_mul_f32_e32 v131, v131, v131
	v_fmac_f32_e32 v133, v132, v132
	v_fmac_f32_e32 v131, v130, v130
	v_add_f32_e32 v130, v133, v131
	v_mul_f32_e32 v131, v141, v141
	v_mul_f32_e32 v132, v135, v135
	v_lshlrev_b32_e32 v214, 16, v136
	v_and_b32_e32 v215, 0xffff0000, v136
	v_lshlrev_b32_e32 v136, 16, v137
	v_and_b32_e32 v137, 0xffff0000, v137
	v_lshlrev_b32_e32 v218, 16, v138
	v_and_b32_e32 v219, 0xffff0000, v138
	v_lshlrev_b32_e32 v138, 16, v139
	v_and_b32_e32 v139, 0xffff0000, v139
	v_fmac_f32_e32 v131, v140, v140
	v_fmac_f32_e32 v132, v134, v134
	v_add_f32_e32 v131, v131, v132
	v_pk_fma_f32 v[116:117], v[116:117], v[76:77], v[214:215]
	v_pk_fma_f32 v[118:119], v[118:119], v[78:79], v[136:137]
	v_pk_fma_f32 v[112:113], v[112:113], v[84:85], v[218:219]
	v_pk_fma_f32 v[114:115], v[114:115], v[86:87], v[138:139]
	v_add_f32_e32 v134, v130, v131
	v_pk_add_f32 v[118:119], v[192:193], v[118:119]
	v_pk_add_f32 v[116:117], v[194:195], v[116:117]
	v_pk_add_f32 v[130:131], v[200:201], v[114:115]
	v_pk_add_f32 v[132:133], v[196:197], v[112:113]
	v_cvt_pk_bf16_f32 v112, v116, v117
	v_cvt_pk_bf16_f32 v113, v118, v119
	v_cvt_pk_bf16_f32 v114, v132, v133
	v_cvt_pk_bf16_f32 v115, v130, v131
	global_store_dwordx4 v[216:217], v[112:115], off offset:256
	v_or_b32_e32 v142, 0x100, v142
	s_nop 0
	v_mul_f32_e32 v112, v117, v117
	v_mul_f32_e32 v113, v119, v119
	v_fmac_f32_e32 v112, v116, v116
	v_fmac_f32_e32 v113, v118, v118
	v_add_f32_e32 v112, v112, v113
	v_mul_f32_e32 v113, v133, v133
	v_mul_f32_e32 v114, v131, v131
	v_fmac_f32_e32 v113, v132, v132
	v_fmac_f32_e32 v114, v130, v130
	v_add_f32_e32 v112, v134, v112
	v_add_f32_e32 v113, v113, v114
	v_add_f32_e32 v134, v113, v112
	v_pk_mul_f32 v[112:113], v[148:149], v[118:119]
	v_pk_mul_f32 v[118:119], v[146:147], v[130:131]
	v_mov_b32_e32 v244, v134
	v_mov_b32_e32 v245, v134
	s_nop 1
	v_permlane16_swap_b32_e32 v244, v245
	v_pk_mul_f32 v[114:115], v[150:151], v[116:117]
	v_pk_mul_f32 v[116:117], v[144:145], v[132:133]
	v_cvt_pk_bf16_f32 v114, v114, v115
	v_cvt_pk_bf16_f32 v115, v112, v113
	s_waitcnt lgkmcnt(0)
	v_add_f32_e32 v112, v244, v245
	v_mov_b32_e32 v246, v112
	v_mov_b32_e32 v247, v112
	s_nop 1
	v_permlane32_swap_b32_e32 v246, v247
	v_cvt_pk_bf16_f32 v116, v116, v117
	v_cvt_pk_bf16_f32 v117, v118, v119
	v_lshl_add_u64 v[118:119], s[6:7], 0, v[142:143]
	global_store_dwordx4 v[118:119], v[114:117], off
	s_and_saveexec_b64 s[42:43], s[2:3]
	s_cbranch_execz .LBB0_1303
	v_lshlrev_b64 v[114:115], 6, v[166:167]
	v_lshl_add_u64 v[114:115], s[10:11], 0, v[114:115]
	v_lshl_add_u64 v[114:115], s[40:41], 2, v[114:115]
	s_lshl_b32 s44, s69, 2
	s_mov_b32 s45, s13
	v_lshl_add_u64 v[114:115], v[114:115], 0, s[44:45]
	s_waitcnt lgkmcnt(0)
	v_add_f32_e32 v112, v246, v247
	global_store_dword v[114:115], v112, off
.LBB0_1303:
	s_or_b64 exec, exec, s[42:43]
	s_waitcnt lgkmcnt(0)
	v_lshlrev_b64 v[112:113], 10, v[128:129]
	s_waitcnt vmcnt(5)
	v_lshlrev_b32_e32 v114, 16, v124
	v_and_b32_e32 v115, 0xffff0000, v124
	v_lshlrev_b32_e32 v116, 16, v125
	v_and_b32_e32 v117, 0xffff0000, v125
	v_lshlrev_b32_e32 v118, 16, v126
	v_and_b32_e32 v119, 0xffff0000, v126
	v_lshlrev_b32_e32 v124, 16, v127
	v_and_b32_e32 v125, 0xffff0000, v127
	v_lshl_add_u64 v[126:127], v[112:113], 0, v[156:157]
	v_or_b32_e32 v112, 48, v164
	v_ashrrev_i32_e32 v113, 31, v112
	v_pk_fma_f32 v[108:109], v[108:109], v[64:65], v[114:115]
	v_pk_fma_f32 v[110:111], v[110:111], v[66:67], v[116:117]
	v_pk_fma_f32 v[104:105], v[104:105], v[80:81], v[118:119]
	v_pk_fma_f32 v[106:107], v[106:107], v[82:83], v[124:125]
	v_lshlrev_b64 v[130:131], 11, v[112:113]
	v_pk_add_f32 v[114:115], v[188:189], v[110:111]
	v_pk_add_f32 v[116:117], v[186:187], v[108:109]
	v_pk_add_f32 v[118:119], v[198:199], v[106:107]
	v_pk_add_f32 v[124:125], v[190:191], v[104:105]
	v_lshlrev_b64 v[126:127], 1, v[126:127]
	v_lshl_add_u64 v[130:131], v[158:159], 0, v[130:131]
	v_cvt_pk_bf16_f32 v104, v116, v117
	v_cvt_pk_bf16_f32 v105, v114, v115
	v_cvt_pk_bf16_f32 v106, v124, v125
	v_cvt_pk_bf16_f32 v107, v118, v119
	v_lshl_add_u64 v[132:133], s[0:1], 0, v[126:127]
	global_load_dwordx4 v[108:111], v[130:131], off
	v_pk_mul_f32 v[134:135], v[162:163], v[118:119]
	global_store_dwordx4 v[132:133], v[104:107], off
	v_pk_mul_f32 v[136:137], v[160:161], v[124:125]
	s_nop 0
	v_pk_mul_f32 v[106:107], v[154:155], v[114:115]
	v_pk_mul_f32 v[104:105], v[152:153], v[116:117]
	v_mul_f32_e32 v117, v117, v117
	v_cvt_pk_bf16_f32 v104, v104, v105
	v_cvt_pk_bf16_f32 v105, v106, v107
	v_cvt_pk_bf16_f32 v106, v136, v137
	v_cvt_pk_bf16_f32 v107, v134, v135
	v_lshl_add_u64 v[134:135], s[6:7], 0, v[126:127]
	global_store_dwordx4 v[134:135], v[104:107], off
	global_load_dwordx4 v[104:107], v[130:131], off offset:256
	v_mul_f32_e32 v115, v115, v115
	v_fmac_f32_e32 v117, v116, v116
	v_fmac_f32_e32 v115, v114, v114
	v_add_f32_e32 v114, v117, v115
	v_mul_f32_e32 v115, v125, v125
	v_mul_f32_e32 v116, v119, v119
	s_waitcnt vmcnt(6)
	v_lshlrev_b32_e32 v130, 16, v120
	v_and_b32_e32 v131, 0xffff0000, v120
	v_lshlrev_b32_e32 v120, 16, v121
	v_and_b32_e32 v121, 0xffff0000, v121
	v_lshlrev_b32_e32 v134, 16, v122
	v_and_b32_e32 v135, 0xffff0000, v122
	v_lshlrev_b32_e32 v122, 16, v123
	v_and_b32_e32 v123, 0xffff0000, v123
	v_fmac_f32_e32 v115, v124, v124
	v_fmac_f32_e32 v116, v118, v118
	v_add_f32_e32 v115, v115, v116
	v_pk_fma_f32 v[100:101], v[100:101], v[76:77], v[130:131]
	v_pk_fma_f32 v[102:103], v[102:103], v[78:79], v[120:121]
	v_pk_fma_f32 v[96:97], v[96:97], v[84:85], v[134:135]
	v_pk_fma_f32 v[98:99], v[98:99], v[86:87], v[122:123]
	v_add_f32_e32 v118, v114, v115
	v_pk_add_f32 v[102:103], v[192:193], v[102:103]
	v_pk_add_f32 v[100:101], v[194:195], v[100:101]
	v_pk_add_f32 v[114:115], v[200:201], v[98:99]
	v_pk_add_f32 v[116:117], v[196:197], v[96:97]
	v_cvt_pk_bf16_f32 v96, v100, v101
	v_cvt_pk_bf16_f32 v97, v102, v103
	v_cvt_pk_bf16_f32 v98, v116, v117
	v_cvt_pk_bf16_f32 v99, v114, v115
	global_store_dwordx4 v[132:133], v[96:99], off offset:256
	v_or_b32_e32 v126, 0x100, v126
	s_nop 0
	v_mul_f32_e32 v96, v101, v101
	v_mul_f32_e32 v97, v103, v103
	v_fmac_f32_e32 v96, v100, v100
	v_fmac_f32_e32 v97, v102, v102
	v_add_f32_e32 v96, v96, v97
	v_mul_f32_e32 v97, v117, v117
	v_mul_f32_e32 v98, v115, v115
	v_fmac_f32_e32 v97, v116, v116
	v_fmac_f32_e32 v98, v114, v114
	v_add_f32_e32 v96, v118, v96
	v_add_f32_e32 v97, v97, v98
	v_add_f32_e32 v118, v97, v96
	v_pk_mul_f32 v[96:97], v[148:149], v[102:103]
	v_pk_mul_f32 v[102:103], v[146:147], v[114:115]
	v_mov_b32_e32 v244, v118
	v_mov_b32_e32 v245, v118
	s_nop 1
	v_permlane16_swap_b32_e32 v244, v245
	v_pk_mul_f32 v[98:99], v[150:151], v[100:101]
	v_pk_mul_f32 v[100:101], v[144:145], v[116:117]
	v_cvt_pk_bf16_f32 v98, v98, v99
	v_cvt_pk_bf16_f32 v99, v96, v97
	s_waitcnt lgkmcnt(0)
	v_add_f32_e32 v96, v244, v245
	v_mov_b32_e32 v246, v96
	v_mov_b32_e32 v247, v96
	s_nop 1
	v_permlane32_swap_b32_e32 v246, v247
	v_cvt_pk_bf16_f32 v100, v100, v101
	v_cvt_pk_bf16_f32 v101, v102, v103
	v_lshl_add_u64 v[102:103], s[6:7], 0, v[126:127]
	global_store_dwordx4 v[102:103], v[98:101], off
	s_and_saveexec_b64 s[42:43], s[2:3]
	s_cbranch_execz .LBB0_1305
	v_lshlrev_b64 v[98:99], 6, v[128:129]
	v_lshl_add_u64 v[98:99], s[10:11], 0, v[98:99]
	v_lshl_add_u64 v[98:99], s[40:41], 2, v[98:99]
	s_lshl_b32 s44, s69, 2
	s_mov_b32 s45, s13
	v_lshl_add_u64 v[98:99], v[98:99], 0, s[44:45]
	s_waitcnt lgkmcnt(0)
	v_add_f32_e32 v96, v246, v247
	global_store_dword v[98:99], v96, off
.LBB0_1305:
	s_or_b64 exec, exec, s[42:43]
	s_waitcnt lgkmcnt(0)
	v_lshlrev_b64 v[96:97], 10, v[112:113]
	s_waitcnt vmcnt(5)
	v_lshlrev_b32_e32 v98, 16, v108
	v_and_b32_e32 v99, 0xffff0000, v108
	v_lshlrev_b32_e32 v100, 16, v109
	v_and_b32_e32 v101, 0xffff0000, v109
	v_lshlrev_b32_e32 v102, 16, v110
	v_and_b32_e32 v103, 0xffff0000, v110
	v_lshlrev_b32_e32 v108, 16, v111
	v_and_b32_e32 v109, 0xffff0000, v111
	v_lshl_add_u64 v[110:111], v[96:97], 0, v[156:157]
	v_add_u32_e32 v96, 0x80, v164
	v_ashrrev_i32_e32 v97, 31, v96
	v_pk_fma_f32 v[92:93], v[92:93], v[64:65], v[98:99]
	v_pk_fma_f32 v[94:95], v[94:95], v[66:67], v[100:101]
	v_pk_fma_f32 v[88:89], v[88:89], v[80:81], v[102:103]
	v_pk_fma_f32 v[90:91], v[90:91], v[82:83], v[108:109]
	v_lshlrev_b64 v[114:115], 11, v[96:97]
	v_pk_add_f32 v[98:99], v[188:189], v[94:95]
	v_pk_add_f32 v[100:101], v[186:187], v[92:93]
	v_pk_add_f32 v[102:103], v[198:199], v[90:91]
	v_pk_add_f32 v[108:109], v[190:191], v[88:89]
	v_lshlrev_b64 v[110:111], 1, v[110:111]
	v_lshl_add_u64 v[114:115], v[158:159], 0, v[114:115]
	v_cvt_pk_bf16_f32 v88, v100, v101
	v_cvt_pk_bf16_f32 v89, v98, v99
	v_cvt_pk_bf16_f32 v90, v108, v109
	v_cvt_pk_bf16_f32 v91, v102, v103
	v_lshl_add_u64 v[116:117], s[0:1], 0, v[110:111]
	global_load_dwordx4 v[92:95], v[114:115], off
	v_pk_mul_f32 v[118:119], v[162:163], v[102:103]
	global_store_dwordx4 v[116:117], v[88:91], off
	v_pk_mul_f32 v[120:121], v[160:161], v[108:109]
	s_nop 0
	v_pk_mul_f32 v[90:91], v[154:155], v[98:99]
	v_pk_mul_f32 v[88:89], v[152:153], v[100:101]
	v_mul_f32_e32 v101, v101, v101
	v_cvt_pk_bf16_f32 v88, v88, v89
	v_cvt_pk_bf16_f32 v89, v90, v91
	v_cvt_pk_bf16_f32 v90, v120, v121
	v_cvt_pk_bf16_f32 v91, v118, v119
	v_lshl_add_u64 v[118:119], s[6:7], 0, v[110:111]
	global_store_dwordx4 v[118:119], v[88:91], off
	global_load_dwordx4 v[88:91], v[114:115], off offset:256
	v_mul_f32_e32 v99, v99, v99
	v_fmac_f32_e32 v101, v100, v100
	v_fmac_f32_e32 v99, v98, v98
	v_add_f32_e32 v98, v101, v99
	v_mul_f32_e32 v99, v109, v109
	v_mul_f32_e32 v100, v103, v103
	s_waitcnt vmcnt(6)
	v_lshlrev_b32_e32 v114, 16, v104
	v_and_b32_e32 v115, 0xffff0000, v104
	v_lshlrev_b32_e32 v104, 16, v105
	v_and_b32_e32 v105, 0xffff0000, v105
	v_lshlrev_b32_e32 v118, 16, v106
	v_and_b32_e32 v119, 0xffff0000, v106
	v_lshlrev_b32_e32 v106, 16, v107
	v_and_b32_e32 v107, 0xffff0000, v107
	v_fmac_f32_e32 v99, v108, v108
	v_fmac_f32_e32 v100, v102, v102
	v_add_f32_e32 v99, v99, v100
	v_pk_fma_f32 v[72:73], v[72:73], v[76:77], v[114:115]
	v_pk_fma_f32 v[74:75], v[74:75], v[78:79], v[104:105]
	v_pk_fma_f32 v[68:69], v[68:69], v[84:85], v[118:119]
	v_pk_fma_f32 v[70:71], v[70:71], v[86:87], v[106:107]
	v_add_f32_e32 v102, v98, v99
	v_pk_add_f32 v[74:75], v[192:193], v[74:75]
	v_pk_add_f32 v[72:73], v[194:195], v[72:73]
	v_pk_add_f32 v[98:99], v[200:201], v[70:71]
	v_pk_add_f32 v[100:101], v[196:197], v[68:69]
	v_cvt_pk_bf16_f32 v68, v72, v73
	v_cvt_pk_bf16_f32 v69, v74, v75
	v_cvt_pk_bf16_f32 v70, v100, v101
	v_cvt_pk_bf16_f32 v71, v98, v99
	global_store_dwordx4 v[116:117], v[68:71], off offset:256
	v_or_b32_e32 v110, 0x100, v110
	s_nop 0
	v_mul_f32_e32 v68, v73, v73
	v_mul_f32_e32 v69, v75, v75
	v_fmac_f32_e32 v68, v72, v72
	v_fmac_f32_e32 v69, v74, v74
	v_add_f32_e32 v68, v68, v69
	v_mul_f32_e32 v69, v101, v101
	v_mul_f32_e32 v70, v99, v99
	v_fmac_f32_e32 v69, v100, v100
	v_fmac_f32_e32 v70, v98, v98
	v_add_f32_e32 v68, v102, v68
	v_add_f32_e32 v69, v69, v70
	v_add_f32_e32 v102, v69, v68
	v_pk_mul_f32 v[68:69], v[148:149], v[74:75]
	v_pk_mul_f32 v[74:75], v[146:147], v[98:99]
	v_mov_b32_e32 v244, v102
	v_mov_b32_e32 v245, v102
	s_nop 1
	v_permlane16_swap_b32_e32 v244, v245
	v_pk_mul_f32 v[70:71], v[150:151], v[72:73]
	v_pk_mul_f32 v[72:73], v[144:145], v[100:101]
	v_cvt_pk_bf16_f32 v70, v70, v71
	v_cvt_pk_bf16_f32 v71, v68, v69
	s_waitcnt lgkmcnt(0)
	v_add_f32_e32 v68, v244, v245
	v_mov_b32_e32 v246, v68
	v_mov_b32_e32 v247, v68
	s_nop 1
	v_permlane32_swap_b32_e32 v246, v247
	v_cvt_pk_bf16_f32 v72, v72, v73
	v_cvt_pk_bf16_f32 v73, v74, v75
	v_lshl_add_u64 v[74:75], s[6:7], 0, v[110:111]
	global_store_dwordx4 v[74:75], v[70:73], off
	s_and_saveexec_b64 s[42:43], s[2:3]
	s_cbranch_execz .LBB0_1307
	v_lshlrev_b64 v[70:71], 6, v[112:113]
	v_lshl_add_u64 v[70:71], s[10:11], 0, v[70:71]
	v_lshl_add_u64 v[70:71], s[40:41], 2, v[70:71]
	s_lshl_b32 s44, s69, 2
	s_mov_b32 s45, s13
	v_lshl_add_u64 v[70:71], v[70:71], 0, s[44:45]
	s_waitcnt lgkmcnt(0)
	v_add_f32_e32 v68, v246, v247
	global_store_dword v[70:71], v68, off
.LBB0_1307:
	s_or_b64 exec, exec, s[42:43]
	s_waitcnt lgkmcnt(0)
	v_lshlrev_b64 v[68:69], 10, v[96:97]
	s_waitcnt vmcnt(5)
	v_lshlrev_b32_e32 v70, 16, v92
	v_and_b32_e32 v71, 0xffff0000, v92
	v_lshlrev_b32_e32 v72, 16, v93
	v_and_b32_e32 v73, 0xffff0000, v93
	v_lshlrev_b32_e32 v74, 16, v94
	v_and_b32_e32 v75, 0xffff0000, v94
	v_lshlrev_b32_e32 v92, 16, v95
	v_and_b32_e32 v93, 0xffff0000, v95
	v_lshl_add_u64 v[94:95], v[68:69], 0, v[156:157]
	v_or_b32_e32 v68, 16, v96
	v_ashrrev_i32_e32 v69, 31, v68
	v_pk_fma_f32 v[60:61], v[60:61], v[64:65], v[70:71]
	v_pk_fma_f32 v[62:63], v[62:63], v[66:67], v[72:73]
	v_pk_fma_f32 v[56:57], v[56:57], v[80:81], v[74:75]
	v_pk_fma_f32 v[58:59], v[58:59], v[82:83], v[92:93]
	v_lshlrev_b64 v[98:99], 11, v[68:69]
	v_pk_add_f32 v[70:71], v[188:189], v[62:63]
	v_pk_add_f32 v[72:73], v[186:187], v[60:61]
	v_pk_add_f32 v[74:75], v[198:199], v[58:59]
	v_pk_add_f32 v[92:93], v[190:191], v[56:57]
	v_lshlrev_b64 v[94:95], 1, v[94:95]
	v_lshl_add_u64 v[98:99], v[158:159], 0, v[98:99]
	v_cvt_pk_bf16_f32 v56, v72, v73
	v_cvt_pk_bf16_f32 v57, v70, v71
	v_cvt_pk_bf16_f32 v58, v92, v93
	v_cvt_pk_bf16_f32 v59, v74, v75
	v_lshl_add_u64 v[100:101], s[0:1], 0, v[94:95]
	global_load_dwordx4 v[60:63], v[98:99], off
	v_pk_mul_f32 v[102:103], v[162:163], v[74:75]
	global_store_dwordx4 v[100:101], v[56:59], off
	v_pk_mul_f32 v[104:105], v[160:161], v[92:93]
	s_nop 0
	v_pk_mul_f32 v[58:59], v[154:155], v[70:71]
	v_pk_mul_f32 v[56:57], v[152:153], v[72:73]
	v_mul_f32_e32 v73, v73, v73
	v_cvt_pk_bf16_f32 v56, v56, v57
	v_cvt_pk_bf16_f32 v57, v58, v59
	v_cvt_pk_bf16_f32 v58, v104, v105
	v_cvt_pk_bf16_f32 v59, v102, v103
	v_lshl_add_u64 v[102:103], s[6:7], 0, v[94:95]
	global_store_dwordx4 v[102:103], v[56:59], off
	global_load_dwordx4 v[56:59], v[98:99], off offset:256
	v_mul_f32_e32 v71, v71, v71
	v_fmac_f32_e32 v73, v72, v72
	v_fmac_f32_e32 v71, v70, v70
	v_add_f32_e32 v70, v73, v71
	v_mul_f32_e32 v71, v93, v93
	v_mul_f32_e32 v72, v75, v75
	s_waitcnt vmcnt(6)
	v_lshlrev_b32_e32 v98, 16, v88
	v_and_b32_e32 v99, 0xffff0000, v88
	v_lshlrev_b32_e32 v88, 16, v89
	v_and_b32_e32 v89, 0xffff0000, v89
	v_lshlrev_b32_e32 v102, 16, v90
	v_and_b32_e32 v103, 0xffff0000, v90
	v_lshlrev_b32_e32 v90, 16, v91
	v_and_b32_e32 v91, 0xffff0000, v91
	v_fmac_f32_e32 v71, v92, v92
	v_fmac_f32_e32 v72, v74, v74
	v_add_f32_e32 v71, v71, v72
	v_pk_fma_f32 v[52:53], v[52:53], v[76:77], v[98:99]
	v_pk_fma_f32 v[54:55], v[54:55], v[78:79], v[88:89]
	v_pk_fma_f32 v[48:49], v[48:49], v[84:85], v[102:103]
	v_pk_fma_f32 v[50:51], v[50:51], v[86:87], v[90:91]
	v_add_f32_e32 v74, v70, v71
	v_pk_add_f32 v[54:55], v[192:193], v[54:55]
	v_pk_add_f32 v[52:53], v[194:195], v[52:53]
	v_pk_add_f32 v[70:71], v[200:201], v[50:51]
	v_pk_add_f32 v[72:73], v[196:197], v[48:49]
	v_cvt_pk_bf16_f32 v48, v52, v53
	v_cvt_pk_bf16_f32 v49, v54, v55
	v_cvt_pk_bf16_f32 v50, v72, v73
	v_cvt_pk_bf16_f32 v51, v70, v71
	global_store_dwordx4 v[100:101], v[48:51], off offset:256
	v_or_b32_e32 v94, 0x100, v94
	s_nop 0
	v_mul_f32_e32 v48, v53, v53
	v_mul_f32_e32 v49, v55, v55
	v_fmac_f32_e32 v48, v52, v52
	v_fmac_f32_e32 v49, v54, v54
	v_add_f32_e32 v48, v48, v49
	v_mul_f32_e32 v49, v73, v73
	v_mul_f32_e32 v50, v71, v71
	v_fmac_f32_e32 v49, v72, v72
	v_fmac_f32_e32 v50, v70, v70
	v_add_f32_e32 v48, v74, v48
	v_add_f32_e32 v49, v49, v50
	v_add_f32_e32 v74, v49, v48
	v_pk_mul_f32 v[48:49], v[148:149], v[54:55]
	v_pk_mul_f32 v[54:55], v[146:147], v[70:71]
	v_mov_b32_e32 v244, v74
	v_mov_b32_e32 v245, v74
	s_nop 1
	v_permlane16_swap_b32_e32 v244, v245
	v_pk_mul_f32 v[50:51], v[150:151], v[52:53]
	v_pk_mul_f32 v[52:53], v[144:145], v[72:73]
	v_cvt_pk_bf16_f32 v50, v50, v51
	v_cvt_pk_bf16_f32 v51, v48, v49
	s_waitcnt lgkmcnt(0)
	v_add_f32_e32 v48, v244, v245
	v_mov_b32_e32 v246, v48
	v_mov_b32_e32 v247, v48
	s_nop 1
	v_permlane32_swap_b32_e32 v246, v247
	v_cvt_pk_bf16_f32 v52, v52, v53
	v_cvt_pk_bf16_f32 v53, v54, v55
	v_lshl_add_u64 v[54:55], s[6:7], 0, v[94:95]
	global_store_dwordx4 v[54:55], v[50:53], off
	s_and_saveexec_b64 s[42:43], s[2:3]
	s_cbranch_execz .LBB0_1309
	v_lshlrev_b64 v[50:51], 6, v[96:97]
	v_lshl_add_u64 v[50:51], s[10:11], 0, v[50:51]
	v_lshl_add_u64 v[50:51], s[40:41], 2, v[50:51]
	s_lshl_b32 s44, s69, 2
	s_mov_b32 s45, s13
	v_lshl_add_u64 v[50:51], v[50:51], 0, s[44:45]
	s_waitcnt lgkmcnt(0)
	v_add_f32_e32 v48, v246, v247
	global_store_dword v[50:51], v48, off
.LBB0_1309:
	s_or_b64 exec, exec, s[42:43]
	s_waitcnt lgkmcnt(0)
	v_lshlrev_b64 v[48:49], 10, v[68:69]
	s_waitcnt vmcnt(5)
	v_lshlrev_b32_e32 v50, 16, v60
	v_and_b32_e32 v51, 0xffff0000, v60
	v_lshlrev_b32_e32 v52, 16, v61
	v_and_b32_e32 v53, 0xffff0000, v61
	v_lshlrev_b32_e32 v54, 16, v62
	v_and_b32_e32 v55, 0xffff0000, v62
	v_lshlrev_b32_e32 v60, 16, v63
	v_and_b32_e32 v61, 0xffff0000, v63
	v_lshl_add_u64 v[62:63], v[48:49], 0, v[156:157]
	v_or_b32_e32 v48, 32, v96
	v_ashrrev_i32_e32 v49, 31, v48
	v_pk_fma_f32 v[44:45], v[44:45], v[64:65], v[50:51]
	v_pk_fma_f32 v[46:47], v[46:47], v[66:67], v[52:53]
	v_pk_fma_f32 v[40:41], v[40:41], v[80:81], v[54:55]
	v_pk_fma_f32 v[42:43], v[42:43], v[82:83], v[60:61]
	v_lshlrev_b64 v[70:71], 11, v[48:49]
	v_pk_add_f32 v[50:51], v[188:189], v[46:47]
	v_pk_add_f32 v[52:53], v[186:187], v[44:45]
	v_pk_add_f32 v[54:55], v[198:199], v[42:43]
	v_pk_add_f32 v[60:61], v[190:191], v[40:41]
	v_lshlrev_b64 v[62:63], 1, v[62:63]
	v_lshl_add_u64 v[70:71], v[158:159], 0, v[70:71]
	v_cvt_pk_bf16_f32 v40, v52, v53
	v_cvt_pk_bf16_f32 v41, v50, v51
	v_cvt_pk_bf16_f32 v42, v60, v61
	v_cvt_pk_bf16_f32 v43, v54, v55
	v_lshl_add_u64 v[72:73], s[0:1], 0, v[62:63]
	global_load_dwordx4 v[44:47], v[70:71], off
	v_pk_mul_f32 v[74:75], v[162:163], v[54:55]
	global_store_dwordx4 v[72:73], v[40:43], off
	v_pk_mul_f32 v[88:89], v[160:161], v[60:61]
	s_nop 0
	v_pk_mul_f32 v[42:43], v[154:155], v[50:51]
	v_pk_mul_f32 v[40:41], v[152:153], v[52:53]
	v_mul_f32_e32 v53, v53, v53
	v_cvt_pk_bf16_f32 v40, v40, v41
	v_cvt_pk_bf16_f32 v41, v42, v43
	v_cvt_pk_bf16_f32 v42, v88, v89
	v_cvt_pk_bf16_f32 v43, v74, v75
	v_lshl_add_u64 v[74:75], s[6:7], 0, v[62:63]
	global_store_dwordx4 v[74:75], v[40:43], off
	global_load_dwordx4 v[40:43], v[70:71], off offset:256
	v_mul_f32_e32 v51, v51, v51
	v_fmac_f32_e32 v53, v52, v52
	v_fmac_f32_e32 v51, v50, v50
	v_add_f32_e32 v50, v53, v51
	v_mul_f32_e32 v51, v61, v61
	v_mul_f32_e32 v52, v55, v55
	s_waitcnt vmcnt(6)
	v_lshlrev_b32_e32 v70, 16, v56
	v_and_b32_e32 v71, 0xffff0000, v56
	v_lshlrev_b32_e32 v56, 16, v57
	v_and_b32_e32 v57, 0xffff0000, v57
	v_lshlrev_b32_e32 v74, 16, v58
	v_and_b32_e32 v75, 0xffff0000, v58
	v_lshlrev_b32_e32 v58, 16, v59
	v_and_b32_e32 v59, 0xffff0000, v59
	v_fmac_f32_e32 v51, v60, v60
	v_fmac_f32_e32 v52, v54, v54
	v_add_f32_e32 v51, v51, v52
	v_pk_fma_f32 v[36:37], v[36:37], v[76:77], v[70:71]
	v_pk_fma_f32 v[38:39], v[38:39], v[78:79], v[56:57]
	v_pk_fma_f32 v[32:33], v[32:33], v[84:85], v[74:75]
	v_pk_fma_f32 v[34:35], v[34:35], v[86:87], v[58:59]
	v_add_f32_e32 v54, v50, v51
	v_pk_add_f32 v[38:39], v[192:193], v[38:39]
	v_pk_add_f32 v[36:37], v[194:195], v[36:37]
	v_pk_add_f32 v[50:51], v[200:201], v[34:35]
	v_pk_add_f32 v[52:53], v[196:197], v[32:33]
	v_cvt_pk_bf16_f32 v32, v36, v37
	v_cvt_pk_bf16_f32 v33, v38, v39
	v_cvt_pk_bf16_f32 v34, v52, v53
	v_cvt_pk_bf16_f32 v35, v50, v51
	global_store_dwordx4 v[72:73], v[32:35], off offset:256
	v_or_b32_e32 v62, 0x100, v62
	s_nop 0
	v_mul_f32_e32 v32, v37, v37
	v_mul_f32_e32 v33, v39, v39
	v_fmac_f32_e32 v32, v36, v36
	v_fmac_f32_e32 v33, v38, v38
	v_add_f32_e32 v32, v32, v33
	v_mul_f32_e32 v33, v53, v53
	v_mul_f32_e32 v34, v51, v51
	v_fmac_f32_e32 v33, v52, v52
	v_fmac_f32_e32 v34, v50, v50
	v_add_f32_e32 v32, v54, v32
	v_add_f32_e32 v33, v33, v34
	v_add_f32_e32 v54, v33, v32
	v_pk_mul_f32 v[32:33], v[148:149], v[38:39]
	v_pk_mul_f32 v[38:39], v[146:147], v[50:51]
	v_mov_b32_e32 v244, v54
	v_mov_b32_e32 v245, v54
	s_nop 1
	v_permlane16_swap_b32_e32 v244, v245
	v_pk_mul_f32 v[34:35], v[150:151], v[36:37]
	v_pk_mul_f32 v[36:37], v[144:145], v[52:53]
	v_cvt_pk_bf16_f32 v34, v34, v35
	v_cvt_pk_bf16_f32 v35, v32, v33
	s_waitcnt lgkmcnt(0)
	v_add_f32_e32 v32, v244, v245
	v_mov_b32_e32 v246, v32
	v_mov_b32_e32 v247, v32
	s_nop 1
	v_permlane32_swap_b32_e32 v246, v247
	v_cvt_pk_bf16_f32 v36, v36, v37
	v_cvt_pk_bf16_f32 v37, v38, v39
	v_lshl_add_u64 v[38:39], s[6:7], 0, v[62:63]
	global_store_dwordx4 v[38:39], v[34:37], off
	s_and_saveexec_b64 s[42:43], s[2:3]
	s_cbranch_execz .LBB0_1311
	v_lshlrev_b64 v[34:35], 6, v[68:69]
	v_lshl_add_u64 v[34:35], s[10:11], 0, v[34:35]
	v_lshl_add_u64 v[34:35], s[40:41], 2, v[34:35]
	s_lshl_b32 s44, s69, 2
	s_mov_b32 s45, s13
	v_lshl_add_u64 v[34:35], v[34:35], 0, s[44:45]
	s_waitcnt lgkmcnt(0)
	v_add_f32_e32 v32, v246, v247
	global_store_dword v[34:35], v32, off
.LBB0_1311:
	s_or_b64 exec, exec, s[42:43]
	s_waitcnt lgkmcnt(0)
	v_lshlrev_b64 v[32:33], 10, v[48:49]
	s_waitcnt vmcnt(5)
	v_lshlrev_b32_e32 v34, 16, v44
	v_and_b32_e32 v35, 0xffff0000, v44
	v_lshlrev_b32_e32 v36, 16, v45
	v_and_b32_e32 v37, 0xffff0000, v45
	v_lshlrev_b32_e32 v38, 16, v46
	v_and_b32_e32 v39, 0xffff0000, v46
	v_lshlrev_b32_e32 v44, 16, v47
	v_and_b32_e32 v45, 0xffff0000, v47
	v_lshl_add_u64 v[46:47], v[32:33], 0, v[156:157]
	v_or_b32_e32 v32, 48, v96
	v_ashrrev_i32_e32 v33, 31, v32
	v_pk_fma_f32 v[28:29], v[28:29], v[64:65], v[34:35]
	v_pk_fma_f32 v[30:31], v[30:31], v[66:67], v[36:37]
	v_pk_fma_f32 v[24:25], v[24:25], v[80:81], v[38:39]
	v_pk_fma_f32 v[26:27], v[26:27], v[82:83], v[44:45]
	v_lshlrev_b64 v[50:51], 11, v[32:33]
	v_pk_add_f32 v[34:35], v[188:189], v[30:31]
	v_pk_add_f32 v[36:37], v[186:187], v[28:29]
	v_pk_add_f32 v[38:39], v[198:199], v[26:27]
	v_pk_add_f32 v[44:45], v[190:191], v[24:25]
	v_lshlrev_b64 v[46:47], 1, v[46:47]
	v_lshl_add_u64 v[50:51], v[158:159], 0, v[50:51]
	v_cvt_pk_bf16_f32 v28, v36, v37
	v_cvt_pk_bf16_f32 v29, v34, v35
	v_cvt_pk_bf16_f32 v30, v44, v45
	v_cvt_pk_bf16_f32 v31, v38, v39
	v_lshl_add_u64 v[52:53], s[0:1], 0, v[46:47]
	global_load_dwordx4 v[24:27], v[50:51], off
	v_pk_mul_f32 v[54:55], v[162:163], v[38:39]
	global_store_dwordx4 v[52:53], v[28:31], off
	v_pk_mul_f32 v[56:57], v[160:161], v[44:45]
	s_nop 0
	v_pk_mul_f32 v[30:31], v[154:155], v[34:35]
	v_pk_mul_f32 v[28:29], v[152:153], v[36:37]
	v_mul_f32_e32 v37, v37, v37
	v_cvt_pk_bf16_f32 v28, v28, v29
	v_cvt_pk_bf16_f32 v29, v30, v31
	v_cvt_pk_bf16_f32 v30, v56, v57
	v_cvt_pk_bf16_f32 v31, v54, v55
	v_lshl_add_u64 v[54:55], s[6:7], 0, v[46:47]
	global_store_dwordx4 v[54:55], v[28:31], off
	global_load_dwordx4 v[28:31], v[50:51], off offset:256
	v_mul_f32_e32 v35, v35, v35
	v_fmac_f32_e32 v37, v36, v36
	v_fmac_f32_e32 v35, v34, v34
	v_add_f32_e32 v34, v37, v35
	v_mul_f32_e32 v35, v45, v45
	v_mul_f32_e32 v36, v39, v39
	s_waitcnt vmcnt(6)
	v_lshlrev_b32_e32 v50, 16, v40
	v_and_b32_e32 v51, 0xffff0000, v40
	v_lshlrev_b32_e32 v40, 16, v41
	v_and_b32_e32 v41, 0xffff0000, v41
	v_lshlrev_b32_e32 v54, 16, v42
	v_and_b32_e32 v55, 0xffff0000, v42
	v_lshlrev_b32_e32 v42, 16, v43
	v_and_b32_e32 v43, 0xffff0000, v43
	v_fmac_f32_e32 v35, v44, v44
	v_fmac_f32_e32 v36, v38, v38
	v_add_f32_e32 v35, v35, v36
	v_pk_fma_f32 v[20:21], v[20:21], v[76:77], v[50:51]
	v_pk_fma_f32 v[22:23], v[22:23], v[78:79], v[40:41]
	v_pk_fma_f32 v[16:17], v[16:17], v[84:85], v[54:55]
	v_pk_fma_f32 v[18:19], v[18:19], v[86:87], v[42:43]
	v_add_f32_e32 v38, v34, v35
	v_pk_add_f32 v[22:23], v[192:193], v[22:23]
	v_pk_add_f32 v[20:21], v[194:195], v[20:21]
	v_pk_add_f32 v[34:35], v[200:201], v[18:19]
	v_pk_add_f32 v[36:37], v[196:197], v[16:17]
	v_cvt_pk_bf16_f32 v16, v20, v21
	v_cvt_pk_bf16_f32 v17, v22, v23
	v_cvt_pk_bf16_f32 v18, v36, v37
	v_cvt_pk_bf16_f32 v19, v34, v35
	global_store_dwordx4 v[52:53], v[16:19], off offset:256
	v_or_b32_e32 v46, 0x100, v46
	s_nop 0
	v_mul_f32_e32 v16, v21, v21
	v_mul_f32_e32 v17, v23, v23
	v_fmac_f32_e32 v16, v20, v20
	v_fmac_f32_e32 v17, v22, v22
	v_add_f32_e32 v16, v16, v17
	v_mul_f32_e32 v17, v37, v37
	v_mul_f32_e32 v18, v35, v35
	v_fmac_f32_e32 v17, v36, v36
	v_fmac_f32_e32 v18, v34, v34
	v_add_f32_e32 v16, v38, v16
	v_add_f32_e32 v17, v17, v18
	v_add_f32_e32 v38, v17, v16
	v_pk_mul_f32 v[16:17], v[148:149], v[22:23]
	v_pk_mul_f32 v[22:23], v[146:147], v[34:35]
	v_mov_b32_e32 v244, v38
	v_mov_b32_e32 v245, v38
	s_nop 1
	v_permlane16_swap_b32_e32 v244, v245
	v_pk_mul_f32 v[18:19], v[150:151], v[20:21]
	v_pk_mul_f32 v[20:21], v[144:145], v[36:37]
	v_cvt_pk_bf16_f32 v18, v18, v19
	v_cvt_pk_bf16_f32 v19, v16, v17
	s_waitcnt lgkmcnt(0)
	v_add_f32_e32 v16, v244, v245
	v_mov_b32_e32 v246, v16
	v_mov_b32_e32 v247, v16
	s_nop 1
	v_permlane32_swap_b32_e32 v246, v247
	v_cvt_pk_bf16_f32 v20, v20, v21
	v_cvt_pk_bf16_f32 v21, v22, v23
	v_lshl_add_u64 v[22:23], s[6:7], 0, v[46:47]
	global_store_dwordx4 v[22:23], v[18:21], off
	s_and_saveexec_b64 s[42:43], s[2:3]
	s_cbranch_execz .LBB0_1313
	v_lshlrev_b64 v[18:19], 6, v[48:49]
	v_lshl_add_u64 v[18:19], s[10:11], 0, v[18:19]
	v_lshl_add_u64 v[18:19], s[40:41], 2, v[18:19]
	s_lshl_b32 s44, s69, 2
	s_mov_b32 s45, s13
	v_lshl_add_u64 v[18:19], v[18:19], 0, s[44:45]
	s_waitcnt lgkmcnt(0)
	v_add_f32_e32 v16, v246, v247
	global_store_dword v[18:19], v16, off
.LBB0_1313:
	s_or_b64 exec, exec, s[42:43]
	s_waitcnt vmcnt(5)
	v_lshlrev_b32_e32 v16, 16, v24
	s_waitcnt lgkmcnt(0)
	v_and_b32_e32 v17, 0xffff0000, v24
	v_lshlrev_b32_e32 v18, 16, v25
	v_and_b32_e32 v19, 0xffff0000, v25
	v_lshlrev_b32_e32 v20, 16, v26
	v_and_b32_e32 v21, 0xffff0000, v26
	v_lshlrev_b32_e32 v22, 16, v27
	v_and_b32_e32 v23, 0xffff0000, v27
	v_lshlrev_b64 v[34:35], 10, v[32:33]
	v_lshl_add_u64 v[34:35], v[34:35], 0, v[156:157]
	v_pk_fma_f32 v[12:13], v[12:13], v[80:81], v[20:21]
	v_pk_fma_f32 v[14:15], v[14:15], v[82:83], v[22:23]
	v_pk_fma_f32 v[8:9], v[8:9], v[64:65], v[16:17]
	v_pk_fma_f32 v[10:11], v[10:11], v[66:67], v[18:19]
	v_pk_add_f32 v[14:15], v[198:199], v[14:15]
	v_pk_add_f32 v[12:13], v[190:191], v[12:13]
	v_pk_add_f32 v[16:17], v[188:189], v[10:11]
	v_pk_add_f32 v[18:19], v[186:187], v[8:9]
	v_lshlrev_b64 v[20:21], 1, v[34:35]
	v_cvt_pk_bf16_f32 v8, v18, v19
	v_cvt_pk_bf16_f32 v9, v16, v17
	v_cvt_pk_bf16_f32 v10, v12, v13
	v_cvt_pk_bf16_f32 v11, v14, v15
	v_lshl_add_u64 v[22:23], s[0:1], 0, v[20:21]
	s_waitcnt vmcnt(2)
	v_lshlrev_b32_e32 v24, 16, v28
	v_and_b32_e32 v25, 0xffff0000, v28
	global_store_dwordx4 v[22:23], v[8:11], off
	v_pk_mul_f32 v[34:35], v[162:163], v[14:15]
	v_pk_mul_f32 v[36:37], v[160:161], v[12:13]
	v_pk_mul_f32 v[10:11], v[154:155], v[16:17]
	v_pk_mul_f32 v[8:9], v[152:153], v[18:19]
	v_pk_fma_f32 v[0:1], v[0:1], v[76:77], v[24:25]
	v_cvt_pk_bf16_f32 v8, v8, v9
	v_cvt_pk_bf16_f32 v9, v10, v11
	v_cvt_pk_bf16_f32 v10, v36, v37
	v_cvt_pk_bf16_f32 v11, v34, v35
	v_lshl_add_u64 v[34:35], s[6:7], 0, v[20:21]
	v_lshlrev_b32_e32 v26, 16, v29
	v_and_b32_e32 v27, 0xffff0000, v29
	global_store_dwordx4 v[34:35], v[8:11], off
	v_pk_fma_f32 v[2:3], v[2:3], v[78:79], v[26:27]
	v_lshlrev_b32_e32 v28, 16, v30
	v_pk_add_f32 v[8:9], v[194:195], v[0:1]
	v_mul_f32_e32 v0, v19, v19
	v_mul_f32_e32 v1, v17, v17
	v_fmac_f32_e32 v0, v18, v18
	v_fmac_f32_e32 v1, v16, v16
	v_and_b32_e32 v29, 0xffff0000, v30
	v_lshlrev_b32_e32 v30, 16, v31
	v_and_b32_e32 v31, 0xffff0000, v31
	v_pk_add_f32 v[10:11], v[192:193], v[2:3]
	v_add_f32_e32 v0, v0, v1
	v_mul_f32_e32 v1, v13, v13
	v_mul_f32_e32 v2, v15, v15
	v_pk_fma_f32 v[6:7], v[6:7], v[86:87], v[30:31]
	v_pk_fma_f32 v[4:5], v[4:5], v[84:85], v[28:29]
	v_fmac_f32_e32 v1, v12, v12
	v_fmac_f32_e32 v2, v14, v14
	v_pk_add_f32 v[4:5], v[196:197], v[4:5]
	v_pk_add_f32 v[6:7], v[200:201], v[6:7]
	v_add_f32_e32 v1, v1, v2
	v_add_f32_e32 v12, v1, v0
	v_cvt_pk_bf16_f32 v0, v8, v9
	v_cvt_pk_bf16_f32 v1, v10, v11
	v_cvt_pk_bf16_f32 v2, v4, v5
	v_cvt_pk_bf16_f32 v3, v6, v7
	global_store_dwordx4 v[22:23], v[0:3], off offset:256
	v_or_b32_e32 v20, 0x100, v20
	s_nop 0
	v_mul_f32_e32 v0, v9, v9
	v_mul_f32_e32 v1, v11, v11
	v_fmac_f32_e32 v0, v8, v8
	v_fmac_f32_e32 v1, v10, v10
	v_add_f32_e32 v0, v0, v1
	v_mul_f32_e32 v1, v5, v5
	v_mul_f32_e32 v2, v7, v7
	v_fmac_f32_e32 v1, v4, v4
	v_fmac_f32_e32 v2, v6, v6
	v_add_f32_e32 v0, v12, v0
	v_add_f32_e32 v1, v1, v2
	v_add_f32_e32 v12, v1, v0
	v_pk_mul_f32 v[2:3], v[150:151], v[8:9]
	v_mov_b32_e32 v244, v12
	v_mov_b32_e32 v245, v12
	s_nop 1
	v_permlane16_swap_b32_e32 v244, v245
	v_pk_mul_f32 v[0:1], v[148:149], v[10:11]
	v_cvt_pk_bf16_f32 v2, v2, v3
	v_cvt_pk_bf16_f32 v3, v0, v1
	v_pk_mul_f32 v[6:7], v[146:147], v[6:7]
	s_waitcnt lgkmcnt(0)
	v_add_f32_e32 v0, v244, v245
	v_mov_b32_e32 v246, v0
	v_mov_b32_e32 v247, v0
	s_nop 1
	v_permlane32_swap_b32_e32 v246, v247
	v_pk_mul_f32 v[4:5], v[144:145], v[4:5]
	s_nop 0
	v_cvt_pk_bf16_f32 v4, v4, v5
	v_cvt_pk_bf16_f32 v5, v6, v7
	v_lshl_add_u64 v[6:7], s[6:7], 0, v[20:21]
	global_store_dwordx4 v[6:7], v[2:5], off
	s_and_saveexec_b64 s[0:1], s[2:3]
	s_cbranch_execz .LBB0_1262
	v_lshlrev_b64 v[2:3], 6, v[32:33]
	v_lshl_add_u64 v[2:3], s[10:11], 0, v[2:3]
	v_lshl_add_u64 v[2:3], s[40:41], 2, v[2:3]
	s_lshl_b32 s40, s69, 2
	s_mov_b32 s41, s13
	v_lshl_add_u64 v[2:3], v[2:3], 0, s[40:41]
	s_waitcnt lgkmcnt(0)
	v_add_f32_e32 v0, v246, v247
	global_store_dword v[2:3], v0, off
	s_branch .LBB0_1262
